# S6: S4 + K-loop load segments issue SALU/m0/LDS-DMAs first and the ds_read_b128 block after (42 segments)
# baseline (speedup 1.0000x reference)
.Ldefbar_skip_0:
	v_add_u32_e32 v250, 0x10000, v141
	s_add_i32 s69, s8, 2
	s_add_u32 s0, s52, 0xfff80080
	s_addc_u32 s1, s53, -1
	s_add_i32 s70, 0, 0x10000
	s_cmp_eq_u32 s66, s8
	s_cselect_b32 s59, s41, s1
	s_cselect_b32 s58, s45, s0
	s_cselect_b32 s9, s43, s68
	s_cselect_b32 s8, s65, s67
	s_add_i32 s0, 0, 0x14000
	s_add_i32 m0, s27, 0xc000
	s_nop 0
	global_load_lds_dwordx4 v138, s[52:53]
	s_add_i32 m0, s27, 0xe000
	s_nop 0
	global_load_lds_dwordx4 v136, s[52:53]
	ds_read_b128 v[144:147], v250
	ds_read_b128 v[148:151], v250 offset:1024
	ds_read_b128 v[152:155], v250 offset:2048
	ds_read_b128 v[156:159], v250 offset:3072
	ds_read_b128 v[160:163], v250 offset:16384
	ds_read_b128 v[164:167], v250 offset:17408
	ds_read_b128 v[168:171], v250 offset:18432
	ds_read_b128 v[172:175], v250 offset:19456
	ds_read_b128 v[176:179], v143
	ds_read_b128 v[180:183], v143 offset:1024
	ds_read_b128 v[184:187], v143 offset:2048
	ds_read_b128 v[188:191], v143 offset:3072
	ds_read_b128 v[192:195], v143 offset:4096
	ds_read_b128 v[202:205], v143 offset:5120
	ds_read_b128 v[206:209], v143 offset:6144
	ds_read_b128 v[210:213], v143 offset:7168
	s_waitcnt vmcnt(8)
	s_waitcnt lgkmcnt(0)
	s_setprio 1
	s_barrier
	v_mfma_f32_16x16x32_bf16 v[126:129], v[144:147], v[176:179], 0
	v_mfma_f32_16x16x32_bf16 v[118:121], v[152:155], v[176:179], 0
	v_mfma_f32_16x16x32_bf16 v[110:113], v[144:147], v[184:187], 0
	v_mfma_f32_16x16x32_bf16 v[102:105], v[152:155], v[184:187], 0
	v_mfma_f32_16x16x32_bf16 v[94:97], v[144:147], v[192:195], 0
	v_mfma_f32_16x16x32_bf16 v[86:89], v[152:155], v[192:195], 0
	v_mfma_f32_16x16x32_bf16 v[78:81], v[144:147], v[206:209], 0
	v_mfma_f32_16x16x32_bf16 v[70:73], v[152:155], v[206:209], 0
	v_mfma_f32_16x16x32_bf16 v[126:129], v[148:151], v[180:183], v[126:129]
	v_mfma_f32_16x16x32_bf16 v[118:121], v[156:159], v[180:183], v[118:121]
	v_mfma_f32_16x16x32_bf16 v[110:113], v[148:151], v[188:191], v[110:113]
	v_mfma_f32_16x16x32_bf16 v[102:105], v[156:159], v[188:191], v[102:105]
	v_mfma_f32_16x16x32_bf16 v[94:97], v[148:151], v[202:205], v[94:97]
	v_mfma_f32_16x16x32_bf16 v[86:89], v[156:159], v[202:205], v[86:89]
	v_mfma_f32_16x16x32_bf16 v[78:81], v[148:151], v[210:213], v[78:81]
	v_mfma_f32_16x16x32_bf16 v[70:73], v[156:159], v[210:213], v[70:73]
	v_mfma_f32_16x16x32_bf16 v[122:125], v[160:163], v[176:179], 0
	v_mfma_f32_16x16x32_bf16 v[114:117], v[168:171], v[176:179], 0
	v_mfma_f32_16x16x32_bf16 v[106:109], v[160:163], v[184:187], 0
	v_mfma_f32_16x16x32_bf16 v[98:101], v[168:171], v[184:187], 0
	v_mfma_f32_16x16x32_bf16 v[90:93], v[160:163], v[192:195], 0
	v_mfma_f32_16x16x32_bf16 v[82:85], v[168:171], v[192:195], 0
	v_mfma_f32_16x16x32_bf16 v[74:77], v[160:163], v[206:209], 0
	v_mfma_f32_16x16x32_bf16 v[66:69], v[168:171], v[206:209], 0
	v_mfma_f32_16x16x32_bf16 v[122:125], v[164:167], v[180:183], v[122:125]
	v_mfma_f32_16x16x32_bf16 v[114:117], v[172:175], v[180:183], v[114:117]
	v_mfma_f32_16x16x32_bf16 v[106:109], v[164:167], v[188:191], v[106:109]
	v_mfma_f32_16x16x32_bf16 v[98:101], v[172:175], v[188:191], v[98:101]
	v_mfma_f32_16x16x32_bf16 v[90:93], v[164:167], v[202:205], v[90:93]
	v_mfma_f32_16x16x32_bf16 v[82:85], v[172:175], v[202:205], v[82:85]
	v_mfma_f32_16x16x32_bf16 v[74:77], v[164:167], v[210:213], v[74:77]
	v_mfma_f32_16x16x32_bf16 v[66:69], v[172:175], v[210:213], v[66:69]
	s_barrier
	s_setprio 0
	s_add_i32 s1, s70, s26
	s_add_u32 s98, s8, s16
	s_addc_u32 s99, s9, s17
	s_mov_b32 m0, s1
	s_nop 0
	global_load_lds_dwordx4 v196, s[8:9]
	s_add_i32 m0, s1, 0x2000
	s_add_u32 s70, s8, 0x80000
	s_addc_u32 s71, s9, 0
	s_add_i32 s0, s0, s26
	global_load_lds_dwordx4 v130, s[8:9]
	s_mov_b32 m0, s0
	s_nop 0
	global_load_lds_dwordx4 v196, s[70:71]
	s_add_i32 m0, s0, 0x2000
	s_nop 0
	global_load_lds_dwordx4 v130, s[70:71]
	s_add_u32 s78, s58, s16
	s_addc_u32 s79, s59, s17
	s_mov_b32 m0, s27
	s_nop 0
	global_load_lds_dwordx4 v134, s[58:59]
	s_mov_b32 m0, s28
	s_nop 0
	global_load_lds_dwordx4 v132, s[58:59]
	ds_read_b128 v[176:179], v143 offset:16384
	ds_read_b128 v[180:183], v143 offset:17408
	ds_read_b128 v[184:187], v143 offset:18432
	ds_read_b128 v[188:191], v143 offset:19456
	ds_read_b128 v[192:195], v143 offset:20480
	ds_read_b128 v[202:205], v143 offset:21504
	ds_read_b128 v[206:209], v143 offset:22528
	ds_read_b128 v[210:213], v143 offset:23552
	s_waitcnt vmcnt(8)
	s_waitcnt lgkmcnt(0)
	s_setprio 1
	s_barrier
	v_mfma_f32_16x16x32_bf16 v[62:65], v[144:147], v[176:179], 0
	v_mfma_f32_16x16x32_bf16 v[54:57], v[152:155], v[176:179], 0
	v_mfma_f32_16x16x32_bf16 v[46:49], v[144:147], v[184:187], 0
	v_mfma_f32_16x16x32_bf16 v[38:41], v[152:155], v[184:187], 0
	v_mfma_f32_16x16x32_bf16 v[30:33], v[144:147], v[192:195], 0
	v_mfma_f32_16x16x32_bf16 v[22:25], v[152:155], v[192:195], 0
	v_mfma_f32_16x16x32_bf16 v[14:17], v[144:147], v[206:209], 0
	v_mfma_f32_16x16x32_bf16 v[6:9], v[152:155], v[206:209], 0
	v_mfma_f32_16x16x32_bf16 v[62:65], v[148:151], v[180:183], v[62:65]
	v_mfma_f32_16x16x32_bf16 v[54:57], v[156:159], v[180:183], v[54:57]
	v_mfma_f32_16x16x32_bf16 v[46:49], v[148:151], v[188:191], v[46:49]
	v_mfma_f32_16x16x32_bf16 v[38:41], v[156:159], v[188:191], v[38:41]
	v_mfma_f32_16x16x32_bf16 v[30:33], v[148:151], v[202:205], v[30:33]
	v_mfma_f32_16x16x32_bf16 v[22:25], v[156:159], v[202:205], v[22:25]
	v_mfma_f32_16x16x32_bf16 v[14:17], v[148:151], v[210:213], v[14:17]
	v_mfma_f32_16x16x32_bf16 v[6:9], v[156:159], v[210:213], v[6:9]
	v_mfma_f32_16x16x32_bf16 v[58:61], v[160:163], v[176:179], 0
	v_mfma_f32_16x16x32_bf16 v[50:53], v[168:171], v[176:179], 0
	v_mfma_f32_16x16x32_bf16 v[42:45], v[160:163], v[184:187], 0
	v_mfma_f32_16x16x32_bf16 v[34:37], v[168:171], v[184:187], 0
	v_mfma_f32_16x16x32_bf16 v[26:29], v[160:163], v[192:195], 0
	v_mfma_f32_16x16x32_bf16 v[18:21], v[168:171], v[192:195], 0
	v_mfma_f32_16x16x32_bf16 v[10:13], v[160:163], v[206:209], 0
	v_mfma_f32_16x16x32_bf16 v[2:5], v[168:171], v[206:209], 0
	v_mfma_f32_16x16x32_bf16 v[58:61], v[164:167], v[180:183], v[58:61]
	v_mfma_f32_16x16x32_bf16 v[50:53], v[172:175], v[180:183], v[50:53]
	v_mfma_f32_16x16x32_bf16 v[42:45], v[164:167], v[188:191], v[42:45]
	v_mfma_f32_16x16x32_bf16 v[34:37], v[172:175], v[188:191], v[34:37]
	v_mfma_f32_16x16x32_bf16 v[26:29], v[164:167], v[202:205], v[26:29]
	v_mfma_f32_16x16x32_bf16 v[18:21], v[172:175], v[202:205], v[18:21]
	v_mfma_f32_16x16x32_bf16 v[10:13], v[164:167], v[210:213], v[10:13]
	v_mfma_f32_16x16x32_bf16 v[2:5], v[172:175], v[210:213], v[2:5]
	s_barrier
	s_setprio 0
	s_branch .Lkmid_0
.LBB0_904:
	s_add_i32 s69, s8, 2
	s_add_u32 s0, s52, 0xfff80080
	s_addc_u32 s1, s53, -1
	s_add_i32 s70, 0, 0x10000
	s_cmp_eq_u32 s66, s8
	s_cselect_b32 s59, s41, s1
	s_cselect_b32 s58, s45, s0
	s_cselect_b32 s9, s43, s68
	s_cselect_b32 s8, s65, s67
	s_add_i32 s0, 0, 0x14000
	s_add_i32 m0, s27, 0xc000
	s_nop 0
	global_load_lds_dwordx4 v138, s[52:53]
	s_add_i32 m0, s27, 0xe000
	s_nop 0
	global_load_lds_dwordx4 v136, s[52:53]
	ds_read_b128 v[144:147], v250
	ds_read_b128 v[148:151], v250 offset:1024
	ds_read_b128 v[152:155], v250 offset:2048
	ds_read_b128 v[156:159], v250 offset:3072
	ds_read_b128 v[160:163], v250 offset:16384
	ds_read_b128 v[164:167], v250 offset:17408
	ds_read_b128 v[168:171], v250 offset:18432
	ds_read_b128 v[172:175], v250 offset:19456
	ds_read_b128 v[176:179], v143
	ds_read_b128 v[180:183], v143 offset:1024
	ds_read_b128 v[184:187], v143 offset:2048
	ds_read_b128 v[188:191], v143 offset:3072
	ds_read_b128 v[192:195], v143 offset:4096
	ds_read_b128 v[202:205], v143 offset:5120
	ds_read_b128 v[206:209], v143 offset:6144
	ds_read_b128 v[210:213], v143 offset:7168
	s_waitcnt vmcnt(8)
	s_waitcnt lgkmcnt(0)
	s_setprio 1
	s_barrier
	v_mfma_f32_16x16x32_bf16 v[126:129], v[144:147], v[176:179], v[126:129]
	v_mfma_f32_16x16x32_bf16 v[118:121], v[152:155], v[176:179], v[118:121]
	v_mfma_f32_16x16x32_bf16 v[110:113], v[144:147], v[184:187], v[110:113]
	v_mfma_f32_16x16x32_bf16 v[102:105], v[152:155], v[184:187], v[102:105]
	v_mfma_f32_16x16x32_bf16 v[94:97], v[144:147], v[192:195], v[94:97]
	v_mfma_f32_16x16x32_bf16 v[86:89], v[152:155], v[192:195], v[86:89]
	v_mfma_f32_16x16x32_bf16 v[78:81], v[144:147], v[206:209], v[78:81]
	v_mfma_f32_16x16x32_bf16 v[70:73], v[152:155], v[206:209], v[70:73]
	v_mfma_f32_16x16x32_bf16 v[126:129], v[148:151], v[180:183], v[126:129]
	v_mfma_f32_16x16x32_bf16 v[118:121], v[156:159], v[180:183], v[118:121]
	v_mfma_f32_16x16x32_bf16 v[110:113], v[148:151], v[188:191], v[110:113]
	v_mfma_f32_16x16x32_bf16 v[102:105], v[156:159], v[188:191], v[102:105]
	v_mfma_f32_16x16x32_bf16 v[94:97], v[148:151], v[202:205], v[94:97]
	v_mfma_f32_16x16x32_bf16 v[86:89], v[156:159], v[202:205], v[86:89]
	v_mfma_f32_16x16x32_bf16 v[78:81], v[148:151], v[210:213], v[78:81]
	v_mfma_f32_16x16x32_bf16 v[70:73], v[156:159], v[210:213], v[70:73]
	v_mfma_f32_16x16x32_bf16 v[122:125], v[160:163], v[176:179], v[122:125]
	v_mfma_f32_16x16x32_bf16 v[114:117], v[168:171], v[176:179], v[114:117]
	v_mfma_f32_16x16x32_bf16 v[106:109], v[160:163], v[184:187], v[106:109]
	v_mfma_f32_16x16x32_bf16 v[98:101], v[168:171], v[184:187], v[98:101]
	v_mfma_f32_16x16x32_bf16 v[90:93], v[160:163], v[192:195], v[90:93]
	v_mfma_f32_16x16x32_bf16 v[82:85], v[168:171], v[192:195], v[82:85]
	v_mfma_f32_16x16x32_bf16 v[74:77], v[160:163], v[206:209], v[74:77]
	v_mfma_f32_16x16x32_bf16 v[66:69], v[168:171], v[206:209], v[66:69]
	v_mfma_f32_16x16x32_bf16 v[122:125], v[164:167], v[180:183], v[122:125]
	v_mfma_f32_16x16x32_bf16 v[114:117], v[172:175], v[180:183], v[114:117]
	v_mfma_f32_16x16x32_bf16 v[106:109], v[164:167], v[188:191], v[106:109]
	v_mfma_f32_16x16x32_bf16 v[98:101], v[172:175], v[188:191], v[98:101]
	v_mfma_f32_16x16x32_bf16 v[90:93], v[164:167], v[202:205], v[90:93]
	v_mfma_f32_16x16x32_bf16 v[82:85], v[172:175], v[202:205], v[82:85]
	v_mfma_f32_16x16x32_bf16 v[74:77], v[164:167], v[210:213], v[74:77]
	v_mfma_f32_16x16x32_bf16 v[66:69], v[172:175], v[210:213], v[66:69]
	s_barrier
	s_setprio 0
	s_add_i32 s1, s70, s26
	s_add_u32 s98, s8, s16
	s_addc_u32 s99, s9, s17
	s_mov_b32 m0, s1
	s_nop 0
	global_load_lds_dwordx4 v196, s[8:9]
	s_add_i32 m0, s1, 0x2000
	s_add_u32 s70, s8, 0x80000
	s_addc_u32 s71, s9, 0
	s_add_i32 s0, s0, s26
	global_load_lds_dwordx4 v130, s[8:9]
	s_mov_b32 m0, s0
	s_nop 0
	global_load_lds_dwordx4 v196, s[70:71]
	s_add_i32 m0, s0, 0x2000
	s_nop 0
	global_load_lds_dwordx4 v130, s[70:71]
	s_add_u32 s78, s58, s16
	s_addc_u32 s79, s59, s17
	s_mov_b32 m0, s27
	s_nop 0
	global_load_lds_dwordx4 v134, s[58:59]
	s_mov_b32 m0, s28
	s_nop 0
	global_load_lds_dwordx4 v132, s[58:59]
	ds_read_b128 v[176:179], v143 offset:16384
	ds_read_b128 v[180:183], v143 offset:17408
	ds_read_b128 v[184:187], v143 offset:18432
	ds_read_b128 v[188:191], v143 offset:19456
	ds_read_b128 v[192:195], v143 offset:20480
	ds_read_b128 v[202:205], v143 offset:21504
	ds_read_b128 v[206:209], v143 offset:22528
	ds_read_b128 v[210:213], v143 offset:23552
	s_waitcnt vmcnt(8)
	s_waitcnt lgkmcnt(0)
	s_setprio 1
	s_barrier
	v_mfma_f32_16x16x32_bf16 v[62:65], v[144:147], v[176:179], v[62:65]
	v_mfma_f32_16x16x32_bf16 v[54:57], v[152:155], v[176:179], v[54:57]
	v_mfma_f32_16x16x32_bf16 v[46:49], v[144:147], v[184:187], v[46:49]
	v_mfma_f32_16x16x32_bf16 v[38:41], v[152:155], v[184:187], v[38:41]
	v_mfma_f32_16x16x32_bf16 v[30:33], v[144:147], v[192:195], v[30:33]
	v_mfma_f32_16x16x32_bf16 v[22:25], v[152:155], v[192:195], v[22:25]
	v_mfma_f32_16x16x32_bf16 v[14:17], v[144:147], v[206:209], v[14:17]
	v_mfma_f32_16x16x32_bf16 v[6:9], v[152:155], v[206:209], v[6:9]
	v_mfma_f32_16x16x32_bf16 v[62:65], v[148:151], v[180:183], v[62:65]
	v_mfma_f32_16x16x32_bf16 v[54:57], v[156:159], v[180:183], v[54:57]
	v_mfma_f32_16x16x32_bf16 v[46:49], v[148:151], v[188:191], v[46:49]
	v_mfma_f32_16x16x32_bf16 v[38:41], v[156:159], v[188:191], v[38:41]
	v_mfma_f32_16x16x32_bf16 v[30:33], v[148:151], v[202:205], v[30:33]
	v_mfma_f32_16x16x32_bf16 v[22:25], v[156:159], v[202:205], v[22:25]
	v_mfma_f32_16x16x32_bf16 v[14:17], v[148:151], v[210:213], v[14:17]
	v_mfma_f32_16x16x32_bf16 v[6:9], v[156:159], v[210:213], v[6:9]
	v_mfma_f32_16x16x32_bf16 v[58:61], v[160:163], v[176:179], v[58:61]
	v_mfma_f32_16x16x32_bf16 v[50:53], v[168:171], v[176:179], v[50:53]
	v_mfma_f32_16x16x32_bf16 v[42:45], v[160:163], v[184:187], v[42:45]
	v_mfma_f32_16x16x32_bf16 v[34:37], v[168:171], v[184:187], v[34:37]
	v_mfma_f32_16x16x32_bf16 v[26:29], v[160:163], v[192:195], v[26:29]
	v_mfma_f32_16x16x32_bf16 v[18:21], v[168:171], v[192:195], v[18:21]
	v_mfma_f32_16x16x32_bf16 v[10:13], v[160:163], v[206:209], v[10:13]
	v_mfma_f32_16x16x32_bf16 v[2:5], v[168:171], v[206:209], v[2:5]
	v_mfma_f32_16x16x32_bf16 v[58:61], v[164:167], v[180:183], v[58:61]
	v_mfma_f32_16x16x32_bf16 v[50:53], v[172:175], v[180:183], v[50:53]
	v_mfma_f32_16x16x32_bf16 v[42:45], v[164:167], v[188:191], v[42:45]
	v_mfma_f32_16x16x32_bf16 v[34:37], v[172:175], v[188:191], v[34:37]
	v_mfma_f32_16x16x32_bf16 v[26:29], v[164:167], v[202:205], v[26:29]
	v_mfma_f32_16x16x32_bf16 v[18:21], v[172:175], v[202:205], v[18:21]
	v_mfma_f32_16x16x32_bf16 v[10:13], v[164:167], v[210:213], v[10:13]
	v_mfma_f32_16x16x32_bf16 v[2:5], v[172:175], v[210:213], v[2:5]
	s_barrier
	s_setprio 0
.Lkmid_0:
	s_add_i32 s0, 0, 0x18000
	s_add_i32 s1, 0, 0x1c000
	s_add_u32 s58, s58, 0x80000
	s_addc_u32 s59, s59, 0
	s_mov_b32 m0, s29
	s_nop 0
	global_load_lds_dwordx4 v134, s[58:59]
	s_mov_b32 m0, s30
	s_nop 0
	global_load_lds_dwordx4 v132, s[58:59]
	ds_read_b128 v[144:147], v250 offset:32768
	ds_read_b128 v[148:151], v250 offset:33792
	ds_read_b128 v[152:155], v250 offset:34816
	ds_read_b128 v[156:159], v250 offset:35840
	ds_read_b128 v[160:163], v250 offset:49152
	ds_read_b128 v[164:167], v250 offset:50176
	ds_read_b128 v[168:171], v250 offset:51200
	ds_read_b128 v[172:175], v250 offset:52224
	ds_read_b128 v[176:179], v143 offset:32768
	ds_read_b128 v[180:183], v143 offset:33792
	ds_read_b128 v[184:187], v143 offset:34816
	ds_read_b128 v[188:191], v143 offset:35840
	ds_read_b128 v[192:195], v143 offset:36864
	ds_read_b128 v[202:205], v143 offset:37888
	ds_read_b128 v[206:209], v143 offset:38912
	ds_read_b128 v[210:213], v143 offset:39936
	s_waitcnt vmcnt(8)
	s_waitcnt lgkmcnt(0)
	s_setprio 1
	s_barrier
	v_mfma_f32_16x16x32_bf16 v[126:129], v[144:147], v[176:179], v[126:129]
	v_mfma_f32_16x16x32_bf16 v[118:121], v[152:155], v[176:179], v[118:121]
	v_mfma_f32_16x16x32_bf16 v[110:113], v[144:147], v[184:187], v[110:113]
	v_mfma_f32_16x16x32_bf16 v[102:105], v[152:155], v[184:187], v[102:105]
	v_mfma_f32_16x16x32_bf16 v[94:97], v[144:147], v[192:195], v[94:97]
	v_mfma_f32_16x16x32_bf16 v[86:89], v[152:155], v[192:195], v[86:89]
	v_mfma_f32_16x16x32_bf16 v[78:81], v[144:147], v[206:209], v[78:81]
	v_mfma_f32_16x16x32_bf16 v[70:73], v[152:155], v[206:209], v[70:73]
	v_mfma_f32_16x16x32_bf16 v[126:129], v[148:151], v[180:183], v[126:129]
	v_mfma_f32_16x16x32_bf16 v[118:121], v[156:159], v[180:183], v[118:121]
	v_mfma_f32_16x16x32_bf16 v[110:113], v[148:151], v[188:191], v[110:113]
	v_mfma_f32_16x16x32_bf16 v[102:105], v[156:159], v[188:191], v[102:105]
	v_mfma_f32_16x16x32_bf16 v[94:97], v[148:151], v[202:205], v[94:97]
	v_mfma_f32_16x16x32_bf16 v[86:89], v[156:159], v[202:205], v[86:89]
	v_mfma_f32_16x16x32_bf16 v[78:81], v[148:151], v[210:213], v[78:81]
	v_mfma_f32_16x16x32_bf16 v[70:73], v[156:159], v[210:213], v[70:73]
	v_mfma_f32_16x16x32_bf16 v[122:125], v[160:163], v[176:179], v[122:125]
	v_mfma_f32_16x16x32_bf16 v[114:117], v[168:171], v[176:179], v[114:117]
	v_mfma_f32_16x16x32_bf16 v[106:109], v[160:163], v[184:187], v[106:109]
	v_mfma_f32_16x16x32_bf16 v[98:101], v[168:171], v[184:187], v[98:101]
	v_mfma_f32_16x16x32_bf16 v[90:93], v[160:163], v[192:195], v[90:93]
	v_mfma_f32_16x16x32_bf16 v[82:85], v[168:171], v[192:195], v[82:85]
	v_mfma_f32_16x16x32_bf16 v[74:77], v[160:163], v[206:209], v[74:77]
	v_mfma_f32_16x16x32_bf16 v[66:69], v[168:171], v[206:209], v[66:69]
	v_mfma_f32_16x16x32_bf16 v[122:125], v[164:167], v[180:183], v[122:125]
	v_mfma_f32_16x16x32_bf16 v[114:117], v[172:175], v[180:183], v[114:117]
	v_mfma_f32_16x16x32_bf16 v[106:109], v[164:167], v[188:191], v[106:109]
	v_mfma_f32_16x16x32_bf16 v[98:101], v[172:175], v[188:191], v[98:101]
	v_mfma_f32_16x16x32_bf16 v[90:93], v[164:167], v[202:205], v[90:93]
	v_mfma_f32_16x16x32_bf16 v[82:85], v[172:175], v[202:205], v[82:85]
	v_mfma_f32_16x16x32_bf16 v[74:77], v[164:167], v[210:213], v[74:77]
	v_mfma_f32_16x16x32_bf16 v[66:69], v[172:175], v[210:213], v[66:69]
	s_barrier
	s_setprio 0
	s_add_i32 s0, s0, s26
	s_mov_b32 m0, s0
	s_nop 0
	global_load_lds_dwordx4 v196, s[98:99]
	s_add_i32 m0, s0, 0x2000
	s_add_u32 s8, s8, 0x80080
	s_addc_u32 s9, s9, 0
	s_add_i32 s0, s1, s26
	global_load_lds_dwordx4 v130, s[98:99]
	s_mov_b32 m0, s0
	s_nop 0
	global_load_lds_dwordx4 v196, s[8:9]
	s_add_i32 m0, s0, 0x2000
	s_nop 0
	global_load_lds_dwordx4 v130, s[8:9]
	s_mov_b32 m0, s31
	s_nop 0
	global_load_lds_dwordx4 v134, s[78:79]
	s_mov_b32 m0, s34
	s_nop 0
	global_load_lds_dwordx4 v132, s[78:79]
	ds_read_b128 v[176:179], v143 offset:49152
	ds_read_b128 v[180:183], v143 offset:50176
	ds_read_b128 v[184:187], v143 offset:51200
	ds_read_b128 v[188:191], v143 offset:52224
	ds_read_b128 v[192:195], v143 offset:53248
	ds_read_b128 v[202:205], v143 offset:54272
	ds_read_b128 v[206:209], v143 offset:55296
	ds_read_b128 v[210:213], v143 offset:56320
	s_waitcnt vmcnt(8)
	s_waitcnt lgkmcnt(0)
	s_setprio 1
	s_barrier
	v_mfma_f32_16x16x32_bf16 v[62:65], v[144:147], v[176:179], v[62:65]
	v_mfma_f32_16x16x32_bf16 v[54:57], v[152:155], v[176:179], v[54:57]
	v_mfma_f32_16x16x32_bf16 v[46:49], v[144:147], v[184:187], v[46:49]
	v_mfma_f32_16x16x32_bf16 v[38:41], v[152:155], v[184:187], v[38:41]
	v_mfma_f32_16x16x32_bf16 v[30:33], v[144:147], v[192:195], v[30:33]
	v_mfma_f32_16x16x32_bf16 v[22:25], v[152:155], v[192:195], v[22:25]
	v_mfma_f32_16x16x32_bf16 v[14:17], v[144:147], v[206:209], v[14:17]
	v_mfma_f32_16x16x32_bf16 v[6:9], v[152:155], v[206:209], v[6:9]
	v_mfma_f32_16x16x32_bf16 v[62:65], v[148:151], v[180:183], v[62:65]
	v_mfma_f32_16x16x32_bf16 v[54:57], v[156:159], v[180:183], v[54:57]
	v_mfma_f32_16x16x32_bf16 v[46:49], v[148:151], v[188:191], v[46:49]
	v_mfma_f32_16x16x32_bf16 v[38:41], v[156:159], v[188:191], v[38:41]
	v_mfma_f32_16x16x32_bf16 v[30:33], v[148:151], v[202:205], v[30:33]
	v_mfma_f32_16x16x32_bf16 v[22:25], v[156:159], v[202:205], v[22:25]
	v_mfma_f32_16x16x32_bf16 v[14:17], v[148:151], v[210:213], v[14:17]
	v_mfma_f32_16x16x32_bf16 v[6:9], v[156:159], v[210:213], v[6:9]
	v_mfma_f32_16x16x32_bf16 v[58:61], v[160:163], v[176:179], v[58:61]
	v_mfma_f32_16x16x32_bf16 v[50:53], v[168:171], v[176:179], v[50:53]
	v_mfma_f32_16x16x32_bf16 v[42:45], v[160:163], v[184:187], v[42:45]
	v_mfma_f32_16x16x32_bf16 v[34:37], v[168:171], v[184:187], v[34:37]
	v_mfma_f32_16x16x32_bf16 v[26:29], v[160:163], v[192:195], v[26:29]
	v_mfma_f32_16x16x32_bf16 v[18:21], v[168:171], v[192:195], v[18:21]
	v_mfma_f32_16x16x32_bf16 v[10:13], v[160:163], v[206:209], v[10:13]
	v_mfma_f32_16x16x32_bf16 v[2:5], v[168:171], v[206:209], v[2:5]
	v_mfma_f32_16x16x32_bf16 v[58:61], v[164:167], v[180:183], v[58:61]
	v_mfma_f32_16x16x32_bf16 v[50:53], v[172:175], v[180:183], v[50:53]
	v_mfma_f32_16x16x32_bf16 v[42:45], v[164:167], v[188:191], v[42:45]
	v_mfma_f32_16x16x32_bf16 v[34:37], v[172:175], v[188:191], v[34:37]
	v_mfma_f32_16x16x32_bf16 v[26:29], v[164:167], v[202:205], v[26:29]
	v_mfma_f32_16x16x32_bf16 v[18:21], v[172:175], v[202:205], v[18:21]
	v_mfma_f32_16x16x32_bf16 v[10:13], v[164:167], v[210:213], v[10:13]
	v_mfma_f32_16x16x32_bf16 v[2:5], v[172:175], v[210:213], v[2:5]
	s_barrier
	s_setprio 0
	s_add_u32 s67, s67, 0x100
	s_addc_u32 s68, s68, 0
	s_add_u32 s52, s52, 0x100
	s_addc_u32 s53, s53, 0
	s_cmp_ge_i32 s69, s62
	s_mov_b32 s8, s69
	s_cbranch_scc0 .LBB0_904
	s_and_b64 vcc, exec, s[38:39]
	s_cbranch_vccz .LBB0_907
	s_barrier

.Ldefbar_skip_1:
	v_add_u32_e32 v250, 0x10000, v188
	s_add_i32 s72, s50, 2
	s_add_u32 s8, s48, 0x100
	s_addc_u32 s9, s49, 0
	s_add_i32 s0, 0, 0x10000
	s_cmp_eq_u32 s41, s50
	s_cselect_b32 s53, s45, s9
	s_cselect_b32 s52, s44, s8
	s_cselect_b32 s51, s47, s71
	s_cselect_b32 s50, s46, s70
	s_add_i32 s1, 0, 0x14000
	v_lshl_add_u64 v[194:195], s[48:49], 0, v[162:163]
	s_add_i32 m0, s27, 0xc000
	s_nop 0
	global_load_lds_dwordx4 v[194:195], off
	v_lshl_add_u64 v[194:195], s[48:49], 0, v[160:161]
	s_add_i32 m0, s27, 0xe000
	s_nop 0
	global_load_lds_dwordx4 v[194:195], off
	ds_read_b128 v[130:133], v250
	ds_read_b128 v[134:137], v250 offset:1024
	ds_read_b128 v[138:141], v250 offset:2048
	ds_read_b128 v[142:145], v250 offset:3072
	ds_read_b128 v[146:149], v250 offset:16384
	ds_read_b128 v[164:167], v250 offset:17408
	ds_read_b128 v[168:171], v250 offset:18432
	ds_read_b128 v[172:175], v250 offset:19456
	ds_read_b128 v[176:179], v189
	ds_read_b128 v[180:183], v189 offset:1024
	ds_read_b128 v[184:187], v189 offset:2048
	ds_read_b128 v[190:193], v189 offset:3072
	ds_read_b128 v[202:205], v189 offset:4096
	ds_read_b128 v[206:209], v189 offset:5120
	ds_read_b128 v[210:213], v189 offset:6144
	ds_read_b128 v[214:217], v189 offset:7168
	s_waitcnt vmcnt(8)
	s_waitcnt lgkmcnt(0)
	s_setprio 1
	s_barrier
	v_mfma_f32_16x16x32_bf16 v[126:129], v[130:133], v[176:179], 0
	v_mfma_f32_16x16x32_bf16 v[122:125], v[138:141], v[176:179], 0
	v_mfma_f32_16x16x32_bf16 v[110:113], v[130:133], v[184:187], 0
	v_mfma_f32_16x16x32_bf16 v[106:109], v[138:141], v[184:187], 0
	v_mfma_f32_16x16x32_bf16 v[98:101], v[130:133], v[202:205], 0
	v_mfma_f32_16x16x32_bf16 v[90:93], v[138:141], v[202:205], 0
	v_mfma_f32_16x16x32_bf16 v[82:85], v[130:133], v[210:213], 0
	v_mfma_f32_16x16x32_bf16 v[74:77], v[138:141], v[210:213], 0
	v_mfma_f32_16x16x32_bf16 v[126:129], v[134:137], v[180:183], v[126:129]
	v_mfma_f32_16x16x32_bf16 v[122:125], v[142:145], v[180:183], v[122:125]
	v_mfma_f32_16x16x32_bf16 v[110:113], v[134:137], v[190:193], v[110:113]
	v_mfma_f32_16x16x32_bf16 v[106:109], v[142:145], v[190:193], v[106:109]
	v_mfma_f32_16x16x32_bf16 v[98:101], v[134:137], v[206:209], v[98:101]
	v_mfma_f32_16x16x32_bf16 v[90:93], v[142:145], v[206:209], v[90:93]
	v_mfma_f32_16x16x32_bf16 v[82:85], v[134:137], v[214:217], v[82:85]
	v_mfma_f32_16x16x32_bf16 v[74:77], v[142:145], v[214:217], v[74:77]
	v_mfma_f32_16x16x32_bf16 v[118:121], v[146:149], v[176:179], 0
	v_mfma_f32_16x16x32_bf16 v[114:117], v[168:171], v[176:179], 0
	v_mfma_f32_16x16x32_bf16 v[102:105], v[146:149], v[184:187], 0
	v_mfma_f32_16x16x32_bf16 v[94:97], v[168:171], v[184:187], 0
	v_mfma_f32_16x16x32_bf16 v[86:89], v[146:149], v[202:205], 0
	v_mfma_f32_16x16x32_bf16 v[78:81], v[168:171], v[202:205], 0
	v_mfma_f32_16x16x32_bf16 v[70:73], v[146:149], v[210:213], 0
	v_mfma_f32_16x16x32_bf16 v[66:69], v[168:171], v[210:213], 0
	v_mfma_f32_16x16x32_bf16 v[118:121], v[164:167], v[180:183], v[118:121]
	v_mfma_f32_16x16x32_bf16 v[114:117], v[172:175], v[180:183], v[114:117]
	v_mfma_f32_16x16x32_bf16 v[102:105], v[164:167], v[190:193], v[102:105]
	v_mfma_f32_16x16x32_bf16 v[94:97], v[172:175], v[190:193], v[94:97]
	v_mfma_f32_16x16x32_bf16 v[86:89], v[164:167], v[206:209], v[86:89]
	v_mfma_f32_16x16x32_bf16 v[78:81], v[172:175], v[206:209], v[78:81]
	v_mfma_f32_16x16x32_bf16 v[70:73], v[164:167], v[214:217], v[70:73]
	v_mfma_f32_16x16x32_bf16 v[66:69], v[172:175], v[214:217], v[66:69]
	s_barrier
	s_setprio 0
	s_add_i32 s0, s0, s26
	s_add_u32 s98, s50, s16
	s_addc_u32 s99, s51, s17
	s_mov_b32 m0, s0
	s_nop 0
	global_load_lds_dwordx4 v196, s[50:51]
	s_add_i32 m0, s0, 0x2000
	s_add_u32 s48, s50, 0x158000
	s_addc_u32 s49, s51, 0
	s_add_i32 s0, s1, s26
	global_load_lds_dwordx4 v154, s[50:51]
	s_mov_b32 m0, s0
	s_nop 0
	global_load_lds_dwordx4 v196, s[48:49]
	s_add_i32 m0, s0, 0x2000
	s_nop 0
	global_load_lds_dwordx4 v154, s[48:49]
	s_add_u32 s78, s52, s16
	s_addc_u32 s79, s53, s17
	s_mov_b32 m0, s27
	s_nop 0
	global_load_lds_dwordx4 v150, s[52:53]
	s_mov_b32 m0, s28
	s_nop 0
	global_load_lds_dwordx4 v152, s[52:53]
	ds_read_b128 v[176:179], v189 offset:16384
	ds_read_b128 v[180:183], v189 offset:17408
	ds_read_b128 v[184:187], v189 offset:18432
	ds_read_b128 v[190:193], v189 offset:19456
	ds_read_b128 v[202:205], v189 offset:20480
	ds_read_b128 v[206:209], v189 offset:21504
	ds_read_b128 v[210:213], v189 offset:22528
	ds_read_b128 v[214:217], v189 offset:23552
	s_waitcnt vmcnt(8)
	s_waitcnt lgkmcnt(0)
	s_setprio 1
	s_barrier
	v_mfma_f32_16x16x32_bf16 v[62:65], v[130:133], v[176:179], 0
	v_mfma_f32_16x16x32_bf16 v[58:61], v[138:141], v[176:179], 0
	v_mfma_f32_16x16x32_bf16 v[50:53], v[130:133], v[184:187], 0
	v_mfma_f32_16x16x32_bf16 v[42:45], v[138:141], v[184:187], 0
	v_mfma_f32_16x16x32_bf16 v[34:37], v[130:133], v[202:205], 0
	v_mfma_f32_16x16x32_bf16 v[26:29], v[138:141], v[202:205], 0
	v_mfma_f32_16x16x32_bf16 v[18:21], v[130:133], v[210:213], 0
	v_mfma_f32_16x16x32_bf16 v[10:13], v[138:141], v[210:213], 0
	v_mfma_f32_16x16x32_bf16 v[62:65], v[134:137], v[180:183], v[62:65]
	v_mfma_f32_16x16x32_bf16 v[58:61], v[142:145], v[180:183], v[58:61]
	v_mfma_f32_16x16x32_bf16 v[50:53], v[134:137], v[190:193], v[50:53]
	v_mfma_f32_16x16x32_bf16 v[42:45], v[142:145], v[190:193], v[42:45]
	v_mfma_f32_16x16x32_bf16 v[34:37], v[134:137], v[206:209], v[34:37]
	v_mfma_f32_16x16x32_bf16 v[26:29], v[142:145], v[206:209], v[26:29]
	v_mfma_f32_16x16x32_bf16 v[18:21], v[134:137], v[214:217], v[18:21]
	v_mfma_f32_16x16x32_bf16 v[10:13], v[142:145], v[214:217], v[10:13]
	v_mfma_f32_16x16x32_bf16 v[54:57], v[146:149], v[176:179], 0
	v_mfma_f32_16x16x32_bf16 v[46:49], v[168:171], v[176:179], 0
	v_mfma_f32_16x16x32_bf16 v[38:41], v[146:149], v[184:187], 0
	v_mfma_f32_16x16x32_bf16 v[30:33], v[168:171], v[184:187], 0
	v_mfma_f32_16x16x32_bf16 v[22:25], v[146:149], v[202:205], 0
	v_mfma_f32_16x16x32_bf16 v[14:17], v[168:171], v[202:205], 0
	v_mfma_f32_16x16x32_bf16 v[6:9], v[146:149], v[210:213], 0
	v_mfma_f32_16x16x32_bf16 v[2:5], v[168:171], v[210:213], 0
	v_mfma_f32_16x16x32_bf16 v[54:57], v[164:167], v[180:183], v[54:57]
	v_mfma_f32_16x16x32_bf16 v[46:49], v[172:175], v[180:183], v[46:49]
	v_mfma_f32_16x16x32_bf16 v[38:41], v[164:167], v[190:193], v[38:41]
	v_mfma_f32_16x16x32_bf16 v[30:33], v[172:175], v[190:193], v[30:33]
	v_mfma_f32_16x16x32_bf16 v[22:25], v[164:167], v[206:209], v[22:25]
	v_mfma_f32_16x16x32_bf16 v[14:17], v[172:175], v[206:209], v[14:17]
	v_mfma_f32_16x16x32_bf16 v[6:9], v[164:167], v[214:217], v[6:9]
	v_mfma_f32_16x16x32_bf16 v[2:5], v[172:175], v[214:217], v[2:5]
	s_barrier
	s_setprio 0
	s_branch .Lkmid_1
.LBB0_987:
	s_add_i32 s72, s50, 2
	s_add_u32 s8, s48, 0x100
	s_addc_u32 s9, s49, 0
	s_add_i32 s0, 0, 0x10000
	s_cmp_eq_u32 s41, s50
	s_cselect_b32 s53, s45, s9
	s_cselect_b32 s52, s44, s8
	s_cselect_b32 s51, s47, s71
	s_cselect_b32 s50, s46, s70
	s_add_i32 s1, 0, 0x14000
	v_lshl_add_u64 v[194:195], s[48:49], 0, v[162:163]
	s_add_i32 m0, s27, 0xc000
	s_nop 0
	global_load_lds_dwordx4 v[194:195], off
	v_lshl_add_u64 v[194:195], s[48:49], 0, v[160:161]
	s_add_i32 m0, s27, 0xe000
	s_nop 0
	global_load_lds_dwordx4 v[194:195], off
	ds_read_b128 v[130:133], v250
	ds_read_b128 v[134:137], v250 offset:1024
	ds_read_b128 v[138:141], v250 offset:2048
	ds_read_b128 v[142:145], v250 offset:3072
	ds_read_b128 v[146:149], v250 offset:16384
	ds_read_b128 v[164:167], v250 offset:17408
	ds_read_b128 v[168:171], v250 offset:18432
	ds_read_b128 v[172:175], v250 offset:19456
	ds_read_b128 v[176:179], v189
	ds_read_b128 v[180:183], v189 offset:1024
	ds_read_b128 v[184:187], v189 offset:2048
	ds_read_b128 v[190:193], v189 offset:3072
	ds_read_b128 v[202:205], v189 offset:4096
	ds_read_b128 v[206:209], v189 offset:5120
	ds_read_b128 v[210:213], v189 offset:6144
	ds_read_b128 v[214:217], v189 offset:7168
	s_waitcnt vmcnt(8)
	s_waitcnt lgkmcnt(0)
	s_setprio 1
	s_barrier
	v_mfma_f32_16x16x32_bf16 v[126:129], v[130:133], v[176:179], v[126:129]
	v_mfma_f32_16x16x32_bf16 v[122:125], v[138:141], v[176:179], v[122:125]
	v_mfma_f32_16x16x32_bf16 v[110:113], v[130:133], v[184:187], v[110:113]
	v_mfma_f32_16x16x32_bf16 v[106:109], v[138:141], v[184:187], v[106:109]
	v_mfma_f32_16x16x32_bf16 v[98:101], v[130:133], v[202:205], v[98:101]
	v_mfma_f32_16x16x32_bf16 v[90:93], v[138:141], v[202:205], v[90:93]
	v_mfma_f32_16x16x32_bf16 v[82:85], v[130:133], v[210:213], v[82:85]
	v_mfma_f32_16x16x32_bf16 v[74:77], v[138:141], v[210:213], v[74:77]
	v_mfma_f32_16x16x32_bf16 v[126:129], v[134:137], v[180:183], v[126:129]
	v_mfma_f32_16x16x32_bf16 v[122:125], v[142:145], v[180:183], v[122:125]
	v_mfma_f32_16x16x32_bf16 v[110:113], v[134:137], v[190:193], v[110:113]
	v_mfma_f32_16x16x32_bf16 v[106:109], v[142:145], v[190:193], v[106:109]
	v_mfma_f32_16x16x32_bf16 v[98:101], v[134:137], v[206:209], v[98:101]
	v_mfma_f32_16x16x32_bf16 v[90:93], v[142:145], v[206:209], v[90:93]
	v_mfma_f32_16x16x32_bf16 v[82:85], v[134:137], v[214:217], v[82:85]
	v_mfma_f32_16x16x32_bf16 v[74:77], v[142:145], v[214:217], v[74:77]
	v_mfma_f32_16x16x32_bf16 v[118:121], v[146:149], v[176:179], v[118:121]
	v_mfma_f32_16x16x32_bf16 v[114:117], v[168:171], v[176:179], v[114:117]
	v_mfma_f32_16x16x32_bf16 v[102:105], v[146:149], v[184:187], v[102:105]
	v_mfma_f32_16x16x32_bf16 v[94:97], v[168:171], v[184:187], v[94:97]
	v_mfma_f32_16x16x32_bf16 v[86:89], v[146:149], v[202:205], v[86:89]
	v_mfma_f32_16x16x32_bf16 v[78:81], v[168:171], v[202:205], v[78:81]
	v_mfma_f32_16x16x32_bf16 v[70:73], v[146:149], v[210:213], v[70:73]
	v_mfma_f32_16x16x32_bf16 v[66:69], v[168:171], v[210:213], v[66:69]
	v_mfma_f32_16x16x32_bf16 v[118:121], v[164:167], v[180:183], v[118:121]
	v_mfma_f32_16x16x32_bf16 v[114:117], v[172:175], v[180:183], v[114:117]
	v_mfma_f32_16x16x32_bf16 v[102:105], v[164:167], v[190:193], v[102:105]
	v_mfma_f32_16x16x32_bf16 v[94:97], v[172:175], v[190:193], v[94:97]
	v_mfma_f32_16x16x32_bf16 v[86:89], v[164:167], v[206:209], v[86:89]
	v_mfma_f32_16x16x32_bf16 v[78:81], v[172:175], v[206:209], v[78:81]
	v_mfma_f32_16x16x32_bf16 v[70:73], v[164:167], v[214:217], v[70:73]
	v_mfma_f32_16x16x32_bf16 v[66:69], v[172:175], v[214:217], v[66:69]
	s_barrier
	s_setprio 0
	s_add_i32 s0, s0, s26
	s_add_u32 s98, s50, s16
	s_addc_u32 s99, s51, s17
	s_mov_b32 m0, s0
	s_nop 0
	global_load_lds_dwordx4 v196, s[50:51]
	s_add_i32 m0, s0, 0x2000
	s_add_u32 s48, s50, 0x158000
	s_addc_u32 s49, s51, 0
	s_add_i32 s0, s1, s26
	global_load_lds_dwordx4 v154, s[50:51]
	s_mov_b32 m0, s0
	s_nop 0
	global_load_lds_dwordx4 v196, s[48:49]
	s_add_i32 m0, s0, 0x2000
	s_nop 0
	global_load_lds_dwordx4 v154, s[48:49]
	s_add_u32 s78, s52, s16
	s_addc_u32 s79, s53, s17
	s_mov_b32 m0, s27
	s_nop 0
	global_load_lds_dwordx4 v150, s[52:53]
	s_mov_b32 m0, s28
	s_nop 0
	global_load_lds_dwordx4 v152, s[52:53]
	ds_read_b128 v[176:179], v189 offset:16384
	ds_read_b128 v[180:183], v189 offset:17408
	ds_read_b128 v[184:187], v189 offset:18432
	ds_read_b128 v[190:193], v189 offset:19456
	ds_read_b128 v[202:205], v189 offset:20480
	ds_read_b128 v[206:209], v189 offset:21504
	ds_read_b128 v[210:213], v189 offset:22528
	ds_read_b128 v[214:217], v189 offset:23552
	s_waitcnt vmcnt(8)
	s_waitcnt lgkmcnt(0)
	s_setprio 1
	s_barrier
	v_mfma_f32_16x16x32_bf16 v[62:65], v[130:133], v[176:179], v[62:65]
	v_mfma_f32_16x16x32_bf16 v[58:61], v[138:141], v[176:179], v[58:61]
	v_mfma_f32_16x16x32_bf16 v[50:53], v[130:133], v[184:187], v[50:53]
	v_mfma_f32_16x16x32_bf16 v[42:45], v[138:141], v[184:187], v[42:45]
	v_mfma_f32_16x16x32_bf16 v[34:37], v[130:133], v[202:205], v[34:37]
	v_mfma_f32_16x16x32_bf16 v[26:29], v[138:141], v[202:205], v[26:29]
	v_mfma_f32_16x16x32_bf16 v[18:21], v[130:133], v[210:213], v[18:21]
	v_mfma_f32_16x16x32_bf16 v[10:13], v[138:141], v[210:213], v[10:13]
	v_mfma_f32_16x16x32_bf16 v[62:65], v[134:137], v[180:183], v[62:65]
	v_mfma_f32_16x16x32_bf16 v[58:61], v[142:145], v[180:183], v[58:61]
	v_mfma_f32_16x16x32_bf16 v[50:53], v[134:137], v[190:193], v[50:53]
	v_mfma_f32_16x16x32_bf16 v[42:45], v[142:145], v[190:193], v[42:45]
	v_mfma_f32_16x16x32_bf16 v[34:37], v[134:137], v[206:209], v[34:37]
	v_mfma_f32_16x16x32_bf16 v[26:29], v[142:145], v[206:209], v[26:29]
	v_mfma_f32_16x16x32_bf16 v[18:21], v[134:137], v[214:217], v[18:21]
	v_mfma_f32_16x16x32_bf16 v[10:13], v[142:145], v[214:217], v[10:13]
	v_mfma_f32_16x16x32_bf16 v[54:57], v[146:149], v[176:179], v[54:57]
	v_mfma_f32_16x16x32_bf16 v[46:49], v[168:171], v[176:179], v[46:49]
	v_mfma_f32_16x16x32_bf16 v[38:41], v[146:149], v[184:187], v[38:41]
	v_mfma_f32_16x16x32_bf16 v[30:33], v[168:171], v[184:187], v[30:33]
	v_mfma_f32_16x16x32_bf16 v[22:25], v[146:149], v[202:205], v[22:25]
	v_mfma_f32_16x16x32_bf16 v[14:17], v[168:171], v[202:205], v[14:17]
	v_mfma_f32_16x16x32_bf16 v[6:9], v[146:149], v[210:213], v[6:9]
	v_mfma_f32_16x16x32_bf16 v[2:5], v[168:171], v[210:213], v[2:5]
	v_mfma_f32_16x16x32_bf16 v[54:57], v[164:167], v[180:183], v[54:57]
	v_mfma_f32_16x16x32_bf16 v[46:49], v[172:175], v[180:183], v[46:49]
	v_mfma_f32_16x16x32_bf16 v[38:41], v[164:167], v[190:193], v[38:41]
	v_mfma_f32_16x16x32_bf16 v[30:33], v[172:175], v[190:193], v[30:33]
	v_mfma_f32_16x16x32_bf16 v[22:25], v[164:167], v[206:209], v[22:25]
	v_mfma_f32_16x16x32_bf16 v[14:17], v[172:175], v[206:209], v[14:17]
	v_mfma_f32_16x16x32_bf16 v[6:9], v[164:167], v[214:217], v[6:9]
	v_mfma_f32_16x16x32_bf16 v[2:5], v[172:175], v[214:217], v[2:5]
	s_barrier
	s_setprio 0
.Lkmid_1:
	s_add_i32 s0, 0, 0x18000
	s_add_i32 s1, 0, 0x1c000
	s_add_u32 s48, s52, 0x158000
	s_addc_u32 s49, s53, 0
	s_mov_b32 m0, s29
	s_nop 0
	global_load_lds_dwordx4 v150, s[48:49]
	s_mov_b32 m0, s30
	s_nop 0
	global_load_lds_dwordx4 v152, s[48:49]
	ds_read_b128 v[130:133], v250 offset:32768
	ds_read_b128 v[134:137], v250 offset:33792
	ds_read_b128 v[138:141], v250 offset:34816
	ds_read_b128 v[142:145], v250 offset:35840
	ds_read_b128 v[146:149], v250 offset:49152
	ds_read_b128 v[164:167], v250 offset:50176
	ds_read_b128 v[168:171], v250 offset:51200
	ds_read_b128 v[172:175], v250 offset:52224
	ds_read_b128 v[176:179], v189 offset:32768
	ds_read_b128 v[180:183], v189 offset:33792
	ds_read_b128 v[184:187], v189 offset:34816
	ds_read_b128 v[190:193], v189 offset:35840
	ds_read_b128 v[202:205], v189 offset:36864
	ds_read_b128 v[206:209], v189 offset:37888
	ds_read_b128 v[210:213], v189 offset:38912
	ds_read_b128 v[214:217], v189 offset:39936
	s_waitcnt vmcnt(8)
	s_waitcnt lgkmcnt(0)
	s_setprio 1
	s_barrier
	v_mfma_f32_16x16x32_bf16 v[126:129], v[130:133], v[176:179], v[126:129]
	v_mfma_f32_16x16x32_bf16 v[122:125], v[138:141], v[176:179], v[122:125]
	v_mfma_f32_16x16x32_bf16 v[110:113], v[130:133], v[184:187], v[110:113]
	v_mfma_f32_16x16x32_bf16 v[106:109], v[138:141], v[184:187], v[106:109]
	v_mfma_f32_16x16x32_bf16 v[98:101], v[130:133], v[202:205], v[98:101]
	v_mfma_f32_16x16x32_bf16 v[90:93], v[138:141], v[202:205], v[90:93]
	v_mfma_f32_16x16x32_bf16 v[82:85], v[130:133], v[210:213], v[82:85]
	v_mfma_f32_16x16x32_bf16 v[74:77], v[138:141], v[210:213], v[74:77]
	v_mfma_f32_16x16x32_bf16 v[126:129], v[134:137], v[180:183], v[126:129]
	v_mfma_f32_16x16x32_bf16 v[122:125], v[142:145], v[180:183], v[122:125]
	v_mfma_f32_16x16x32_bf16 v[110:113], v[134:137], v[190:193], v[110:113]
	v_mfma_f32_16x16x32_bf16 v[106:109], v[142:145], v[190:193], v[106:109]
	v_mfma_f32_16x16x32_bf16 v[98:101], v[134:137], v[206:209], v[98:101]
	v_mfma_f32_16x16x32_bf16 v[90:93], v[142:145], v[206:209], v[90:93]
	v_mfma_f32_16x16x32_bf16 v[82:85], v[134:137], v[214:217], v[82:85]
	v_mfma_f32_16x16x32_bf16 v[74:77], v[142:145], v[214:217], v[74:77]
	v_mfma_f32_16x16x32_bf16 v[118:121], v[146:149], v[176:179], v[118:121]
	v_mfma_f32_16x16x32_bf16 v[114:117], v[168:171], v[176:179], v[114:117]
	v_mfma_f32_16x16x32_bf16 v[102:105], v[146:149], v[184:187], v[102:105]
	v_mfma_f32_16x16x32_bf16 v[94:97], v[168:171], v[184:187], v[94:97]
	v_mfma_f32_16x16x32_bf16 v[86:89], v[146:149], v[202:205], v[86:89]
	v_mfma_f32_16x16x32_bf16 v[78:81], v[168:171], v[202:205], v[78:81]
	v_mfma_f32_16x16x32_bf16 v[70:73], v[146:149], v[210:213], v[70:73]
	v_mfma_f32_16x16x32_bf16 v[66:69], v[168:171], v[210:213], v[66:69]
	v_mfma_f32_16x16x32_bf16 v[118:121], v[164:167], v[180:183], v[118:121]
	v_mfma_f32_16x16x32_bf16 v[114:117], v[172:175], v[180:183], v[114:117]
	v_mfma_f32_16x16x32_bf16 v[102:105], v[164:167], v[190:193], v[102:105]
	v_mfma_f32_16x16x32_bf16 v[94:97], v[172:175], v[190:193], v[94:97]
	v_mfma_f32_16x16x32_bf16 v[86:89], v[164:167], v[206:209], v[86:89]
	v_mfma_f32_16x16x32_bf16 v[78:81], v[172:175], v[206:209], v[78:81]
	v_mfma_f32_16x16x32_bf16 v[70:73], v[164:167], v[214:217], v[70:73]
	v_mfma_f32_16x16x32_bf16 v[66:69], v[172:175], v[214:217], v[66:69]
	s_barrier
	s_setprio 0
	s_add_i32 s0, s0, s26
	s_mov_b32 m0, s0
	s_nop 0
	global_load_lds_dwordx4 v196, s[98:99]
	s_add_i32 m0, s0, 0x2000
	s_add_u32 s48, s50, 0x158080
	s_addc_u32 s49, s51, 0
	s_add_i32 s0, s1, s26
	global_load_lds_dwordx4 v154, s[98:99]
	s_mov_b32 m0, s0
	s_nop 0
	global_load_lds_dwordx4 v196, s[48:49]
	s_add_i32 m0, s0, 0x2000
	s_nop 0
	global_load_lds_dwordx4 v154, s[48:49]
	s_mov_b32 m0, s35
	s_nop 0
	global_load_lds_dwordx4 v150, s[78:79]
	s_mov_b32 m0, s58
	s_nop 0
	global_load_lds_dwordx4 v152, s[78:79]
	ds_read_b128 v[176:179], v189 offset:49152
	ds_read_b128 v[180:183], v189 offset:50176
	ds_read_b128 v[184:187], v189 offset:51200
	ds_read_b128 v[190:193], v189 offset:52224
	ds_read_b128 v[202:205], v189 offset:53248
	ds_read_b128 v[206:209], v189 offset:54272
	ds_read_b128 v[210:213], v189 offset:55296
	ds_read_b128 v[214:217], v189 offset:56320
	s_waitcnt vmcnt(8)
	s_waitcnt lgkmcnt(0)
	s_setprio 1
	s_barrier
	v_mfma_f32_16x16x32_bf16 v[62:65], v[130:133], v[176:179], v[62:65]
	v_mfma_f32_16x16x32_bf16 v[58:61], v[138:141], v[176:179], v[58:61]
	v_mfma_f32_16x16x32_bf16 v[50:53], v[130:133], v[184:187], v[50:53]
	v_mfma_f32_16x16x32_bf16 v[42:45], v[138:141], v[184:187], v[42:45]
	v_mfma_f32_16x16x32_bf16 v[34:37], v[130:133], v[202:205], v[34:37]
	v_mfma_f32_16x16x32_bf16 v[26:29], v[138:141], v[202:205], v[26:29]
	v_mfma_f32_16x16x32_bf16 v[18:21], v[130:133], v[210:213], v[18:21]
	v_mfma_f32_16x16x32_bf16 v[10:13], v[138:141], v[210:213], v[10:13]
	v_mfma_f32_16x16x32_bf16 v[62:65], v[134:137], v[180:183], v[62:65]
	v_mfma_f32_16x16x32_bf16 v[58:61], v[142:145], v[180:183], v[58:61]
	v_mfma_f32_16x16x32_bf16 v[50:53], v[134:137], v[190:193], v[50:53]
	v_mfma_f32_16x16x32_bf16 v[42:45], v[142:145], v[190:193], v[42:45]
	v_mfma_f32_16x16x32_bf16 v[34:37], v[134:137], v[206:209], v[34:37]
	v_mfma_f32_16x16x32_bf16 v[26:29], v[142:145], v[206:209], v[26:29]
	v_mfma_f32_16x16x32_bf16 v[18:21], v[134:137], v[214:217], v[18:21]
	v_mfma_f32_16x16x32_bf16 v[10:13], v[142:145], v[214:217], v[10:13]
	v_mfma_f32_16x16x32_bf16 v[54:57], v[146:149], v[176:179], v[54:57]
	v_mfma_f32_16x16x32_bf16 v[46:49], v[168:171], v[176:179], v[46:49]
	v_mfma_f32_16x16x32_bf16 v[38:41], v[146:149], v[184:187], v[38:41]
	v_mfma_f32_16x16x32_bf16 v[30:33], v[168:171], v[184:187], v[30:33]
	v_mfma_f32_16x16x32_bf16 v[22:25], v[146:149], v[202:205], v[22:25]
	v_mfma_f32_16x16x32_bf16 v[14:17], v[168:171], v[202:205], v[14:17]
	v_mfma_f32_16x16x32_bf16 v[6:9], v[146:149], v[210:213], v[6:9]
	v_mfma_f32_16x16x32_bf16 v[2:5], v[168:171], v[210:213], v[2:5]
	v_mfma_f32_16x16x32_bf16 v[54:57], v[164:167], v[180:183], v[54:57]
	v_mfma_f32_16x16x32_bf16 v[46:49], v[172:175], v[180:183], v[46:49]
	v_mfma_f32_16x16x32_bf16 v[38:41], v[164:167], v[190:193], v[38:41]
	v_mfma_f32_16x16x32_bf16 v[30:33], v[172:175], v[190:193], v[30:33]
	v_mfma_f32_16x16x32_bf16 v[22:25], v[164:167], v[206:209], v[22:25]
	v_mfma_f32_16x16x32_bf16 v[14:17], v[172:175], v[206:209], v[14:17]
	v_mfma_f32_16x16x32_bf16 v[6:9], v[164:167], v[214:217], v[6:9]
	v_mfma_f32_16x16x32_bf16 v[2:5], v[172:175], v[214:217], v[2:5]
	s_barrier
	s_setprio 0
	s_add_u32 s70, s70, 0x100
	s_addc_u32 s71, s71, 0
	s_cmp_ge_i32 s72, s69
	s_mov_b64 s[48:49], s[8:9]
	s_mov_b32 s50, s72
	s_cbranch_scc0 .LBB0_987
	s_and_b64 vcc, exec, s[38:39]
	s_cbranch_vccz .LBB0_990
	s_barrier

.Ldefbar_skip_2:
	v_add_u32_e32 v250, 0x10000, v149
	s_add_i32 s71, s8, 2
	s_add_u32 s0, s58, 0xfff80080
	s_addc_u32 s1, s59, -1
	s_add_i32 s72, 0, 0x10000
	s_cmp_eq_u32 s68, s8
	s_cselect_b32 s63, s43, s1
	s_cselect_b32 s62, s47, s0
	s_cselect_b32 s9, s45, s70
	s_cselect_b32 s8, s67, s69
	s_add_i32 s0, 0, 0x14000
	s_add_i32 m0, s27, 0xc000
	s_nop 0
	global_load_lds_dwordx4 v140, s[58:59]
	s_add_i32 m0, s27, 0xe000
	s_nop 0
	global_load_lds_dwordx4 v138, s[58:59]
	ds_read_b128 v[142:145], v250
	ds_read_b128 v[152:155], v250 offset:1024
	ds_read_b128 v[156:159], v250 offset:2048
	ds_read_b128 v[160:163], v250 offset:3072
	ds_read_b128 v[164:167], v250 offset:16384
	ds_read_b128 v[168:171], v250 offset:17408
	ds_read_b128 v[172:175], v250 offset:18432
	ds_read_b128 v[176:179], v250 offset:19456
	ds_read_b128 v[180:183], v151
	ds_read_b128 v[184:187], v151 offset:1024
	ds_read_b128 v[188:191], v151 offset:2048
	ds_read_b128 v[192:195], v151 offset:3072
	ds_read_b128 v[202:205], v151 offset:4096
	ds_read_b128 v[206:209], v151 offset:5120
	ds_read_b128 v[210:213], v151 offset:6144
	ds_read_b128 v[214:217], v151 offset:7168
	s_waitcnt vmcnt(8)
	s_waitcnt lgkmcnt(0)
	s_setprio 1
	s_barrier
	v_mfma_f32_16x16x32_bf16 v[126:129], v[142:145], v[180:183], 0
	v_mfma_f32_16x16x32_bf16 v[122:125], v[156:159], v[180:183], 0
	v_mfma_f32_16x16x32_bf16 v[118:121], v[142:145], v[188:191], 0
	v_mfma_f32_16x16x32_bf16 v[110:113], v[156:159], v[188:191], 0
	v_mfma_f32_16x16x32_bf16 v[102:105], v[142:145], v[202:205], 0
	v_mfma_f32_16x16x32_bf16 v[94:97], v[156:159], v[202:205], 0
	v_mfma_f32_16x16x32_bf16 v[86:89], v[142:145], v[210:213], 0
	v_mfma_f32_16x16x32_bf16 v[78:81], v[156:159], v[210:213], 0
	v_mfma_f32_16x16x32_bf16 v[126:129], v[152:155], v[184:187], v[126:129]
	v_mfma_f32_16x16x32_bf16 v[122:125], v[160:163], v[184:187], v[122:125]
	v_mfma_f32_16x16x32_bf16 v[118:121], v[152:155], v[192:195], v[118:121]
	v_mfma_f32_16x16x32_bf16 v[110:113], v[160:163], v[192:195], v[110:113]
	v_mfma_f32_16x16x32_bf16 v[102:105], v[152:155], v[206:209], v[102:105]
	v_mfma_f32_16x16x32_bf16 v[94:97], v[160:163], v[206:209], v[94:97]
	v_mfma_f32_16x16x32_bf16 v[86:89], v[152:155], v[214:217], v[86:89]
	v_mfma_f32_16x16x32_bf16 v[78:81], v[160:163], v[214:217], v[78:81]
	v_mfma_f32_16x16x32_bf16 v[114:117], v[164:167], v[180:183], 0
	v_mfma_f32_16x16x32_bf16 v[106:109], v[172:175], v[180:183], 0
	v_mfma_f32_16x16x32_bf16 v[98:101], v[164:167], v[188:191], 0
	v_mfma_f32_16x16x32_bf16 v[90:93], v[172:175], v[188:191], 0
	v_mfma_f32_16x16x32_bf16 v[82:85], v[164:167], v[202:205], 0
	v_mfma_f32_16x16x32_bf16 v[74:77], v[172:175], v[202:205], 0
	v_mfma_f32_16x16x32_bf16 v[70:73], v[164:167], v[210:213], 0
	v_mfma_f32_16x16x32_bf16 v[66:69], v[172:175], v[210:213], 0
	v_mfma_f32_16x16x32_bf16 v[114:117], v[168:171], v[184:187], v[114:117]
	v_mfma_f32_16x16x32_bf16 v[106:109], v[176:179], v[184:187], v[106:109]
	v_mfma_f32_16x16x32_bf16 v[98:101], v[168:171], v[192:195], v[98:101]
	v_mfma_f32_16x16x32_bf16 v[90:93], v[176:179], v[192:195], v[90:93]
	v_mfma_f32_16x16x32_bf16 v[82:85], v[168:171], v[206:209], v[82:85]
	v_mfma_f32_16x16x32_bf16 v[74:77], v[176:179], v[206:209], v[74:77]
	v_mfma_f32_16x16x32_bf16 v[70:73], v[168:171], v[214:217], v[70:73]
	v_mfma_f32_16x16x32_bf16 v[66:69], v[176:179], v[214:217], v[66:69]
	s_barrier
	s_setprio 0
	s_add_i32 s1, s72, s26
	s_add_u32 s98, s8, s16
	s_addc_u32 s99, s9, s17
	s_mov_b32 m0, s1
	s_nop 0
	global_load_lds_dwordx4 v196, s[8:9]
	s_add_i32 m0, s1, 0x2000
	s_add_u32 s72, s8, 0x80000
	s_addc_u32 s73, s9, 0
	s_add_i32 s0, s0, s26
	global_load_lds_dwordx4 v130, s[8:9]
	s_mov_b32 m0, s0
	s_nop 0
	global_load_lds_dwordx4 v196, s[72:73]
	s_add_i32 m0, s0, 0x2000
	s_nop 0
	global_load_lds_dwordx4 v130, s[72:73]
	s_add_u32 s78, s62, s16
	s_addc_u32 s79, s63, s17
	s_mov_b32 m0, s27
	s_nop 0
	global_load_lds_dwordx4 v134, s[62:63]
	s_mov_b32 m0, s28
	s_nop 0
	global_load_lds_dwordx4 v132, s[62:63]
	ds_read_b128 v[180:183], v151 offset:16384
	ds_read_b128 v[184:187], v151 offset:17408
	ds_read_b128 v[188:191], v151 offset:18432
	ds_read_b128 v[192:195], v151 offset:19456
	ds_read_b128 v[202:205], v151 offset:20480
	ds_read_b128 v[206:209], v151 offset:21504
	ds_read_b128 v[210:213], v151 offset:22528
	ds_read_b128 v[214:217], v151 offset:23552
	s_waitcnt vmcnt(8)
	s_waitcnt lgkmcnt(0)
	s_setprio 1
	s_barrier
	v_mfma_f32_16x16x32_bf16 v[62:65], v[142:145], v[180:183], 0
	v_mfma_f32_16x16x32_bf16 v[58:61], v[156:159], v[180:183], 0
	v_mfma_f32_16x16x32_bf16 v[54:57], v[142:145], v[188:191], 0
	v_mfma_f32_16x16x32_bf16 v[46:49], v[156:159], v[188:191], 0
	v_mfma_f32_16x16x32_bf16 v[38:41], v[142:145], v[202:205], 0
	v_mfma_f32_16x16x32_bf16 v[30:33], v[156:159], v[202:205], 0
	v_mfma_f32_16x16x32_bf16 v[22:25], v[142:145], v[210:213], 0
	v_mfma_f32_16x16x32_bf16 v[14:17], v[156:159], v[210:213], 0
	v_mfma_f32_16x16x32_bf16 v[62:65], v[152:155], v[184:187], v[62:65]
	v_mfma_f32_16x16x32_bf16 v[58:61], v[160:163], v[184:187], v[58:61]
	v_mfma_f32_16x16x32_bf16 v[54:57], v[152:155], v[192:195], v[54:57]
	v_mfma_f32_16x16x32_bf16 v[46:49], v[160:163], v[192:195], v[46:49]
	v_mfma_f32_16x16x32_bf16 v[38:41], v[152:155], v[206:209], v[38:41]
	v_mfma_f32_16x16x32_bf16 v[30:33], v[160:163], v[206:209], v[30:33]
	v_mfma_f32_16x16x32_bf16 v[22:25], v[152:155], v[214:217], v[22:25]
	v_mfma_f32_16x16x32_bf16 v[14:17], v[160:163], v[214:217], v[14:17]
	v_mfma_f32_16x16x32_bf16 v[50:53], v[164:167], v[180:183], 0
	v_mfma_f32_16x16x32_bf16 v[42:45], v[172:175], v[180:183], 0
	v_mfma_f32_16x16x32_bf16 v[34:37], v[164:167], v[188:191], 0
	v_mfma_f32_16x16x32_bf16 v[26:29], v[172:175], v[188:191], 0
	v_mfma_f32_16x16x32_bf16 v[18:21], v[164:167], v[202:205], 0
	v_mfma_f32_16x16x32_bf16 v[10:13], v[172:175], v[202:205], 0
	v_mfma_f32_16x16x32_bf16 v[6:9], v[164:167], v[210:213], 0
	v_mfma_f32_16x16x32_bf16 v[2:5], v[172:175], v[210:213], 0
	v_mfma_f32_16x16x32_bf16 v[50:53], v[168:171], v[184:187], v[50:53]
	v_mfma_f32_16x16x32_bf16 v[42:45], v[176:179], v[184:187], v[42:45]
	v_mfma_f32_16x16x32_bf16 v[34:37], v[168:171], v[192:195], v[34:37]
	v_mfma_f32_16x16x32_bf16 v[26:29], v[176:179], v[192:195], v[26:29]
	v_mfma_f32_16x16x32_bf16 v[18:21], v[168:171], v[206:209], v[18:21]
	v_mfma_f32_16x16x32_bf16 v[10:13], v[176:179], v[206:209], v[10:13]
	v_mfma_f32_16x16x32_bf16 v[6:9], v[168:171], v[214:217], v[6:9]
	v_mfma_f32_16x16x32_bf16 v[2:5], v[176:179], v[214:217], v[2:5]
	s_barrier
	s_setprio 0
	s_branch .Lkmid_2
.LBB0_1135:
	s_add_i32 s71, s8, 2
	s_add_u32 s0, s58, 0xfff80080
	s_addc_u32 s1, s59, -1
	s_add_i32 s72, 0, 0x10000
	s_cmp_eq_u32 s68, s8
	s_cselect_b32 s63, s43, s1
	s_cselect_b32 s62, s47, s0
	s_cselect_b32 s9, s45, s70
	s_cselect_b32 s8, s67, s69
	s_add_i32 s0, 0, 0x14000
	s_add_i32 m0, s27, 0xc000
	s_nop 0
	global_load_lds_dwordx4 v140, s[58:59]
	s_add_i32 m0, s27, 0xe000
	s_nop 0
	global_load_lds_dwordx4 v138, s[58:59]
	ds_read_b128 v[142:145], v250
	ds_read_b128 v[152:155], v250 offset:1024
	ds_read_b128 v[156:159], v250 offset:2048
	ds_read_b128 v[160:163], v250 offset:3072
	ds_read_b128 v[164:167], v250 offset:16384
	ds_read_b128 v[168:171], v250 offset:17408
	ds_read_b128 v[172:175], v250 offset:18432
	ds_read_b128 v[176:179], v250 offset:19456
	ds_read_b128 v[180:183], v151
	ds_read_b128 v[184:187], v151 offset:1024
	ds_read_b128 v[188:191], v151 offset:2048
	ds_read_b128 v[192:195], v151 offset:3072
	ds_read_b128 v[202:205], v151 offset:4096
	ds_read_b128 v[206:209], v151 offset:5120
	ds_read_b128 v[210:213], v151 offset:6144
	ds_read_b128 v[214:217], v151 offset:7168
	s_waitcnt vmcnt(8)
	s_waitcnt lgkmcnt(0)
	s_setprio 1
	s_barrier
	v_mfma_f32_16x16x32_bf16 v[126:129], v[142:145], v[180:183], v[126:129]
	v_mfma_f32_16x16x32_bf16 v[122:125], v[156:159], v[180:183], v[122:125]
	v_mfma_f32_16x16x32_bf16 v[118:121], v[142:145], v[188:191], v[118:121]
	v_mfma_f32_16x16x32_bf16 v[110:113], v[156:159], v[188:191], v[110:113]
	v_mfma_f32_16x16x32_bf16 v[102:105], v[142:145], v[202:205], v[102:105]
	v_mfma_f32_16x16x32_bf16 v[94:97], v[156:159], v[202:205], v[94:97]
	v_mfma_f32_16x16x32_bf16 v[86:89], v[142:145], v[210:213], v[86:89]
	v_mfma_f32_16x16x32_bf16 v[78:81], v[156:159], v[210:213], v[78:81]
	v_mfma_f32_16x16x32_bf16 v[126:129], v[152:155], v[184:187], v[126:129]
	v_mfma_f32_16x16x32_bf16 v[122:125], v[160:163], v[184:187], v[122:125]
	v_mfma_f32_16x16x32_bf16 v[118:121], v[152:155], v[192:195], v[118:121]
	v_mfma_f32_16x16x32_bf16 v[110:113], v[160:163], v[192:195], v[110:113]
	v_mfma_f32_16x16x32_bf16 v[102:105], v[152:155], v[206:209], v[102:105]
	v_mfma_f32_16x16x32_bf16 v[94:97], v[160:163], v[206:209], v[94:97]
	v_mfma_f32_16x16x32_bf16 v[86:89], v[152:155], v[214:217], v[86:89]
	v_mfma_f32_16x16x32_bf16 v[78:81], v[160:163], v[214:217], v[78:81]
	v_mfma_f32_16x16x32_bf16 v[114:117], v[164:167], v[180:183], v[114:117]
	v_mfma_f32_16x16x32_bf16 v[106:109], v[172:175], v[180:183], v[106:109]
	v_mfma_f32_16x16x32_bf16 v[98:101], v[164:167], v[188:191], v[98:101]
	v_mfma_f32_16x16x32_bf16 v[90:93], v[172:175], v[188:191], v[90:93]
	v_mfma_f32_16x16x32_bf16 v[82:85], v[164:167], v[202:205], v[82:85]
	v_mfma_f32_16x16x32_bf16 v[74:77], v[172:175], v[202:205], v[74:77]
	v_mfma_f32_16x16x32_bf16 v[70:73], v[164:167], v[210:213], v[70:73]
	v_mfma_f32_16x16x32_bf16 v[66:69], v[172:175], v[210:213], v[66:69]
	v_mfma_f32_16x16x32_bf16 v[114:117], v[168:171], v[184:187], v[114:117]
	v_mfma_f32_16x16x32_bf16 v[106:109], v[176:179], v[184:187], v[106:109]
	v_mfma_f32_16x16x32_bf16 v[98:101], v[168:171], v[192:195], v[98:101]
	v_mfma_f32_16x16x32_bf16 v[90:93], v[176:179], v[192:195], v[90:93]
	v_mfma_f32_16x16x32_bf16 v[82:85], v[168:171], v[206:209], v[82:85]
	v_mfma_f32_16x16x32_bf16 v[74:77], v[176:179], v[206:209], v[74:77]
	v_mfma_f32_16x16x32_bf16 v[70:73], v[168:171], v[214:217], v[70:73]
	v_mfma_f32_16x16x32_bf16 v[66:69], v[176:179], v[214:217], v[66:69]
	s_barrier
	s_setprio 0
	s_add_i32 s1, s72, s26
	s_add_u32 s98, s8, s16
	s_addc_u32 s99, s9, s17
	s_mov_b32 m0, s1
	s_nop 0
	global_load_lds_dwordx4 v196, s[8:9]
	s_add_i32 m0, s1, 0x2000
	s_add_u32 s72, s8, 0x80000
	s_addc_u32 s73, s9, 0
	s_add_i32 s0, s0, s26
	global_load_lds_dwordx4 v130, s[8:9]
	s_mov_b32 m0, s0
	s_nop 0
	global_load_lds_dwordx4 v196, s[72:73]
	s_add_i32 m0, s0, 0x2000
	s_nop 0
	global_load_lds_dwordx4 v130, s[72:73]
	s_add_u32 s78, s62, s16
	s_addc_u32 s79, s63, s17
	s_mov_b32 m0, s27
	s_nop 0
	global_load_lds_dwordx4 v134, s[62:63]
	s_mov_b32 m0, s28
	s_nop 0
	global_load_lds_dwordx4 v132, s[62:63]
	ds_read_b128 v[180:183], v151 offset:16384
	ds_read_b128 v[184:187], v151 offset:17408
	ds_read_b128 v[188:191], v151 offset:18432
	ds_read_b128 v[192:195], v151 offset:19456
	ds_read_b128 v[202:205], v151 offset:20480
	ds_read_b128 v[206:209], v151 offset:21504
	ds_read_b128 v[210:213], v151 offset:22528
	ds_read_b128 v[214:217], v151 offset:23552
	s_waitcnt vmcnt(8)
	s_waitcnt lgkmcnt(0)
	s_setprio 1
	s_barrier
	v_mfma_f32_16x16x32_bf16 v[62:65], v[142:145], v[180:183], v[62:65]
	v_mfma_f32_16x16x32_bf16 v[58:61], v[156:159], v[180:183], v[58:61]
	v_mfma_f32_16x16x32_bf16 v[54:57], v[142:145], v[188:191], v[54:57]
	v_mfma_f32_16x16x32_bf16 v[46:49], v[156:159], v[188:191], v[46:49]
	v_mfma_f32_16x16x32_bf16 v[38:41], v[142:145], v[202:205], v[38:41]
	v_mfma_f32_16x16x32_bf16 v[30:33], v[156:159], v[202:205], v[30:33]
	v_mfma_f32_16x16x32_bf16 v[22:25], v[142:145], v[210:213], v[22:25]
	v_mfma_f32_16x16x32_bf16 v[14:17], v[156:159], v[210:213], v[14:17]
	v_mfma_f32_16x16x32_bf16 v[62:65], v[152:155], v[184:187], v[62:65]
	v_mfma_f32_16x16x32_bf16 v[58:61], v[160:163], v[184:187], v[58:61]
	v_mfma_f32_16x16x32_bf16 v[54:57], v[152:155], v[192:195], v[54:57]
	v_mfma_f32_16x16x32_bf16 v[46:49], v[160:163], v[192:195], v[46:49]
	v_mfma_f32_16x16x32_bf16 v[38:41], v[152:155], v[206:209], v[38:41]
	v_mfma_f32_16x16x32_bf16 v[30:33], v[160:163], v[206:209], v[30:33]
	v_mfma_f32_16x16x32_bf16 v[22:25], v[152:155], v[214:217], v[22:25]
	v_mfma_f32_16x16x32_bf16 v[14:17], v[160:163], v[214:217], v[14:17]
	v_mfma_f32_16x16x32_bf16 v[50:53], v[164:167], v[180:183], v[50:53]
	v_mfma_f32_16x16x32_bf16 v[42:45], v[172:175], v[180:183], v[42:45]
	v_mfma_f32_16x16x32_bf16 v[34:37], v[164:167], v[188:191], v[34:37]
	v_mfma_f32_16x16x32_bf16 v[26:29], v[172:175], v[188:191], v[26:29]
	v_mfma_f32_16x16x32_bf16 v[18:21], v[164:167], v[202:205], v[18:21]
	v_mfma_f32_16x16x32_bf16 v[10:13], v[172:175], v[202:205], v[10:13]
	v_mfma_f32_16x16x32_bf16 v[6:9], v[164:167], v[210:213], v[6:9]
	v_mfma_f32_16x16x32_bf16 v[2:5], v[172:175], v[210:213], v[2:5]
	v_mfma_f32_16x16x32_bf16 v[50:53], v[168:171], v[184:187], v[50:53]
	v_mfma_f32_16x16x32_bf16 v[42:45], v[176:179], v[184:187], v[42:45]
	v_mfma_f32_16x16x32_bf16 v[34:37], v[168:171], v[192:195], v[34:37]
	v_mfma_f32_16x16x32_bf16 v[26:29], v[176:179], v[192:195], v[26:29]
	v_mfma_f32_16x16x32_bf16 v[18:21], v[168:171], v[206:209], v[18:21]
	v_mfma_f32_16x16x32_bf16 v[10:13], v[176:179], v[206:209], v[10:13]
	v_mfma_f32_16x16x32_bf16 v[6:9], v[168:171], v[214:217], v[6:9]
	v_mfma_f32_16x16x32_bf16 v[2:5], v[176:179], v[214:217], v[2:5]
	s_barrier
	s_setprio 0
.Lkmid_2:
	s_add_i32 s0, 0, 0x18000
	s_add_i32 s1, 0, 0x1c000
	s_add_u32 s62, s62, 0x80000
	s_addc_u32 s63, s63, 0
	s_mov_b32 m0, s29
	s_nop 0
	global_load_lds_dwordx4 v134, s[62:63]
	s_mov_b32 m0, s30
	s_nop 0
	global_load_lds_dwordx4 v132, s[62:63]
	ds_read_b128 v[142:145], v250 offset:32768
	ds_read_b128 v[152:155], v250 offset:33792
	ds_read_b128 v[156:159], v250 offset:34816
	ds_read_b128 v[160:163], v250 offset:35840
	ds_read_b128 v[164:167], v250 offset:49152
	ds_read_b128 v[168:171], v250 offset:50176
	ds_read_b128 v[172:175], v250 offset:51200
	ds_read_b128 v[176:179], v250 offset:52224
	ds_read_b128 v[180:183], v151 offset:32768
	ds_read_b128 v[184:187], v151 offset:33792
	ds_read_b128 v[188:191], v151 offset:34816
	ds_read_b128 v[192:195], v151 offset:35840
	ds_read_b128 v[202:205], v151 offset:36864
	ds_read_b128 v[206:209], v151 offset:37888
	ds_read_b128 v[210:213], v151 offset:38912
	ds_read_b128 v[214:217], v151 offset:39936
	s_waitcnt vmcnt(8)
	s_waitcnt lgkmcnt(0)
	s_setprio 1
	s_barrier
	v_mfma_f32_16x16x32_bf16 v[126:129], v[142:145], v[180:183], v[126:129]
	v_mfma_f32_16x16x32_bf16 v[122:125], v[156:159], v[180:183], v[122:125]
	v_mfma_f32_16x16x32_bf16 v[118:121], v[142:145], v[188:191], v[118:121]
	v_mfma_f32_16x16x32_bf16 v[110:113], v[156:159], v[188:191], v[110:113]
	v_mfma_f32_16x16x32_bf16 v[102:105], v[142:145], v[202:205], v[102:105]
	v_mfma_f32_16x16x32_bf16 v[94:97], v[156:159], v[202:205], v[94:97]
	v_mfma_f32_16x16x32_bf16 v[86:89], v[142:145], v[210:213], v[86:89]
	v_mfma_f32_16x16x32_bf16 v[78:81], v[156:159], v[210:213], v[78:81]
	v_mfma_f32_16x16x32_bf16 v[126:129], v[152:155], v[184:187], v[126:129]
	v_mfma_f32_16x16x32_bf16 v[122:125], v[160:163], v[184:187], v[122:125]
	v_mfma_f32_16x16x32_bf16 v[118:121], v[152:155], v[192:195], v[118:121]
	v_mfma_f32_16x16x32_bf16 v[110:113], v[160:163], v[192:195], v[110:113]
	v_mfma_f32_16x16x32_bf16 v[102:105], v[152:155], v[206:209], v[102:105]
	v_mfma_f32_16x16x32_bf16 v[94:97], v[160:163], v[206:209], v[94:97]
	v_mfma_f32_16x16x32_bf16 v[86:89], v[152:155], v[214:217], v[86:89]
	v_mfma_f32_16x16x32_bf16 v[78:81], v[160:163], v[214:217], v[78:81]
	v_mfma_f32_16x16x32_bf16 v[114:117], v[164:167], v[180:183], v[114:117]
	v_mfma_f32_16x16x32_bf16 v[106:109], v[172:175], v[180:183], v[106:109]
	v_mfma_f32_16x16x32_bf16 v[98:101], v[164:167], v[188:191], v[98:101]
	v_mfma_f32_16x16x32_bf16 v[90:93], v[172:175], v[188:191], v[90:93]
	v_mfma_f32_16x16x32_bf16 v[82:85], v[164:167], v[202:205], v[82:85]
	v_mfma_f32_16x16x32_bf16 v[74:77], v[172:175], v[202:205], v[74:77]
	v_mfma_f32_16x16x32_bf16 v[70:73], v[164:167], v[210:213], v[70:73]
	v_mfma_f32_16x16x32_bf16 v[66:69], v[172:175], v[210:213], v[66:69]
	v_mfma_f32_16x16x32_bf16 v[114:117], v[168:171], v[184:187], v[114:117]
	v_mfma_f32_16x16x32_bf16 v[106:109], v[176:179], v[184:187], v[106:109]
	v_mfma_f32_16x16x32_bf16 v[98:101], v[168:171], v[192:195], v[98:101]
	v_mfma_f32_16x16x32_bf16 v[90:93], v[176:179], v[192:195], v[90:93]
	v_mfma_f32_16x16x32_bf16 v[82:85], v[168:171], v[206:209], v[82:85]
	v_mfma_f32_16x16x32_bf16 v[74:77], v[176:179], v[206:209], v[74:77]
	v_mfma_f32_16x16x32_bf16 v[70:73], v[168:171], v[214:217], v[70:73]
	v_mfma_f32_16x16x32_bf16 v[66:69], v[176:179], v[214:217], v[66:69]
	s_barrier
	s_setprio 0
	s_add_i32 s0, s0, s26
	s_mov_b32 m0, s0
	s_nop 0
	global_load_lds_dwordx4 v196, s[98:99]
	s_add_i32 m0, s0, 0x2000
	s_add_u32 s8, s8, 0x80080
	s_addc_u32 s9, s9, 0
	s_add_i32 s0, s1, s26
	global_load_lds_dwordx4 v130, s[98:99]
	s_mov_b32 m0, s0
	s_nop 0
	global_load_lds_dwordx4 v196, s[8:9]
	s_add_i32 m0, s0, 0x2000
	s_nop 0
	global_load_lds_dwordx4 v130, s[8:9]
	s_mov_b32 m0, s31
	s_nop 0
	global_load_lds_dwordx4 v134, s[78:79]
	s_mov_b32 m0, s34
	s_nop 0
	global_load_lds_dwordx4 v132, s[78:79]
	ds_read_b128 v[180:183], v151 offset:49152
	ds_read_b128 v[184:187], v151 offset:50176
	ds_read_b128 v[188:191], v151 offset:51200
	ds_read_b128 v[192:195], v151 offset:52224
	ds_read_b128 v[202:205], v151 offset:53248
	ds_read_b128 v[206:209], v151 offset:54272
	ds_read_b128 v[210:213], v151 offset:55296
	ds_read_b128 v[214:217], v151 offset:56320
	s_waitcnt vmcnt(8)
	s_waitcnt lgkmcnt(0)
	s_setprio 1
	s_barrier
	v_mfma_f32_16x16x32_bf16 v[62:65], v[142:145], v[180:183], v[62:65]
	v_mfma_f32_16x16x32_bf16 v[58:61], v[156:159], v[180:183], v[58:61]
	v_mfma_f32_16x16x32_bf16 v[54:57], v[142:145], v[188:191], v[54:57]
	v_mfma_f32_16x16x32_bf16 v[46:49], v[156:159], v[188:191], v[46:49]
	v_mfma_f32_16x16x32_bf16 v[38:41], v[142:145], v[202:205], v[38:41]
	v_mfma_f32_16x16x32_bf16 v[30:33], v[156:159], v[202:205], v[30:33]
	v_mfma_f32_16x16x32_bf16 v[22:25], v[142:145], v[210:213], v[22:25]
	v_mfma_f32_16x16x32_bf16 v[14:17], v[156:159], v[210:213], v[14:17]
	v_mfma_f32_16x16x32_bf16 v[62:65], v[152:155], v[184:187], v[62:65]
	v_mfma_f32_16x16x32_bf16 v[58:61], v[160:163], v[184:187], v[58:61]
	v_mfma_f32_16x16x32_bf16 v[54:57], v[152:155], v[192:195], v[54:57]
	v_mfma_f32_16x16x32_bf16 v[46:49], v[160:163], v[192:195], v[46:49]
	v_mfma_f32_16x16x32_bf16 v[38:41], v[152:155], v[206:209], v[38:41]
	v_mfma_f32_16x16x32_bf16 v[30:33], v[160:163], v[206:209], v[30:33]
	v_mfma_f32_16x16x32_bf16 v[22:25], v[152:155], v[214:217], v[22:25]
	v_mfma_f32_16x16x32_bf16 v[14:17], v[160:163], v[214:217], v[14:17]
	v_mfma_f32_16x16x32_bf16 v[50:53], v[164:167], v[180:183], v[50:53]
	v_mfma_f32_16x16x32_bf16 v[42:45], v[172:175], v[180:183], v[42:45]
	v_mfma_f32_16x16x32_bf16 v[34:37], v[164:167], v[188:191], v[34:37]
	v_mfma_f32_16x16x32_bf16 v[26:29], v[172:175], v[188:191], v[26:29]
	v_mfma_f32_16x16x32_bf16 v[18:21], v[164:167], v[202:205], v[18:21]
	v_mfma_f32_16x16x32_bf16 v[10:13], v[172:175], v[202:205], v[10:13]
	v_mfma_f32_16x16x32_bf16 v[6:9], v[164:167], v[210:213], v[6:9]
	v_mfma_f32_16x16x32_bf16 v[2:5], v[172:175], v[210:213], v[2:5]
	v_mfma_f32_16x16x32_bf16 v[50:53], v[168:171], v[184:187], v[50:53]
	v_mfma_f32_16x16x32_bf16 v[42:45], v[176:179], v[184:187], v[42:45]
	v_mfma_f32_16x16x32_bf16 v[34:37], v[168:171], v[192:195], v[34:37]
	v_mfma_f32_16x16x32_bf16 v[26:29], v[176:179], v[192:195], v[26:29]
	v_mfma_f32_16x16x32_bf16 v[18:21], v[168:171], v[206:209], v[18:21]
	v_mfma_f32_16x16x32_bf16 v[10:13], v[176:179], v[206:209], v[10:13]
	v_mfma_f32_16x16x32_bf16 v[6:9], v[168:171], v[214:217], v[6:9]
	v_mfma_f32_16x16x32_bf16 v[2:5], v[176:179], v[214:217], v[2:5]
	s_barrier
	s_setprio 0
	s_add_u32 s69, s69, 0x100
	s_addc_u32 s70, s70, 0
	s_add_u32 s58, s58, 0x100
	s_addc_u32 s59, s59, 0
	s_cmp_ge_i32 s71, s64
	s_mov_b32 s8, s71
	s_cbranch_scc0 .LBB0_1135
	s_and_b64 vcc, exec, s[38:39]
	s_cbranch_vccz .LBB0_1138
	s_barrier

.Ldefbar_skip_3:
	v_add_u32_e32 v250, 0x10000, v244
	s_add_i32 s73, s8, 2
	s_add_u32 s0, s44, 0xfff00080
	s_addc_u32 s1, s45, -1
	s_add_i32 s77, 0, 0x10000
	s_cmp_eq_u32 s70, s8
	s_cselect_b32 s67, s51, s1
	s_cselect_b32 s66, s53, s0
	s_cselect_b32 s9, s49, s72
	s_cselect_b32 s8, s69, s71
	s_add_i32 s78, 0, 0x14000
	s_add_i32 m0, s3, 0xc000
	s_nop 0
	global_load_lds_dwordx4 v210, s[44:45]
	s_add_i32 m0, s3, 0xe000
	s_nop 0
	global_load_lds_dwordx4 v208, s[44:45]
	ds_read_b128 v[130:133], v250
	ds_read_b128 v[134:137], v250 offset:1024
	ds_read_b128 v[138:141], v250 offset:2048
	ds_read_b128 v[142:145], v250 offset:3072
	ds_read_b128 v[146:149], v250 offset:16384
	ds_read_b128 v[150:153], v250 offset:17408
	ds_read_b128 v[154:157], v250 offset:18432
	ds_read_b128 v[158:161], v250 offset:19456
	ds_read_b128 v[162:165], v246
	ds_read_b128 v[166:169], v246 offset:1024
	ds_read_b128 v[170:173], v246 offset:2048
	ds_read_b128 v[174:177], v246 offset:3072
	ds_read_b128 v[178:181], v246 offset:4096
	ds_read_b128 v[182:185], v246 offset:5120
	ds_read_b128 v[186:189], v246 offset:6144
	ds_read_b128 v[190:193], v246 offset:7168
	s_waitcnt vmcnt(8)
	s_waitcnt lgkmcnt(0)
	s_setprio 1
	s_barrier
	v_mfma_f32_16x16x32_bf16 v[126:129], v[130:133], v[162:165], 0
	v_mfma_f32_16x16x32_bf16 v[122:125], v[138:141], v[162:165], 0
	v_mfma_f32_16x16x32_bf16 v[110:113], v[130:133], v[170:173], 0
	v_mfma_f32_16x16x32_bf16 v[106:109], v[138:141], v[170:173], 0
	v_mfma_f32_16x16x32_bf16 v[94:97], v[130:133], v[178:181], 0
	v_mfma_f32_16x16x32_bf16 v[90:93], v[138:141], v[178:181], 0
	v_mfma_f32_16x16x32_bf16 v[78:81], v[130:133], v[186:189], 0
	v_mfma_f32_16x16x32_bf16 v[74:77], v[138:141], v[186:189], 0
	v_mfma_f32_16x16x32_bf16 v[126:129], v[134:137], v[166:169], v[126:129]
	v_mfma_f32_16x16x32_bf16 v[122:125], v[142:145], v[166:169], v[122:125]
	v_mfma_f32_16x16x32_bf16 v[110:113], v[134:137], v[174:177], v[110:113]
	v_mfma_f32_16x16x32_bf16 v[106:109], v[142:145], v[174:177], v[106:109]
	v_mfma_f32_16x16x32_bf16 v[94:97], v[134:137], v[182:185], v[94:97]
	v_mfma_f32_16x16x32_bf16 v[90:93], v[142:145], v[182:185], v[90:93]
	v_mfma_f32_16x16x32_bf16 v[78:81], v[134:137], v[190:193], v[78:81]
	v_mfma_f32_16x16x32_bf16 v[74:77], v[142:145], v[190:193], v[74:77]
	v_mfma_f32_16x16x32_bf16 v[118:121], v[146:149], v[162:165], 0
	v_mfma_f32_16x16x32_bf16 v[114:117], v[154:157], v[162:165], 0
	v_mfma_f32_16x16x32_bf16 v[102:105], v[146:149], v[170:173], 0
	v_mfma_f32_16x16x32_bf16 v[98:101], v[154:157], v[170:173], 0
	v_mfma_f32_16x16x32_bf16 v[86:89], v[146:149], v[178:181], 0
	v_mfma_f32_16x16x32_bf16 v[82:85], v[154:157], v[178:181], 0
	v_mfma_f32_16x16x32_bf16 v[70:73], v[146:149], v[186:189], 0
	v_mfma_f32_16x16x32_bf16 v[66:69], v[154:157], v[186:189], 0
	v_mfma_f32_16x16x32_bf16 v[118:121], v[150:153], v[166:169], v[118:121]
	v_mfma_f32_16x16x32_bf16 v[114:117], v[158:161], v[166:169], v[114:117]
	v_mfma_f32_16x16x32_bf16 v[102:105], v[150:153], v[174:177], v[102:105]
	v_mfma_f32_16x16x32_bf16 v[98:101], v[158:161], v[174:177], v[98:101]
	v_mfma_f32_16x16x32_bf16 v[86:89], v[150:153], v[182:185], v[86:89]
	v_mfma_f32_16x16x32_bf16 v[82:85], v[158:161], v[182:185], v[82:85]
	v_mfma_f32_16x16x32_bf16 v[70:73], v[150:153], v[190:193], v[70:73]
	v_mfma_f32_16x16x32_bf16 v[66:69], v[158:161], v[190:193], v[66:69]
	s_barrier
	s_setprio 0
	s_add_i32 s0, s77, s2
	s_add_u32 s98, s8, s16
	s_addc_u32 s99, s9, s17
	s_mov_b32 m0, s0
	s_nop 0
	global_load_lds_dwordx4 v196, s[8:9]
	s_add_i32 m0, s0, 0x2000
	s_add_u32 s0, s8, 0x100000
	s_addc_u32 s1, s9, 0
	s_add_i32 s77, s78, s2
	global_load_lds_dwordx4 v202, s[8:9]
	s_mov_b32 m0, s77
	v_lshl_add_u64 v[216:217], s[66:67], 0, v[204:205]
	global_load_lds_dwordx4 v196, s[0:1]
	s_add_i32 m0, s77, 0x2000
	s_nop 0
	global_load_lds_dwordx4 v202, s[0:1]
	v_lshl_add_u64 v[214:215], s[66:67], 0, v[206:207]
	s_mov_b32 m0, s3
	s_nop 0
	global_load_lds_dwordx4 v206, s[66:67]
	s_mov_b32 m0, s10
	s_nop 0
	global_load_lds_dwordx4 v204, s[66:67]
	ds_read_b128 v[162:165], v246 offset:16384
	ds_read_b128 v[166:169], v246 offset:17408
	ds_read_b128 v[170:173], v246 offset:18432
	ds_read_b128 v[174:177], v246 offset:19456
	ds_read_b128 v[178:181], v246 offset:20480
	ds_read_b128 v[182:185], v246 offset:21504
	ds_read_b128 v[186:189], v246 offset:22528
	ds_read_b128 v[190:193], v246 offset:23552
	s_waitcnt vmcnt(8)
	s_waitcnt lgkmcnt(0)
	s_setprio 1
	s_barrier
	v_mfma_f32_16x16x32_bf16 v[62:65], v[130:133], v[162:165], 0
	v_mfma_f32_16x16x32_bf16 v[58:61], v[138:141], v[162:165], 0
	v_mfma_f32_16x16x32_bf16 v[46:49], v[130:133], v[170:173], 0
	v_mfma_f32_16x16x32_bf16 v[42:45], v[138:141], v[170:173], 0
	v_mfma_f32_16x16x32_bf16 v[30:33], v[130:133], v[178:181], 0
	v_mfma_f32_16x16x32_bf16 v[26:29], v[138:141], v[178:181], 0
	v_mfma_f32_16x16x32_bf16 v[14:17], v[130:133], v[186:189], 0
	v_mfma_f32_16x16x32_bf16 v[10:13], v[138:141], v[186:189], 0
	v_mfma_f32_16x16x32_bf16 v[62:65], v[134:137], v[166:169], v[62:65]
	v_mfma_f32_16x16x32_bf16 v[58:61], v[142:145], v[166:169], v[58:61]
	v_mfma_f32_16x16x32_bf16 v[46:49], v[134:137], v[174:177], v[46:49]
	v_mfma_f32_16x16x32_bf16 v[42:45], v[142:145], v[174:177], v[42:45]
	v_mfma_f32_16x16x32_bf16 v[30:33], v[134:137], v[182:185], v[30:33]
	v_mfma_f32_16x16x32_bf16 v[26:29], v[142:145], v[182:185], v[26:29]
	v_mfma_f32_16x16x32_bf16 v[14:17], v[134:137], v[190:193], v[14:17]
	v_mfma_f32_16x16x32_bf16 v[10:13], v[142:145], v[190:193], v[10:13]
	v_mfma_f32_16x16x32_bf16 v[54:57], v[146:149], v[162:165], 0
	v_mfma_f32_16x16x32_bf16 v[50:53], v[154:157], v[162:165], 0
	v_mfma_f32_16x16x32_bf16 v[38:41], v[146:149], v[170:173], 0
	v_mfma_f32_16x16x32_bf16 v[34:37], v[154:157], v[170:173], 0
	v_mfma_f32_16x16x32_bf16 v[22:25], v[146:149], v[178:181], 0
	v_mfma_f32_16x16x32_bf16 v[18:21], v[154:157], v[178:181], 0
	v_mfma_f32_16x16x32_bf16 v[6:9], v[146:149], v[186:189], 0
	v_mfma_f32_16x16x32_bf16 v[2:5], v[154:157], v[186:189], 0
	v_mfma_f32_16x16x32_bf16 v[54:57], v[150:153], v[166:169], v[54:57]
	v_mfma_f32_16x16x32_bf16 v[50:53], v[158:161], v[166:169], v[50:53]
	v_mfma_f32_16x16x32_bf16 v[38:41], v[150:153], v[174:177], v[38:41]
	v_mfma_f32_16x16x32_bf16 v[34:37], v[158:161], v[174:177], v[34:37]
	v_mfma_f32_16x16x32_bf16 v[22:25], v[150:153], v[182:185], v[22:25]
	v_mfma_f32_16x16x32_bf16 v[18:21], v[158:161], v[182:185], v[18:21]
	v_mfma_f32_16x16x32_bf16 v[6:9], v[150:153], v[190:193], v[6:9]
	v_mfma_f32_16x16x32_bf16 v[2:5], v[158:161], v[190:193], v[2:5]
	s_barrier
	s_setprio 0
	s_branch .Lkmid_3
.LBB0_2239:
	s_add_i32 s73, s8, 2
	s_add_u32 s0, s44, 0xfff00080
	s_addc_u32 s1, s45, -1
	s_add_i32 s77, 0, 0x10000
	s_cmp_eq_u32 s70, s8
	s_cselect_b32 s67, s51, s1
	s_cselect_b32 s66, s53, s0
	s_cselect_b32 s9, s49, s72
	s_cselect_b32 s8, s69, s71
	s_add_i32 s78, 0, 0x14000
	s_add_i32 m0, s3, 0xc000
	s_nop 0
	global_load_lds_dwordx4 v210, s[44:45]
	s_add_i32 m0, s3, 0xe000
	s_nop 0
	global_load_lds_dwordx4 v208, s[44:45]
	ds_read_b128 v[130:133], v250
	ds_read_b128 v[134:137], v250 offset:1024
	ds_read_b128 v[138:141], v250 offset:2048
	ds_read_b128 v[142:145], v250 offset:3072
	ds_read_b128 v[146:149], v250 offset:16384
	ds_read_b128 v[150:153], v250 offset:17408
	ds_read_b128 v[154:157], v250 offset:18432
	ds_read_b128 v[158:161], v250 offset:19456
	ds_read_b128 v[162:165], v246
	ds_read_b128 v[166:169], v246 offset:1024
	ds_read_b128 v[170:173], v246 offset:2048
	ds_read_b128 v[174:177], v246 offset:3072
	ds_read_b128 v[178:181], v246 offset:4096
	ds_read_b128 v[182:185], v246 offset:5120
	ds_read_b128 v[186:189], v246 offset:6144
	ds_read_b128 v[190:193], v246 offset:7168
	s_waitcnt vmcnt(8)
	s_waitcnt lgkmcnt(0)
	s_setprio 1
	s_barrier
	v_mfma_f32_16x16x32_bf16 v[126:129], v[130:133], v[162:165], v[126:129]
	v_mfma_f32_16x16x32_bf16 v[122:125], v[138:141], v[162:165], v[122:125]
	v_mfma_f32_16x16x32_bf16 v[110:113], v[130:133], v[170:173], v[110:113]
	v_mfma_f32_16x16x32_bf16 v[106:109], v[138:141], v[170:173], v[106:109]
	v_mfma_f32_16x16x32_bf16 v[94:97], v[130:133], v[178:181], v[94:97]
	v_mfma_f32_16x16x32_bf16 v[90:93], v[138:141], v[178:181], v[90:93]
	v_mfma_f32_16x16x32_bf16 v[78:81], v[130:133], v[186:189], v[78:81]
	v_mfma_f32_16x16x32_bf16 v[74:77], v[138:141], v[186:189], v[74:77]
	v_mfma_f32_16x16x32_bf16 v[126:129], v[134:137], v[166:169], v[126:129]
	v_mfma_f32_16x16x32_bf16 v[122:125], v[142:145], v[166:169], v[122:125]
	v_mfma_f32_16x16x32_bf16 v[110:113], v[134:137], v[174:177], v[110:113]
	v_mfma_f32_16x16x32_bf16 v[106:109], v[142:145], v[174:177], v[106:109]
	v_mfma_f32_16x16x32_bf16 v[94:97], v[134:137], v[182:185], v[94:97]
	v_mfma_f32_16x16x32_bf16 v[90:93], v[142:145], v[182:185], v[90:93]
	v_mfma_f32_16x16x32_bf16 v[78:81], v[134:137], v[190:193], v[78:81]
	v_mfma_f32_16x16x32_bf16 v[74:77], v[142:145], v[190:193], v[74:77]
	v_mfma_f32_16x16x32_bf16 v[118:121], v[146:149], v[162:165], v[118:121]
	v_mfma_f32_16x16x32_bf16 v[114:117], v[154:157], v[162:165], v[114:117]
	v_mfma_f32_16x16x32_bf16 v[102:105], v[146:149], v[170:173], v[102:105]
	v_mfma_f32_16x16x32_bf16 v[98:101], v[154:157], v[170:173], v[98:101]
	v_mfma_f32_16x16x32_bf16 v[86:89], v[146:149], v[178:181], v[86:89]
	v_mfma_f32_16x16x32_bf16 v[82:85], v[154:157], v[178:181], v[82:85]
	v_mfma_f32_16x16x32_bf16 v[70:73], v[146:149], v[186:189], v[70:73]
	v_mfma_f32_16x16x32_bf16 v[66:69], v[154:157], v[186:189], v[66:69]
	v_mfma_f32_16x16x32_bf16 v[118:121], v[150:153], v[166:169], v[118:121]
	v_mfma_f32_16x16x32_bf16 v[114:117], v[158:161], v[166:169], v[114:117]
	v_mfma_f32_16x16x32_bf16 v[102:105], v[150:153], v[174:177], v[102:105]
	v_mfma_f32_16x16x32_bf16 v[98:101], v[158:161], v[174:177], v[98:101]
	v_mfma_f32_16x16x32_bf16 v[86:89], v[150:153], v[182:185], v[86:89]
	v_mfma_f32_16x16x32_bf16 v[82:85], v[158:161], v[182:185], v[82:85]
	v_mfma_f32_16x16x32_bf16 v[70:73], v[150:153], v[190:193], v[70:73]
	v_mfma_f32_16x16x32_bf16 v[66:69], v[158:161], v[190:193], v[66:69]
	s_barrier
	s_setprio 0
	s_add_i32 s0, s77, s2
	s_add_u32 s98, s8, s16
	s_addc_u32 s99, s9, s17
	s_mov_b32 m0, s0
	s_nop 0
	global_load_lds_dwordx4 v196, s[8:9]
	s_add_i32 m0, s0, 0x2000
	s_add_u32 s0, s8, 0x100000
	s_addc_u32 s1, s9, 0
	s_add_i32 s77, s78, s2
	global_load_lds_dwordx4 v202, s[8:9]
	s_mov_b32 m0, s77
	v_lshl_add_u64 v[216:217], s[66:67], 0, v[204:205]
	global_load_lds_dwordx4 v196, s[0:1]
	s_add_i32 m0, s77, 0x2000
	s_nop 0
	global_load_lds_dwordx4 v202, s[0:1]
	v_lshl_add_u64 v[214:215], s[66:67], 0, v[206:207]
	s_mov_b32 m0, s3
	s_nop 0
	global_load_lds_dwordx4 v206, s[66:67]
	s_mov_b32 m0, s10
	s_nop 0
	global_load_lds_dwordx4 v204, s[66:67]
	ds_read_b128 v[162:165], v246 offset:16384
	ds_read_b128 v[166:169], v246 offset:17408
	ds_read_b128 v[170:173], v246 offset:18432
	ds_read_b128 v[174:177], v246 offset:19456
	ds_read_b128 v[178:181], v246 offset:20480
	ds_read_b128 v[182:185], v246 offset:21504
	ds_read_b128 v[186:189], v246 offset:22528
	ds_read_b128 v[190:193], v246 offset:23552
	s_waitcnt vmcnt(8)
	s_waitcnt lgkmcnt(0)
	s_setprio 1
	s_barrier
	v_mfma_f32_16x16x32_bf16 v[62:65], v[130:133], v[162:165], v[62:65]
	v_mfma_f32_16x16x32_bf16 v[58:61], v[138:141], v[162:165], v[58:61]
	v_mfma_f32_16x16x32_bf16 v[46:49], v[130:133], v[170:173], v[46:49]
	v_mfma_f32_16x16x32_bf16 v[42:45], v[138:141], v[170:173], v[42:45]
	v_mfma_f32_16x16x32_bf16 v[30:33], v[130:133], v[178:181], v[30:33]
	v_mfma_f32_16x16x32_bf16 v[26:29], v[138:141], v[178:181], v[26:29]
	v_mfma_f32_16x16x32_bf16 v[14:17], v[130:133], v[186:189], v[14:17]
	v_mfma_f32_16x16x32_bf16 v[10:13], v[138:141], v[186:189], v[10:13]
	v_mfma_f32_16x16x32_bf16 v[62:65], v[134:137], v[166:169], v[62:65]
	v_mfma_f32_16x16x32_bf16 v[58:61], v[142:145], v[166:169], v[58:61]
	v_mfma_f32_16x16x32_bf16 v[46:49], v[134:137], v[174:177], v[46:49]
	v_mfma_f32_16x16x32_bf16 v[42:45], v[142:145], v[174:177], v[42:45]
	v_mfma_f32_16x16x32_bf16 v[30:33], v[134:137], v[182:185], v[30:33]
	v_mfma_f32_16x16x32_bf16 v[26:29], v[142:145], v[182:185], v[26:29]
	v_mfma_f32_16x16x32_bf16 v[14:17], v[134:137], v[190:193], v[14:17]
	v_mfma_f32_16x16x32_bf16 v[10:13], v[142:145], v[190:193], v[10:13]
	v_mfma_f32_16x16x32_bf16 v[54:57], v[146:149], v[162:165], v[54:57]
	v_mfma_f32_16x16x32_bf16 v[50:53], v[154:157], v[162:165], v[50:53]
	v_mfma_f32_16x16x32_bf16 v[38:41], v[146:149], v[170:173], v[38:41]
	v_mfma_f32_16x16x32_bf16 v[34:37], v[154:157], v[170:173], v[34:37]
	v_mfma_f32_16x16x32_bf16 v[22:25], v[146:149], v[178:181], v[22:25]
	v_mfma_f32_16x16x32_bf16 v[18:21], v[154:157], v[178:181], v[18:21]
	v_mfma_f32_16x16x32_bf16 v[6:9], v[146:149], v[186:189], v[6:9]
	v_mfma_f32_16x16x32_bf16 v[2:5], v[154:157], v[186:189], v[2:5]
	v_mfma_f32_16x16x32_bf16 v[54:57], v[150:153], v[166:169], v[54:57]
	v_mfma_f32_16x16x32_bf16 v[50:53], v[158:161], v[166:169], v[50:53]
	v_mfma_f32_16x16x32_bf16 v[38:41], v[150:153], v[174:177], v[38:41]
	v_mfma_f32_16x16x32_bf16 v[34:37], v[158:161], v[174:177], v[34:37]
	v_mfma_f32_16x16x32_bf16 v[22:25], v[150:153], v[182:185], v[22:25]
	v_mfma_f32_16x16x32_bf16 v[18:21], v[158:161], v[182:185], v[18:21]
	v_mfma_f32_16x16x32_bf16 v[6:9], v[150:153], v[190:193], v[6:9]
	v_mfma_f32_16x16x32_bf16 v[2:5], v[158:161], v[190:193], v[2:5]
	s_barrier
	s_setprio 0
.Lkmid_3:
	s_add_i32 s77, 0, 0x18000
	s_add_i32 s78, 0, 0x1c000
	s_add_u32 s0, s66, 0x100000
	s_addc_u32 s1, s67, 0
	s_mov_b32 m0, s11
	s_nop 0
	global_load_lds_dwordx4 v206, s[0:1]
	s_mov_b32 m0, s26
	s_nop 0
	global_load_lds_dwordx4 v204, s[0:1]
	ds_read_b128 v[130:133], v250 offset:32768
	ds_read_b128 v[134:137], v250 offset:33792
	ds_read_b128 v[138:141], v250 offset:34816
	ds_read_b128 v[142:145], v250 offset:35840
	ds_read_b128 v[146:149], v250 offset:49152
	ds_read_b128 v[150:153], v250 offset:50176
	ds_read_b128 v[154:157], v250 offset:51200
	ds_read_b128 v[158:161], v250 offset:52224
	ds_read_b128 v[162:165], v246 offset:32768
	ds_read_b128 v[166:169], v246 offset:33792
	ds_read_b128 v[170:173], v246 offset:34816
	ds_read_b128 v[174:177], v246 offset:35840
	ds_read_b128 v[178:181], v246 offset:36864
	ds_read_b128 v[182:185], v246 offset:37888
	ds_read_b128 v[186:189], v246 offset:38912
	ds_read_b128 v[190:193], v246 offset:39936
	s_waitcnt vmcnt(8)
	s_waitcnt lgkmcnt(0)
	s_setprio 1
	s_barrier
	v_mfma_f32_16x16x32_bf16 v[126:129], v[130:133], v[162:165], v[126:129]
	v_mfma_f32_16x16x32_bf16 v[122:125], v[138:141], v[162:165], v[122:125]
	v_mfma_f32_16x16x32_bf16 v[110:113], v[130:133], v[170:173], v[110:113]
	v_mfma_f32_16x16x32_bf16 v[106:109], v[138:141], v[170:173], v[106:109]
	v_mfma_f32_16x16x32_bf16 v[94:97], v[130:133], v[178:181], v[94:97]
	v_mfma_f32_16x16x32_bf16 v[90:93], v[138:141], v[178:181], v[90:93]
	v_mfma_f32_16x16x32_bf16 v[78:81], v[130:133], v[186:189], v[78:81]
	v_mfma_f32_16x16x32_bf16 v[74:77], v[138:141], v[186:189], v[74:77]
	v_mfma_f32_16x16x32_bf16 v[126:129], v[134:137], v[166:169], v[126:129]
	v_mfma_f32_16x16x32_bf16 v[122:125], v[142:145], v[166:169], v[122:125]
	v_mfma_f32_16x16x32_bf16 v[110:113], v[134:137], v[174:177], v[110:113]
	v_mfma_f32_16x16x32_bf16 v[106:109], v[142:145], v[174:177], v[106:109]
	v_mfma_f32_16x16x32_bf16 v[94:97], v[134:137], v[182:185], v[94:97]
	v_mfma_f32_16x16x32_bf16 v[90:93], v[142:145], v[182:185], v[90:93]
	v_mfma_f32_16x16x32_bf16 v[78:81], v[134:137], v[190:193], v[78:81]
	v_mfma_f32_16x16x32_bf16 v[74:77], v[142:145], v[190:193], v[74:77]
	v_mfma_f32_16x16x32_bf16 v[118:121], v[146:149], v[162:165], v[118:121]
	v_mfma_f32_16x16x32_bf16 v[114:117], v[154:157], v[162:165], v[114:117]
	v_mfma_f32_16x16x32_bf16 v[102:105], v[146:149], v[170:173], v[102:105]
	v_mfma_f32_16x16x32_bf16 v[98:101], v[154:157], v[170:173], v[98:101]
	v_mfma_f32_16x16x32_bf16 v[86:89], v[146:149], v[178:181], v[86:89]
	v_mfma_f32_16x16x32_bf16 v[82:85], v[154:157], v[178:181], v[82:85]
	v_mfma_f32_16x16x32_bf16 v[70:73], v[146:149], v[186:189], v[70:73]
	v_mfma_f32_16x16x32_bf16 v[66:69], v[154:157], v[186:189], v[66:69]
	v_mfma_f32_16x16x32_bf16 v[118:121], v[150:153], v[166:169], v[118:121]
	v_mfma_f32_16x16x32_bf16 v[114:117], v[158:161], v[166:169], v[114:117]
	v_mfma_f32_16x16x32_bf16 v[102:105], v[150:153], v[174:177], v[102:105]
	v_mfma_f32_16x16x32_bf16 v[98:101], v[158:161], v[174:177], v[98:101]
	v_mfma_f32_16x16x32_bf16 v[86:89], v[150:153], v[182:185], v[86:89]
	v_mfma_f32_16x16x32_bf16 v[82:85], v[158:161], v[182:185], v[82:85]
	v_mfma_f32_16x16x32_bf16 v[70:73], v[150:153], v[190:193], v[70:73]
	v_mfma_f32_16x16x32_bf16 v[66:69], v[158:161], v[190:193], v[66:69]
	s_barrier
	s_setprio 0
	s_add_i32 s0, s77, s2
	s_mov_b32 m0, s0
	s_nop 0
	global_load_lds_dwordx4 v196, s[98:99]
	s_add_i32 m0, s0, 0x2000
	s_add_u32 s0, s8, 0x100080
	s_addc_u32 s1, s9, 0
	s_add_i32 s8, s78, s2
	global_load_lds_dwordx4 v202, s[98:99]
	s_mov_b32 m0, s8
	s_nop 0
	global_load_lds_dwordx4 v196, s[0:1]
	s_add_i32 m0, s8, 0x2000
	s_nop 0
	global_load_lds_dwordx4 v202, s[0:1]
	v_lshl_add_u64 v[194:195], v[214:215], 0, s[16:17]
	s_mov_b32 m0, s27
	s_nop 0
	global_load_lds_dwordx4 v[194:195], off
	v_lshl_add_u64 v[194:195], v[216:217], 0, s[16:17]
	s_mov_b32 m0, s28
	s_nop 0
	global_load_lds_dwordx4 v[194:195], off
	ds_read_b128 v[162:165], v246 offset:49152
	ds_read_b128 v[166:169], v246 offset:50176
	ds_read_b128 v[170:173], v246 offset:51200
	ds_read_b128 v[174:177], v246 offset:52224
	ds_read_b128 v[178:181], v246 offset:53248
	ds_read_b128 v[182:185], v246 offset:54272
	ds_read_b128 v[186:189], v246 offset:55296
	ds_read_b128 v[190:193], v246 offset:56320
	s_waitcnt vmcnt(8)
	s_waitcnt lgkmcnt(0)
	s_setprio 1
	s_barrier
	v_mfma_f32_16x16x32_bf16 v[62:65], v[130:133], v[162:165], v[62:65]
	v_mfma_f32_16x16x32_bf16 v[58:61], v[138:141], v[162:165], v[58:61]
	v_mfma_f32_16x16x32_bf16 v[46:49], v[130:133], v[170:173], v[46:49]
	v_mfma_f32_16x16x32_bf16 v[42:45], v[138:141], v[170:173], v[42:45]
	v_mfma_f32_16x16x32_bf16 v[30:33], v[130:133], v[178:181], v[30:33]
	v_mfma_f32_16x16x32_bf16 v[26:29], v[138:141], v[178:181], v[26:29]
	v_mfma_f32_16x16x32_bf16 v[14:17], v[130:133], v[186:189], v[14:17]
	v_mfma_f32_16x16x32_bf16 v[10:13], v[138:141], v[186:189], v[10:13]
	v_mfma_f32_16x16x32_bf16 v[62:65], v[134:137], v[166:169], v[62:65]
	v_mfma_f32_16x16x32_bf16 v[58:61], v[142:145], v[166:169], v[58:61]
	v_mfma_f32_16x16x32_bf16 v[46:49], v[134:137], v[174:177], v[46:49]
	v_mfma_f32_16x16x32_bf16 v[42:45], v[142:145], v[174:177], v[42:45]
	v_mfma_f32_16x16x32_bf16 v[30:33], v[134:137], v[182:185], v[30:33]
	v_mfma_f32_16x16x32_bf16 v[26:29], v[142:145], v[182:185], v[26:29]
	v_mfma_f32_16x16x32_bf16 v[14:17], v[134:137], v[190:193], v[14:17]
	v_mfma_f32_16x16x32_bf16 v[10:13], v[142:145], v[190:193], v[10:13]
	v_mfma_f32_16x16x32_bf16 v[54:57], v[146:149], v[162:165], v[54:57]
	v_mfma_f32_16x16x32_bf16 v[50:53], v[154:157], v[162:165], v[50:53]
	v_mfma_f32_16x16x32_bf16 v[38:41], v[146:149], v[170:173], v[38:41]
	v_mfma_f32_16x16x32_bf16 v[34:37], v[154:157], v[170:173], v[34:37]
	v_mfma_f32_16x16x32_bf16 v[22:25], v[146:149], v[178:181], v[22:25]
	v_mfma_f32_16x16x32_bf16 v[18:21], v[154:157], v[178:181], v[18:21]
	v_mfma_f32_16x16x32_bf16 v[6:9], v[146:149], v[186:189], v[6:9]
	v_mfma_f32_16x16x32_bf16 v[2:5], v[154:157], v[186:189], v[2:5]
	v_mfma_f32_16x16x32_bf16 v[54:57], v[150:153], v[166:169], v[54:57]
	v_mfma_f32_16x16x32_bf16 v[50:53], v[158:161], v[166:169], v[50:53]
	v_mfma_f32_16x16x32_bf16 v[38:41], v[150:153], v[174:177], v[38:41]
	v_mfma_f32_16x16x32_bf16 v[34:37], v[158:161], v[174:177], v[34:37]
	v_mfma_f32_16x16x32_bf16 v[22:25], v[150:153], v[182:185], v[22:25]
	v_mfma_f32_16x16x32_bf16 v[18:21], v[158:161], v[182:185], v[18:21]
	v_mfma_f32_16x16x32_bf16 v[6:9], v[150:153], v[190:193], v[6:9]
	v_mfma_f32_16x16x32_bf16 v[2:5], v[158:161], v[190:193], v[2:5]
	s_barrier
	s_setprio 0
	s_add_u32 s71, s71, 0x100
	s_addc_u32 s72, s72, 0
	s_add_u32 s44, s44, 0x100
	s_addc_u32 s45, s45, 0
	s_cmp_ge_i32 s73, s35
	s_mov_b32 s8, s73
	s_cbranch_scc0 .LBB0_2239
	s_and_b64 vcc, exec, s[46:47]
	s_cbranch_vccz .LBB0_2242
	s_barrier

.Ldefbar_skip_4:
	v_add_u32_e32 v250, 0x10000, v188
	s_add_i32 s77, s8, 2
	s_add_u32 s0, s62, 0xfff80080
	s_addc_u32 s1, s63, -1
	s_add_i32 s78, 0, 0x10000
	s_cmp_eq_u32 s71, s8
	s_cselect_b32 s65, s41, s1
	s_cselect_b32 s64, s45, s0
	s_cselect_b32 s9, s43, s73
	s_cselect_b32 s8, s70, s72
	s_add_i32 s79, 0, 0x14000
	s_add_i32 m0, s27, 0xc000
	s_nop 0
	global_load_lds_dwordx4 v178, s[62:63]
	s_add_i32 m0, s27, 0xe000
	s_nop 0
	global_load_lds_dwordx4 v176, s[62:63]
	ds_read_b128 v[130:133], v250
	ds_read_b128 v[134:137], v250 offset:1024
	ds_read_b128 v[138:141], v250 offset:2048
	ds_read_b128 v[142:145], v250 offset:3072
	ds_read_b128 v[146:149], v250 offset:16384
	ds_read_b128 v[150:153], v250 offset:17408
	ds_read_b128 v[154:157], v250 offset:18432
	ds_read_b128 v[158:161], v250 offset:19456
	ds_read_b128 v[162:165], v189
	ds_read_b128 v[180:183], v189 offset:1024
	ds_read_b128 v[184:187], v189 offset:2048
	ds_read_b128 v[190:193], v189 offset:3072
	ds_read_b128 v[202:205], v189 offset:4096
	ds_read_b128 v[206:209], v189 offset:5120
	ds_read_b128 v[210:213], v189 offset:6144
	ds_read_b128 v[214:217], v189 offset:7168
	s_waitcnt vmcnt(8)
	s_waitcnt lgkmcnt(0)
	s_setprio 1
	s_barrier
	v_mfma_f32_16x16x32_bf16 v[126:129], v[130:133], v[162:165], 0
	v_mfma_f32_16x16x32_bf16 v[122:125], v[138:141], v[162:165], 0
	v_mfma_f32_16x16x32_bf16 v[110:113], v[130:133], v[184:187], 0
	v_mfma_f32_16x16x32_bf16 v[106:109], v[138:141], v[184:187], 0
	v_mfma_f32_16x16x32_bf16 v[98:101], v[130:133], v[202:205], 0
	v_mfma_f32_16x16x32_bf16 v[90:93], v[138:141], v[202:205], 0
	v_mfma_f32_16x16x32_bf16 v[82:85], v[130:133], v[210:213], 0
	v_mfma_f32_16x16x32_bf16 v[74:77], v[138:141], v[210:213], 0
	v_mfma_f32_16x16x32_bf16 v[126:129], v[134:137], v[180:183], v[126:129]
	v_mfma_f32_16x16x32_bf16 v[122:125], v[142:145], v[180:183], v[122:125]
	v_mfma_f32_16x16x32_bf16 v[110:113], v[134:137], v[190:193], v[110:113]
	v_mfma_f32_16x16x32_bf16 v[106:109], v[142:145], v[190:193], v[106:109]
	v_mfma_f32_16x16x32_bf16 v[98:101], v[134:137], v[206:209], v[98:101]
	v_mfma_f32_16x16x32_bf16 v[90:93], v[142:145], v[206:209], v[90:93]
	v_mfma_f32_16x16x32_bf16 v[82:85], v[134:137], v[214:217], v[82:85]
	v_mfma_f32_16x16x32_bf16 v[74:77], v[142:145], v[214:217], v[74:77]
	v_mfma_f32_16x16x32_bf16 v[118:121], v[146:149], v[162:165], 0
	v_mfma_f32_16x16x32_bf16 v[114:117], v[154:157], v[162:165], 0
	v_mfma_f32_16x16x32_bf16 v[102:105], v[146:149], v[184:187], 0
	v_mfma_f32_16x16x32_bf16 v[94:97], v[154:157], v[184:187], 0
	v_mfma_f32_16x16x32_bf16 v[86:89], v[146:149], v[202:205], 0
	v_mfma_f32_16x16x32_bf16 v[78:81], v[154:157], v[202:205], 0
	v_mfma_f32_16x16x32_bf16 v[70:73], v[146:149], v[210:213], 0
	v_mfma_f32_16x16x32_bf16 v[66:69], v[154:157], v[210:213], 0
	v_mfma_f32_16x16x32_bf16 v[118:121], v[150:153], v[180:183], v[118:121]
	v_mfma_f32_16x16x32_bf16 v[114:117], v[158:161], v[180:183], v[114:117]
	v_mfma_f32_16x16x32_bf16 v[102:105], v[150:153], v[190:193], v[102:105]
	v_mfma_f32_16x16x32_bf16 v[94:97], v[158:161], v[190:193], v[94:97]
	v_mfma_f32_16x16x32_bf16 v[86:89], v[150:153], v[206:209], v[86:89]
	v_mfma_f32_16x16x32_bf16 v[78:81], v[158:161], v[206:209], v[78:81]
	v_mfma_f32_16x16x32_bf16 v[70:73], v[150:153], v[214:217], v[70:73]
	v_mfma_f32_16x16x32_bf16 v[66:69], v[158:161], v[214:217], v[66:69]
	s_barrier
	s_setprio 0
	s_add_i32 s0, s78, s26
	s_add_u32 s98, s8, s16
	s_addc_u32 s99, s9, s17
	s_mov_b32 m0, s0
	s_nop 0
	global_load_lds_dwordx4 v196, s[8:9]
	s_add_i32 m0, s0, 0x2000
	s_add_u32 s0, s8, 0x80000
	s_addc_u32 s1, s9, 0
	s_add_i32 s78, s79, s26
	global_load_lds_dwordx4 v170, s[8:9]
	s_mov_b32 m0, s78
	v_lshl_add_u64 v[222:223], s[64:65], 0, v[168:169]
	global_load_lds_dwordx4 v196, s[0:1]
	s_add_i32 m0, s78, 0x2000
	s_nop 0
	global_load_lds_dwordx4 v170, s[0:1]
	v_lshl_add_u64 v[220:221], s[64:65], 0, v[166:167]
	s_mov_b32 m0, s27
	s_nop 0
	global_load_lds_dwordx4 v166, s[64:65]
	s_mov_b32 m0, s28
	s_nop 0
	global_load_lds_dwordx4 v168, s[64:65]
	ds_read_b128 v[162:165], v189 offset:16384
	ds_read_b128 v[180:183], v189 offset:17408
	ds_read_b128 v[184:187], v189 offset:18432
	ds_read_b128 v[190:193], v189 offset:19456
	ds_read_b128 v[202:205], v189 offset:20480
	ds_read_b128 v[206:209], v189 offset:21504
	ds_read_b128 v[210:213], v189 offset:22528
	ds_read_b128 v[214:217], v189 offset:23552
	s_waitcnt vmcnt(8)
	s_waitcnt lgkmcnt(0)
	s_setprio 1
	s_barrier
	v_mfma_f32_16x16x32_bf16 v[62:65], v[130:133], v[162:165], 0
	v_mfma_f32_16x16x32_bf16 v[58:61], v[138:141], v[162:165], 0
	v_mfma_f32_16x16x32_bf16 v[50:53], v[130:133], v[184:187], 0
	v_mfma_f32_16x16x32_bf16 v[42:45], v[138:141], v[184:187], 0
	v_mfma_f32_16x16x32_bf16 v[34:37], v[130:133], v[202:205], 0
	v_mfma_f32_16x16x32_bf16 v[26:29], v[138:141], v[202:205], 0
	v_mfma_f32_16x16x32_bf16 v[18:21], v[130:133], v[210:213], 0
	v_mfma_f32_16x16x32_bf16 v[10:13], v[138:141], v[210:213], 0
	v_mfma_f32_16x16x32_bf16 v[62:65], v[134:137], v[180:183], v[62:65]
	v_mfma_f32_16x16x32_bf16 v[58:61], v[142:145], v[180:183], v[58:61]
	v_mfma_f32_16x16x32_bf16 v[50:53], v[134:137], v[190:193], v[50:53]
	v_mfma_f32_16x16x32_bf16 v[42:45], v[142:145], v[190:193], v[42:45]
	v_mfma_f32_16x16x32_bf16 v[34:37], v[134:137], v[206:209], v[34:37]
	v_mfma_f32_16x16x32_bf16 v[26:29], v[142:145], v[206:209], v[26:29]
	v_mfma_f32_16x16x32_bf16 v[18:21], v[134:137], v[214:217], v[18:21]
	v_mfma_f32_16x16x32_bf16 v[10:13], v[142:145], v[214:217], v[10:13]
	v_mfma_f32_16x16x32_bf16 v[54:57], v[146:149], v[162:165], 0
	v_mfma_f32_16x16x32_bf16 v[46:49], v[154:157], v[162:165], 0
	v_mfma_f32_16x16x32_bf16 v[38:41], v[146:149], v[184:187], 0
	v_mfma_f32_16x16x32_bf16 v[30:33], v[154:157], v[184:187], 0
	v_mfma_f32_16x16x32_bf16 v[22:25], v[146:149], v[202:205], 0
	v_mfma_f32_16x16x32_bf16 v[14:17], v[154:157], v[202:205], 0
	v_mfma_f32_16x16x32_bf16 v[6:9], v[146:149], v[210:213], 0
	v_mfma_f32_16x16x32_bf16 v[2:5], v[154:157], v[210:213], 0
	v_mfma_f32_16x16x32_bf16 v[54:57], v[150:153], v[180:183], v[54:57]
	v_mfma_f32_16x16x32_bf16 v[46:49], v[158:161], v[180:183], v[46:49]
	v_mfma_f32_16x16x32_bf16 v[38:41], v[150:153], v[190:193], v[38:41]
	v_mfma_f32_16x16x32_bf16 v[30:33], v[158:161], v[190:193], v[30:33]
	v_mfma_f32_16x16x32_bf16 v[22:25], v[150:153], v[206:209], v[22:25]
	v_mfma_f32_16x16x32_bf16 v[14:17], v[158:161], v[206:209], v[14:17]
	v_mfma_f32_16x16x32_bf16 v[6:9], v[150:153], v[214:217], v[6:9]
	v_mfma_f32_16x16x32_bf16 v[2:5], v[158:161], v[214:217], v[2:5]
	s_barrier
	s_setprio 0
	s_branch .Lkmid_4
.LBB0_2357:
	s_add_i32 s77, s8, 2
	s_add_u32 s0, s62, 0xfff80080
	s_addc_u32 s1, s63, -1
	s_add_i32 s78, 0, 0x10000
	s_cmp_eq_u32 s71, s8
	s_cselect_b32 s65, s41, s1
	s_cselect_b32 s64, s45, s0
	s_cselect_b32 s9, s43, s73
	s_cselect_b32 s8, s70, s72
	s_add_i32 s79, 0, 0x14000
	s_add_i32 m0, s27, 0xc000
	s_nop 0
	global_load_lds_dwordx4 v178, s[62:63]
	s_add_i32 m0, s27, 0xe000
	s_nop 0
	global_load_lds_dwordx4 v176, s[62:63]
	ds_read_b128 v[130:133], v250
	ds_read_b128 v[134:137], v250 offset:1024
	ds_read_b128 v[138:141], v250 offset:2048
	ds_read_b128 v[142:145], v250 offset:3072
	ds_read_b128 v[146:149], v250 offset:16384
	ds_read_b128 v[150:153], v250 offset:17408
	ds_read_b128 v[154:157], v250 offset:18432
	ds_read_b128 v[158:161], v250 offset:19456
	ds_read_b128 v[162:165], v189
	ds_read_b128 v[180:183], v189 offset:1024
	ds_read_b128 v[184:187], v189 offset:2048
	ds_read_b128 v[190:193], v189 offset:3072
	ds_read_b128 v[202:205], v189 offset:4096
	ds_read_b128 v[206:209], v189 offset:5120
	ds_read_b128 v[210:213], v189 offset:6144
	ds_read_b128 v[214:217], v189 offset:7168
	s_waitcnt vmcnt(8)
	s_waitcnt lgkmcnt(0)
	s_setprio 1
	s_barrier
	v_mfma_f32_16x16x32_bf16 v[126:129], v[130:133], v[162:165], v[126:129]
	v_mfma_f32_16x16x32_bf16 v[122:125], v[138:141], v[162:165], v[122:125]
	v_mfma_f32_16x16x32_bf16 v[110:113], v[130:133], v[184:187], v[110:113]
	v_mfma_f32_16x16x32_bf16 v[106:109], v[138:141], v[184:187], v[106:109]
	v_mfma_f32_16x16x32_bf16 v[98:101], v[130:133], v[202:205], v[98:101]
	v_mfma_f32_16x16x32_bf16 v[90:93], v[138:141], v[202:205], v[90:93]
	v_mfma_f32_16x16x32_bf16 v[82:85], v[130:133], v[210:213], v[82:85]
	v_mfma_f32_16x16x32_bf16 v[74:77], v[138:141], v[210:213], v[74:77]
	v_mfma_f32_16x16x32_bf16 v[126:129], v[134:137], v[180:183], v[126:129]
	v_mfma_f32_16x16x32_bf16 v[122:125], v[142:145], v[180:183], v[122:125]
	v_mfma_f32_16x16x32_bf16 v[110:113], v[134:137], v[190:193], v[110:113]
	v_mfma_f32_16x16x32_bf16 v[106:109], v[142:145], v[190:193], v[106:109]
	v_mfma_f32_16x16x32_bf16 v[98:101], v[134:137], v[206:209], v[98:101]
	v_mfma_f32_16x16x32_bf16 v[90:93], v[142:145], v[206:209], v[90:93]
	v_mfma_f32_16x16x32_bf16 v[82:85], v[134:137], v[214:217], v[82:85]
	v_mfma_f32_16x16x32_bf16 v[74:77], v[142:145], v[214:217], v[74:77]
	v_mfma_f32_16x16x32_bf16 v[118:121], v[146:149], v[162:165], v[118:121]
	v_mfma_f32_16x16x32_bf16 v[114:117], v[154:157], v[162:165], v[114:117]
	v_mfma_f32_16x16x32_bf16 v[102:105], v[146:149], v[184:187], v[102:105]
	v_mfma_f32_16x16x32_bf16 v[94:97], v[154:157], v[184:187], v[94:97]
	v_mfma_f32_16x16x32_bf16 v[86:89], v[146:149], v[202:205], v[86:89]
	v_mfma_f32_16x16x32_bf16 v[78:81], v[154:157], v[202:205], v[78:81]
	v_mfma_f32_16x16x32_bf16 v[70:73], v[146:149], v[210:213], v[70:73]
	v_mfma_f32_16x16x32_bf16 v[66:69], v[154:157], v[210:213], v[66:69]
	v_mfma_f32_16x16x32_bf16 v[118:121], v[150:153], v[180:183], v[118:121]
	v_mfma_f32_16x16x32_bf16 v[114:117], v[158:161], v[180:183], v[114:117]
	v_mfma_f32_16x16x32_bf16 v[102:105], v[150:153], v[190:193], v[102:105]
	v_mfma_f32_16x16x32_bf16 v[94:97], v[158:161], v[190:193], v[94:97]
	v_mfma_f32_16x16x32_bf16 v[86:89], v[150:153], v[206:209], v[86:89]
	v_mfma_f32_16x16x32_bf16 v[78:81], v[158:161], v[206:209], v[78:81]
	v_mfma_f32_16x16x32_bf16 v[70:73], v[150:153], v[214:217], v[70:73]
	v_mfma_f32_16x16x32_bf16 v[66:69], v[158:161], v[214:217], v[66:69]
	s_barrier
	s_setprio 0
	s_add_i32 s0, s78, s26
	s_add_u32 s98, s8, s16
	s_addc_u32 s99, s9, s17
	s_mov_b32 m0, s0
	s_nop 0
	global_load_lds_dwordx4 v196, s[8:9]
	s_add_i32 m0, s0, 0x2000
	s_add_u32 s0, s8, 0x80000
	s_addc_u32 s1, s9, 0
	s_add_i32 s78, s79, s26
	global_load_lds_dwordx4 v170, s[8:9]
	s_mov_b32 m0, s78
	v_lshl_add_u64 v[222:223], s[64:65], 0, v[168:169]
	global_load_lds_dwordx4 v196, s[0:1]
	s_add_i32 m0, s78, 0x2000
	s_nop 0
	global_load_lds_dwordx4 v170, s[0:1]
	v_lshl_add_u64 v[220:221], s[64:65], 0, v[166:167]
	s_mov_b32 m0, s27
	s_nop 0
	global_load_lds_dwordx4 v166, s[64:65]
	s_mov_b32 m0, s28
	s_nop 0
	global_load_lds_dwordx4 v168, s[64:65]
	ds_read_b128 v[162:165], v189 offset:16384
	ds_read_b128 v[180:183], v189 offset:17408
	ds_read_b128 v[184:187], v189 offset:18432
	ds_read_b128 v[190:193], v189 offset:19456
	ds_read_b128 v[202:205], v189 offset:20480
	ds_read_b128 v[206:209], v189 offset:21504
	ds_read_b128 v[210:213], v189 offset:22528
	ds_read_b128 v[214:217], v189 offset:23552
	s_waitcnt vmcnt(8)
	s_waitcnt lgkmcnt(0)
	s_setprio 1
	s_barrier
	v_mfma_f32_16x16x32_bf16 v[62:65], v[130:133], v[162:165], v[62:65]
	v_mfma_f32_16x16x32_bf16 v[58:61], v[138:141], v[162:165], v[58:61]
	v_mfma_f32_16x16x32_bf16 v[50:53], v[130:133], v[184:187], v[50:53]
	v_mfma_f32_16x16x32_bf16 v[42:45], v[138:141], v[184:187], v[42:45]
	v_mfma_f32_16x16x32_bf16 v[34:37], v[130:133], v[202:205], v[34:37]
	v_mfma_f32_16x16x32_bf16 v[26:29], v[138:141], v[202:205], v[26:29]
	v_mfma_f32_16x16x32_bf16 v[18:21], v[130:133], v[210:213], v[18:21]
	v_mfma_f32_16x16x32_bf16 v[10:13], v[138:141], v[210:213], v[10:13]
	v_mfma_f32_16x16x32_bf16 v[62:65], v[134:137], v[180:183], v[62:65]
	v_mfma_f32_16x16x32_bf16 v[58:61], v[142:145], v[180:183], v[58:61]
	v_mfma_f32_16x16x32_bf16 v[50:53], v[134:137], v[190:193], v[50:53]
	v_mfma_f32_16x16x32_bf16 v[42:45], v[142:145], v[190:193], v[42:45]
	v_mfma_f32_16x16x32_bf16 v[34:37], v[134:137], v[206:209], v[34:37]
	v_mfma_f32_16x16x32_bf16 v[26:29], v[142:145], v[206:209], v[26:29]
	v_mfma_f32_16x16x32_bf16 v[18:21], v[134:137], v[214:217], v[18:21]
	v_mfma_f32_16x16x32_bf16 v[10:13], v[142:145], v[214:217], v[10:13]
	v_mfma_f32_16x16x32_bf16 v[54:57], v[146:149], v[162:165], v[54:57]
	v_mfma_f32_16x16x32_bf16 v[46:49], v[154:157], v[162:165], v[46:49]
	v_mfma_f32_16x16x32_bf16 v[38:41], v[146:149], v[184:187], v[38:41]
	v_mfma_f32_16x16x32_bf16 v[30:33], v[154:157], v[184:187], v[30:33]
	v_mfma_f32_16x16x32_bf16 v[22:25], v[146:149], v[202:205], v[22:25]
	v_mfma_f32_16x16x32_bf16 v[14:17], v[154:157], v[202:205], v[14:17]
	v_mfma_f32_16x16x32_bf16 v[6:9], v[146:149], v[210:213], v[6:9]
	v_mfma_f32_16x16x32_bf16 v[2:5], v[154:157], v[210:213], v[2:5]
	v_mfma_f32_16x16x32_bf16 v[54:57], v[150:153], v[180:183], v[54:57]
	v_mfma_f32_16x16x32_bf16 v[46:49], v[158:161], v[180:183], v[46:49]
	v_mfma_f32_16x16x32_bf16 v[38:41], v[150:153], v[190:193], v[38:41]
	v_mfma_f32_16x16x32_bf16 v[30:33], v[158:161], v[190:193], v[30:33]
	v_mfma_f32_16x16x32_bf16 v[22:25], v[150:153], v[206:209], v[22:25]
	v_mfma_f32_16x16x32_bf16 v[14:17], v[158:161], v[206:209], v[14:17]
	v_mfma_f32_16x16x32_bf16 v[6:9], v[150:153], v[214:217], v[6:9]
	v_mfma_f32_16x16x32_bf16 v[2:5], v[158:161], v[214:217], v[2:5]
	s_barrier
	s_setprio 0
.Lkmid_4:
	s_add_i32 s78, 0, 0x18000
	s_add_i32 s79, 0, 0x1c000
	s_add_u32 s0, s64, 0x80000
	s_addc_u32 s1, s65, 0
	s_mov_b32 m0, s29
	s_nop 0
	global_load_lds_dwordx4 v166, s[0:1]
	s_mov_b32 m0, s30
	s_nop 0
	global_load_lds_dwordx4 v168, s[0:1]
	ds_read_b128 v[130:133], v250 offset:32768
	ds_read_b128 v[134:137], v250 offset:33792
	ds_read_b128 v[138:141], v250 offset:34816
	ds_read_b128 v[142:145], v250 offset:35840
	ds_read_b128 v[146:149], v250 offset:49152
	ds_read_b128 v[150:153], v250 offset:50176
	ds_read_b128 v[154:157], v250 offset:51200
	ds_read_b128 v[158:161], v250 offset:52224
	ds_read_b128 v[162:165], v189 offset:32768
	ds_read_b128 v[180:183], v189 offset:33792
	ds_read_b128 v[184:187], v189 offset:34816
	ds_read_b128 v[190:193], v189 offset:35840
	ds_read_b128 v[202:205], v189 offset:36864
	ds_read_b128 v[206:209], v189 offset:37888
	ds_read_b128 v[210:213], v189 offset:38912
	ds_read_b128 v[214:217], v189 offset:39936
	s_waitcnt vmcnt(8)
	s_waitcnt lgkmcnt(0)
	s_setprio 1
	s_barrier
	v_mfma_f32_16x16x32_bf16 v[126:129], v[130:133], v[162:165], v[126:129]
	v_mfma_f32_16x16x32_bf16 v[122:125], v[138:141], v[162:165], v[122:125]
	v_mfma_f32_16x16x32_bf16 v[110:113], v[130:133], v[184:187], v[110:113]
	v_mfma_f32_16x16x32_bf16 v[106:109], v[138:141], v[184:187], v[106:109]
	v_mfma_f32_16x16x32_bf16 v[98:101], v[130:133], v[202:205], v[98:101]
	v_mfma_f32_16x16x32_bf16 v[90:93], v[138:141], v[202:205], v[90:93]
	v_mfma_f32_16x16x32_bf16 v[82:85], v[130:133], v[210:213], v[82:85]
	v_mfma_f32_16x16x32_bf16 v[74:77], v[138:141], v[210:213], v[74:77]
	v_mfma_f32_16x16x32_bf16 v[126:129], v[134:137], v[180:183], v[126:129]
	v_mfma_f32_16x16x32_bf16 v[122:125], v[142:145], v[180:183], v[122:125]
	v_mfma_f32_16x16x32_bf16 v[110:113], v[134:137], v[190:193], v[110:113]
	v_mfma_f32_16x16x32_bf16 v[106:109], v[142:145], v[190:193], v[106:109]
	v_mfma_f32_16x16x32_bf16 v[98:101], v[134:137], v[206:209], v[98:101]
	v_mfma_f32_16x16x32_bf16 v[90:93], v[142:145], v[206:209], v[90:93]
	v_mfma_f32_16x16x32_bf16 v[82:85], v[134:137], v[214:217], v[82:85]
	v_mfma_f32_16x16x32_bf16 v[74:77], v[142:145], v[214:217], v[74:77]
	v_mfma_f32_16x16x32_bf16 v[118:121], v[146:149], v[162:165], v[118:121]
	v_mfma_f32_16x16x32_bf16 v[114:117], v[154:157], v[162:165], v[114:117]
	v_mfma_f32_16x16x32_bf16 v[102:105], v[146:149], v[184:187], v[102:105]
	v_mfma_f32_16x16x32_bf16 v[94:97], v[154:157], v[184:187], v[94:97]
	v_mfma_f32_16x16x32_bf16 v[86:89], v[146:149], v[202:205], v[86:89]
	v_mfma_f32_16x16x32_bf16 v[78:81], v[154:157], v[202:205], v[78:81]
	v_mfma_f32_16x16x32_bf16 v[70:73], v[146:149], v[210:213], v[70:73]
	v_mfma_f32_16x16x32_bf16 v[66:69], v[154:157], v[210:213], v[66:69]
	v_mfma_f32_16x16x32_bf16 v[118:121], v[150:153], v[180:183], v[118:121]
	v_mfma_f32_16x16x32_bf16 v[114:117], v[158:161], v[180:183], v[114:117]
	v_mfma_f32_16x16x32_bf16 v[102:105], v[150:153], v[190:193], v[102:105]
	v_mfma_f32_16x16x32_bf16 v[94:97], v[158:161], v[190:193], v[94:97]
	v_mfma_f32_16x16x32_bf16 v[86:89], v[150:153], v[206:209], v[86:89]
	v_mfma_f32_16x16x32_bf16 v[78:81], v[158:161], v[206:209], v[78:81]
	v_mfma_f32_16x16x32_bf16 v[70:73], v[150:153], v[214:217], v[70:73]
	v_mfma_f32_16x16x32_bf16 v[66:69], v[158:161], v[214:217], v[66:69]
	s_barrier
	s_setprio 0
	s_add_i32 s0, s78, s26
	s_mov_b32 m0, s0
	s_nop 0
	global_load_lds_dwordx4 v196, s[98:99]
	s_add_i32 m0, s0, 0x2000
	s_add_u32 s0, s8, 0x80080
	s_addc_u32 s1, s9, 0
	s_add_i32 s8, s79, s26
	global_load_lds_dwordx4 v170, s[98:99]
	s_mov_b32 m0, s8
	s_nop 0
	global_load_lds_dwordx4 v196, s[0:1]
	s_add_i32 m0, s8, 0x2000
	s_nop 0
	global_load_lds_dwordx4 v170, s[0:1]
	v_lshl_add_u64 v[194:195], v[220:221], 0, s[16:17]
	s_mov_b32 m0, s35
	s_nop 0
	global_load_lds_dwordx4 v[194:195], off
	v_lshl_add_u64 v[194:195], v[222:223], 0, s[16:17]
	s_mov_b32 m0, s53
	s_nop 0
	global_load_lds_dwordx4 v[194:195], off
	ds_read_b128 v[162:165], v189 offset:49152
	ds_read_b128 v[180:183], v189 offset:50176
	ds_read_b128 v[184:187], v189 offset:51200
	ds_read_b128 v[190:193], v189 offset:52224
	ds_read_b128 v[202:205], v189 offset:53248
	ds_read_b128 v[206:209], v189 offset:54272
	ds_read_b128 v[210:213], v189 offset:55296
	ds_read_b128 v[214:217], v189 offset:56320
	s_waitcnt vmcnt(8)
	s_waitcnt lgkmcnt(0)
	s_setprio 1
	s_barrier
	v_mfma_f32_16x16x32_bf16 v[62:65], v[130:133], v[162:165], v[62:65]
	v_mfma_f32_16x16x32_bf16 v[58:61], v[138:141], v[162:165], v[58:61]
	v_mfma_f32_16x16x32_bf16 v[50:53], v[130:133], v[184:187], v[50:53]
	v_mfma_f32_16x16x32_bf16 v[42:45], v[138:141], v[184:187], v[42:45]
	v_mfma_f32_16x16x32_bf16 v[34:37], v[130:133], v[202:205], v[34:37]
	v_mfma_f32_16x16x32_bf16 v[26:29], v[138:141], v[202:205], v[26:29]
	v_mfma_f32_16x16x32_bf16 v[18:21], v[130:133], v[210:213], v[18:21]
	v_mfma_f32_16x16x32_bf16 v[10:13], v[138:141], v[210:213], v[10:13]
	v_mfma_f32_16x16x32_bf16 v[62:65], v[134:137], v[180:183], v[62:65]
	v_mfma_f32_16x16x32_bf16 v[58:61], v[142:145], v[180:183], v[58:61]
	v_mfma_f32_16x16x32_bf16 v[50:53], v[134:137], v[190:193], v[50:53]
	v_mfma_f32_16x16x32_bf16 v[42:45], v[142:145], v[190:193], v[42:45]
	v_mfma_f32_16x16x32_bf16 v[34:37], v[134:137], v[206:209], v[34:37]
	v_mfma_f32_16x16x32_bf16 v[26:29], v[142:145], v[206:209], v[26:29]
	v_mfma_f32_16x16x32_bf16 v[18:21], v[134:137], v[214:217], v[18:21]
	v_mfma_f32_16x16x32_bf16 v[10:13], v[142:145], v[214:217], v[10:13]
	v_mfma_f32_16x16x32_bf16 v[54:57], v[146:149], v[162:165], v[54:57]
	v_mfma_f32_16x16x32_bf16 v[46:49], v[154:157], v[162:165], v[46:49]
	v_mfma_f32_16x16x32_bf16 v[38:41], v[146:149], v[184:187], v[38:41]
	v_mfma_f32_16x16x32_bf16 v[30:33], v[154:157], v[184:187], v[30:33]
	v_mfma_f32_16x16x32_bf16 v[22:25], v[146:149], v[202:205], v[22:25]
	v_mfma_f32_16x16x32_bf16 v[14:17], v[154:157], v[202:205], v[14:17]
	v_mfma_f32_16x16x32_bf16 v[6:9], v[146:149], v[210:213], v[6:9]
	v_mfma_f32_16x16x32_bf16 v[2:5], v[154:157], v[210:213], v[2:5]
	v_mfma_f32_16x16x32_bf16 v[54:57], v[150:153], v[180:183], v[54:57]
	v_mfma_f32_16x16x32_bf16 v[46:49], v[158:161], v[180:183], v[46:49]
	v_mfma_f32_16x16x32_bf16 v[38:41], v[150:153], v[190:193], v[38:41]
	v_mfma_f32_16x16x32_bf16 v[30:33], v[158:161], v[190:193], v[30:33]
	v_mfma_f32_16x16x32_bf16 v[22:25], v[150:153], v[206:209], v[22:25]
	v_mfma_f32_16x16x32_bf16 v[14:17], v[158:161], v[206:209], v[14:17]
	v_mfma_f32_16x16x32_bf16 v[6:9], v[150:153], v[214:217], v[6:9]
	v_mfma_f32_16x16x32_bf16 v[2:5], v[158:161], v[214:217], v[2:5]
	s_barrier
	s_setprio 0
	s_add_u32 s72, s72, 0x100
	s_addc_u32 s73, s73, 0
	s_add_u32 s62, s62, 0x100
	s_addc_u32 s63, s63, 0
	s_cmp_ge_i32 s77, s69
	s_mov_b32 s8, s77
	s_cbranch_scc0 .LBB0_2357
	s_and_b64 vcc, exec, s[38:39]
	s_cbranch_vccz .LBB0_2360
	s_barrier

.Ldefbar_skip_5:
	v_add_u32_e32 v250, 0x10000, v141
	s_add_i32 s69, s8, 2
	s_add_u32 s0, s52, 0xfff80080
	s_addc_u32 s1, s53, -1
	s_add_i32 s70, 0, 0x10000
	s_cmp_eq_u32 s66, s8
	s_cselect_b32 s59, s41, s1
	s_cselect_b32 s58, s45, s0
	s_cselect_b32 s9, s43, s68
	s_cselect_b32 s8, s65, s67
	s_add_i32 s71, 0, 0x14000
	s_add_i32 m0, s27, 0xc000
	s_nop 0
	global_load_lds_dwordx4 v138, s[52:53]
	s_add_i32 m0, s27, 0xe000
	s_nop 0
	global_load_lds_dwordx4 v136, s[52:53]
	ds_read_b128 v[144:147], v250
	ds_read_b128 v[148:151], v250 offset:1024
	ds_read_b128 v[152:155], v250 offset:2048
	ds_read_b128 v[156:159], v250 offset:3072
	ds_read_b128 v[160:163], v250 offset:16384
	ds_read_b128 v[164:167], v250 offset:17408
	ds_read_b128 v[168:171], v250 offset:18432
	ds_read_b128 v[172:175], v250 offset:19456
	ds_read_b128 v[176:179], v143
	ds_read_b128 v[180:183], v143 offset:1024
	ds_read_b128 v[184:187], v143 offset:2048
	ds_read_b128 v[188:191], v143 offset:3072
	ds_read_b128 v[192:195], v143 offset:4096
	ds_read_b128 v[202:205], v143 offset:5120
	ds_read_b128 v[206:209], v143 offset:6144
	ds_read_b128 v[210:213], v143 offset:7168
	s_waitcnt vmcnt(8)
	s_waitcnt lgkmcnt(0)
	s_setprio 1
	s_barrier
	v_mfma_f32_16x16x32_bf16 v[126:129], v[144:147], v[176:179], 0
	v_mfma_f32_16x16x32_bf16 v[118:121], v[152:155], v[176:179], 0
	v_mfma_f32_16x16x32_bf16 v[110:113], v[144:147], v[184:187], 0
	v_mfma_f32_16x16x32_bf16 v[102:105], v[152:155], v[184:187], 0
	v_mfma_f32_16x16x32_bf16 v[94:97], v[144:147], v[192:195], 0
	v_mfma_f32_16x16x32_bf16 v[86:89], v[152:155], v[192:195], 0
	v_mfma_f32_16x16x32_bf16 v[78:81], v[144:147], v[206:209], 0
	v_mfma_f32_16x16x32_bf16 v[70:73], v[152:155], v[206:209], 0
	v_mfma_f32_16x16x32_bf16 v[126:129], v[148:151], v[180:183], v[126:129]
	v_mfma_f32_16x16x32_bf16 v[118:121], v[156:159], v[180:183], v[118:121]
	v_mfma_f32_16x16x32_bf16 v[110:113], v[148:151], v[188:191], v[110:113]
	v_mfma_f32_16x16x32_bf16 v[102:105], v[156:159], v[188:191], v[102:105]
	v_mfma_f32_16x16x32_bf16 v[94:97], v[148:151], v[202:205], v[94:97]
	v_mfma_f32_16x16x32_bf16 v[86:89], v[156:159], v[202:205], v[86:89]
	v_mfma_f32_16x16x32_bf16 v[78:81], v[148:151], v[210:213], v[78:81]
	v_mfma_f32_16x16x32_bf16 v[70:73], v[156:159], v[210:213], v[70:73]
	v_mfma_f32_16x16x32_bf16 v[122:125], v[160:163], v[176:179], 0
	v_mfma_f32_16x16x32_bf16 v[114:117], v[168:171], v[176:179], 0
	v_mfma_f32_16x16x32_bf16 v[106:109], v[160:163], v[184:187], 0
	v_mfma_f32_16x16x32_bf16 v[98:101], v[168:171], v[184:187], 0
	v_mfma_f32_16x16x32_bf16 v[90:93], v[160:163], v[192:195], 0
	v_mfma_f32_16x16x32_bf16 v[82:85], v[168:171], v[192:195], 0
	v_mfma_f32_16x16x32_bf16 v[74:77], v[160:163], v[206:209], 0
	v_mfma_f32_16x16x32_bf16 v[66:69], v[168:171], v[206:209], 0
	v_mfma_f32_16x16x32_bf16 v[122:125], v[164:167], v[180:183], v[122:125]
	v_mfma_f32_16x16x32_bf16 v[114:117], v[172:175], v[180:183], v[114:117]
	v_mfma_f32_16x16x32_bf16 v[106:109], v[164:167], v[188:191], v[106:109]
	v_mfma_f32_16x16x32_bf16 v[98:101], v[172:175], v[188:191], v[98:101]
	v_mfma_f32_16x16x32_bf16 v[90:93], v[164:167], v[202:205], v[90:93]
	v_mfma_f32_16x16x32_bf16 v[82:85], v[172:175], v[202:205], v[82:85]
	v_mfma_f32_16x16x32_bf16 v[74:77], v[164:167], v[210:213], v[74:77]
	v_mfma_f32_16x16x32_bf16 v[66:69], v[172:175], v[210:213], v[66:69]
	s_barrier
	s_setprio 0
	s_add_i32 s0, s70, s26
	s_add_u32 s98, s8, s16
	s_addc_u32 s99, s9, s17
	s_mov_b32 m0, s0
	s_nop 0
	global_load_lds_dwordx4 v196, s[8:9]
	s_add_i32 m0, s0, 0x2000
	s_add_u32 s0, s8, 0x80000
	s_addc_u32 s1, s9, 0
	s_add_i32 s70, s71, s26
	global_load_lds_dwordx4 v130, s[8:9]
	s_mov_b32 m0, s70
	s_nop 0
	global_load_lds_dwordx4 v196, s[0:1]
	s_add_i32 m0, s70, 0x2000
	s_nop 0
	global_load_lds_dwordx4 v130, s[0:1]
	s_add_u32 s78, s58, s16
	s_addc_u32 s79, s59, s17
	s_mov_b32 m0, s27
	s_nop 0
	global_load_lds_dwordx4 v134, s[58:59]
	s_mov_b32 m0, s28
	s_nop 0
	global_load_lds_dwordx4 v132, s[58:59]
	ds_read_b128 v[176:179], v143 offset:16384
	ds_read_b128 v[180:183], v143 offset:17408
	ds_read_b128 v[184:187], v143 offset:18432
	ds_read_b128 v[188:191], v143 offset:19456
	ds_read_b128 v[192:195], v143 offset:20480
	ds_read_b128 v[202:205], v143 offset:21504
	ds_read_b128 v[206:209], v143 offset:22528
	ds_read_b128 v[210:213], v143 offset:23552
	s_waitcnt vmcnt(8)
	s_waitcnt lgkmcnt(0)
	s_setprio 1
	s_barrier
	v_mfma_f32_16x16x32_bf16 v[62:65], v[144:147], v[176:179], 0
	v_mfma_f32_16x16x32_bf16 v[54:57], v[152:155], v[176:179], 0
	v_mfma_f32_16x16x32_bf16 v[46:49], v[144:147], v[184:187], 0
	v_mfma_f32_16x16x32_bf16 v[38:41], v[152:155], v[184:187], 0
	v_mfma_f32_16x16x32_bf16 v[30:33], v[144:147], v[192:195], 0
	v_mfma_f32_16x16x32_bf16 v[22:25], v[152:155], v[192:195], 0
	v_mfma_f32_16x16x32_bf16 v[14:17], v[144:147], v[206:209], 0
	v_mfma_f32_16x16x32_bf16 v[6:9], v[152:155], v[206:209], 0
	v_mfma_f32_16x16x32_bf16 v[62:65], v[148:151], v[180:183], v[62:65]
	v_mfma_f32_16x16x32_bf16 v[54:57], v[156:159], v[180:183], v[54:57]
	v_mfma_f32_16x16x32_bf16 v[46:49], v[148:151], v[188:191], v[46:49]
	v_mfma_f32_16x16x32_bf16 v[38:41], v[156:159], v[188:191], v[38:41]
	v_mfma_f32_16x16x32_bf16 v[30:33], v[148:151], v[202:205], v[30:33]
	v_mfma_f32_16x16x32_bf16 v[22:25], v[156:159], v[202:205], v[22:25]
	v_mfma_f32_16x16x32_bf16 v[14:17], v[148:151], v[210:213], v[14:17]
	v_mfma_f32_16x16x32_bf16 v[6:9], v[156:159], v[210:213], v[6:9]
	v_mfma_f32_16x16x32_bf16 v[58:61], v[160:163], v[176:179], 0
	v_mfma_f32_16x16x32_bf16 v[50:53], v[168:171], v[176:179], 0
	v_mfma_f32_16x16x32_bf16 v[42:45], v[160:163], v[184:187], 0
	v_mfma_f32_16x16x32_bf16 v[34:37], v[168:171], v[184:187], 0
	v_mfma_f32_16x16x32_bf16 v[26:29], v[160:163], v[192:195], 0
	v_mfma_f32_16x16x32_bf16 v[18:21], v[168:171], v[192:195], 0
	v_mfma_f32_16x16x32_bf16 v[10:13], v[160:163], v[206:209], 0
	v_mfma_f32_16x16x32_bf16 v[2:5], v[168:171], v[206:209], 0
	v_mfma_f32_16x16x32_bf16 v[58:61], v[164:167], v[180:183], v[58:61]
	v_mfma_f32_16x16x32_bf16 v[50:53], v[172:175], v[180:183], v[50:53]
	v_mfma_f32_16x16x32_bf16 v[42:45], v[164:167], v[188:191], v[42:45]
	v_mfma_f32_16x16x32_bf16 v[34:37], v[172:175], v[188:191], v[34:37]
	v_mfma_f32_16x16x32_bf16 v[26:29], v[164:167], v[202:205], v[26:29]
	v_mfma_f32_16x16x32_bf16 v[18:21], v[172:175], v[202:205], v[18:21]
	v_mfma_f32_16x16x32_bf16 v[10:13], v[164:167], v[210:213], v[10:13]
	v_mfma_f32_16x16x32_bf16 v[2:5], v[172:175], v[210:213], v[2:5]
	s_barrier
	s_setprio 0
	s_branch .Lkmid_5
.LBB0_2507:
	s_add_i32 s69, s8, 2
	s_add_u32 s0, s52, 0xfff80080
	s_addc_u32 s1, s53, -1
	s_add_i32 s70, 0, 0x10000
	s_cmp_eq_u32 s66, s8
	s_cselect_b32 s59, s41, s1
	s_cselect_b32 s58, s45, s0
	s_cselect_b32 s9, s43, s68
	s_cselect_b32 s8, s65, s67
	s_add_i32 s71, 0, 0x14000
	s_add_i32 m0, s27, 0xc000
	s_nop 0
	global_load_lds_dwordx4 v138, s[52:53]
	s_add_i32 m0, s27, 0xe000
	s_nop 0
	global_load_lds_dwordx4 v136, s[52:53]
	ds_read_b128 v[144:147], v250
	ds_read_b128 v[148:151], v250 offset:1024
	ds_read_b128 v[152:155], v250 offset:2048
	ds_read_b128 v[156:159], v250 offset:3072
	ds_read_b128 v[160:163], v250 offset:16384
	ds_read_b128 v[164:167], v250 offset:17408
	ds_read_b128 v[168:171], v250 offset:18432
	ds_read_b128 v[172:175], v250 offset:19456
	ds_read_b128 v[176:179], v143
	ds_read_b128 v[180:183], v143 offset:1024
	ds_read_b128 v[184:187], v143 offset:2048
	ds_read_b128 v[188:191], v143 offset:3072
	ds_read_b128 v[192:195], v143 offset:4096
	ds_read_b128 v[202:205], v143 offset:5120
	ds_read_b128 v[206:209], v143 offset:6144
	ds_read_b128 v[210:213], v143 offset:7168
	s_waitcnt vmcnt(8)
	s_waitcnt lgkmcnt(0)
	s_setprio 1
	s_barrier
	v_mfma_f32_16x16x32_bf16 v[126:129], v[144:147], v[176:179], v[126:129]
	v_mfma_f32_16x16x32_bf16 v[118:121], v[152:155], v[176:179], v[118:121]
	v_mfma_f32_16x16x32_bf16 v[110:113], v[144:147], v[184:187], v[110:113]
	v_mfma_f32_16x16x32_bf16 v[102:105], v[152:155], v[184:187], v[102:105]
	v_mfma_f32_16x16x32_bf16 v[94:97], v[144:147], v[192:195], v[94:97]
	v_mfma_f32_16x16x32_bf16 v[86:89], v[152:155], v[192:195], v[86:89]
	v_mfma_f32_16x16x32_bf16 v[78:81], v[144:147], v[206:209], v[78:81]
	v_mfma_f32_16x16x32_bf16 v[70:73], v[152:155], v[206:209], v[70:73]
	v_mfma_f32_16x16x32_bf16 v[126:129], v[148:151], v[180:183], v[126:129]
	v_mfma_f32_16x16x32_bf16 v[118:121], v[156:159], v[180:183], v[118:121]
	v_mfma_f32_16x16x32_bf16 v[110:113], v[148:151], v[188:191], v[110:113]
	v_mfma_f32_16x16x32_bf16 v[102:105], v[156:159], v[188:191], v[102:105]
	v_mfma_f32_16x16x32_bf16 v[94:97], v[148:151], v[202:205], v[94:97]
	v_mfma_f32_16x16x32_bf16 v[86:89], v[156:159], v[202:205], v[86:89]
	v_mfma_f32_16x16x32_bf16 v[78:81], v[148:151], v[210:213], v[78:81]
	v_mfma_f32_16x16x32_bf16 v[70:73], v[156:159], v[210:213], v[70:73]
	v_mfma_f32_16x16x32_bf16 v[122:125], v[160:163], v[176:179], v[122:125]
	v_mfma_f32_16x16x32_bf16 v[114:117], v[168:171], v[176:179], v[114:117]
	v_mfma_f32_16x16x32_bf16 v[106:109], v[160:163], v[184:187], v[106:109]
	v_mfma_f32_16x16x32_bf16 v[98:101], v[168:171], v[184:187], v[98:101]
	v_mfma_f32_16x16x32_bf16 v[90:93], v[160:163], v[192:195], v[90:93]
	v_mfma_f32_16x16x32_bf16 v[82:85], v[168:171], v[192:195], v[82:85]
	v_mfma_f32_16x16x32_bf16 v[74:77], v[160:163], v[206:209], v[74:77]
	v_mfma_f32_16x16x32_bf16 v[66:69], v[168:171], v[206:209], v[66:69]
	v_mfma_f32_16x16x32_bf16 v[122:125], v[164:167], v[180:183], v[122:125]
	v_mfma_f32_16x16x32_bf16 v[114:117], v[172:175], v[180:183], v[114:117]
	v_mfma_f32_16x16x32_bf16 v[106:109], v[164:167], v[188:191], v[106:109]
	v_mfma_f32_16x16x32_bf16 v[98:101], v[172:175], v[188:191], v[98:101]
	v_mfma_f32_16x16x32_bf16 v[90:93], v[164:167], v[202:205], v[90:93]
	v_mfma_f32_16x16x32_bf16 v[82:85], v[172:175], v[202:205], v[82:85]
	v_mfma_f32_16x16x32_bf16 v[74:77], v[164:167], v[210:213], v[74:77]
	v_mfma_f32_16x16x32_bf16 v[66:69], v[172:175], v[210:213], v[66:69]
	s_barrier
	s_setprio 0
	s_add_i32 s0, s70, s26
	s_add_u32 s98, s8, s16
	s_addc_u32 s99, s9, s17
	s_mov_b32 m0, s0
	s_nop 0
	global_load_lds_dwordx4 v196, s[8:9]
	s_add_i32 m0, s0, 0x2000
	s_add_u32 s0, s8, 0x80000
	s_addc_u32 s1, s9, 0
	s_add_i32 s70, s71, s26
	global_load_lds_dwordx4 v130, s[8:9]
	s_mov_b32 m0, s70
	s_nop 0
	global_load_lds_dwordx4 v196, s[0:1]
	s_add_i32 m0, s70, 0x2000
	s_nop 0
	global_load_lds_dwordx4 v130, s[0:1]
	s_add_u32 s78, s58, s16
	s_addc_u32 s79, s59, s17
	s_mov_b32 m0, s27
	s_nop 0
	global_load_lds_dwordx4 v134, s[58:59]
	s_mov_b32 m0, s28
	s_nop 0
	global_load_lds_dwordx4 v132, s[58:59]
	ds_read_b128 v[176:179], v143 offset:16384
	ds_read_b128 v[180:183], v143 offset:17408
	ds_read_b128 v[184:187], v143 offset:18432
	ds_read_b128 v[188:191], v143 offset:19456
	ds_read_b128 v[192:195], v143 offset:20480
	ds_read_b128 v[202:205], v143 offset:21504
	ds_read_b128 v[206:209], v143 offset:22528
	ds_read_b128 v[210:213], v143 offset:23552
	s_waitcnt vmcnt(8)
	s_waitcnt lgkmcnt(0)
	s_setprio 1
	s_barrier
	v_mfma_f32_16x16x32_bf16 v[62:65], v[144:147], v[176:179], v[62:65]
	v_mfma_f32_16x16x32_bf16 v[54:57], v[152:155], v[176:179], v[54:57]
	v_mfma_f32_16x16x32_bf16 v[46:49], v[144:147], v[184:187], v[46:49]
	v_mfma_f32_16x16x32_bf16 v[38:41], v[152:155], v[184:187], v[38:41]
	v_mfma_f32_16x16x32_bf16 v[30:33], v[144:147], v[192:195], v[30:33]
	v_mfma_f32_16x16x32_bf16 v[22:25], v[152:155], v[192:195], v[22:25]
	v_mfma_f32_16x16x32_bf16 v[14:17], v[144:147], v[206:209], v[14:17]
	v_mfma_f32_16x16x32_bf16 v[6:9], v[152:155], v[206:209], v[6:9]
	v_mfma_f32_16x16x32_bf16 v[62:65], v[148:151], v[180:183], v[62:65]
	v_mfma_f32_16x16x32_bf16 v[54:57], v[156:159], v[180:183], v[54:57]
	v_mfma_f32_16x16x32_bf16 v[46:49], v[148:151], v[188:191], v[46:49]
	v_mfma_f32_16x16x32_bf16 v[38:41], v[156:159], v[188:191], v[38:41]
	v_mfma_f32_16x16x32_bf16 v[30:33], v[148:151], v[202:205], v[30:33]
	v_mfma_f32_16x16x32_bf16 v[22:25], v[156:159], v[202:205], v[22:25]
	v_mfma_f32_16x16x32_bf16 v[14:17], v[148:151], v[210:213], v[14:17]
	v_mfma_f32_16x16x32_bf16 v[6:9], v[156:159], v[210:213], v[6:9]
	v_mfma_f32_16x16x32_bf16 v[58:61], v[160:163], v[176:179], v[58:61]
	v_mfma_f32_16x16x32_bf16 v[50:53], v[168:171], v[176:179], v[50:53]
	v_mfma_f32_16x16x32_bf16 v[42:45], v[160:163], v[184:187], v[42:45]
	v_mfma_f32_16x16x32_bf16 v[34:37], v[168:171], v[184:187], v[34:37]
	v_mfma_f32_16x16x32_bf16 v[26:29], v[160:163], v[192:195], v[26:29]
	v_mfma_f32_16x16x32_bf16 v[18:21], v[168:171], v[192:195], v[18:21]
	v_mfma_f32_16x16x32_bf16 v[10:13], v[160:163], v[206:209], v[10:13]
	v_mfma_f32_16x16x32_bf16 v[2:5], v[168:171], v[206:209], v[2:5]
	v_mfma_f32_16x16x32_bf16 v[58:61], v[164:167], v[180:183], v[58:61]
	v_mfma_f32_16x16x32_bf16 v[50:53], v[172:175], v[180:183], v[50:53]
	v_mfma_f32_16x16x32_bf16 v[42:45], v[164:167], v[188:191], v[42:45]
	v_mfma_f32_16x16x32_bf16 v[34:37], v[172:175], v[188:191], v[34:37]
	v_mfma_f32_16x16x32_bf16 v[26:29], v[164:167], v[202:205], v[26:29]
	v_mfma_f32_16x16x32_bf16 v[18:21], v[172:175], v[202:205], v[18:21]
	v_mfma_f32_16x16x32_bf16 v[10:13], v[164:167], v[210:213], v[10:13]
	v_mfma_f32_16x16x32_bf16 v[2:5], v[172:175], v[210:213], v[2:5]
	s_barrier
	s_setprio 0
.Lkmid_5:
	s_add_i32 s70, 0, 0x18000
	s_add_i32 s71, 0, 0x1c000
	s_add_u32 s0, s58, 0x80000
	s_addc_u32 s1, s59, 0
	s_mov_b32 m0, s29
	s_nop 0
	global_load_lds_dwordx4 v134, s[0:1]
	s_mov_b32 m0, s30
	s_nop 0
	global_load_lds_dwordx4 v132, s[0:1]
	ds_read_b128 v[144:147], v250 offset:32768
	ds_read_b128 v[148:151], v250 offset:33792
	ds_read_b128 v[152:155], v250 offset:34816
	ds_read_b128 v[156:159], v250 offset:35840
	ds_read_b128 v[160:163], v250 offset:49152
	ds_read_b128 v[164:167], v250 offset:50176
	ds_read_b128 v[168:171], v250 offset:51200
	ds_read_b128 v[172:175], v250 offset:52224
	ds_read_b128 v[176:179], v143 offset:32768
	ds_read_b128 v[180:183], v143 offset:33792
	ds_read_b128 v[184:187], v143 offset:34816
	ds_read_b128 v[188:191], v143 offset:35840
	ds_read_b128 v[192:195], v143 offset:36864
	ds_read_b128 v[202:205], v143 offset:37888
	ds_read_b128 v[206:209], v143 offset:38912
	ds_read_b128 v[210:213], v143 offset:39936
	s_waitcnt vmcnt(8)
	s_waitcnt lgkmcnt(0)
	s_setprio 1
	s_barrier
	v_mfma_f32_16x16x32_bf16 v[126:129], v[144:147], v[176:179], v[126:129]
	v_mfma_f32_16x16x32_bf16 v[118:121], v[152:155], v[176:179], v[118:121]
	v_mfma_f32_16x16x32_bf16 v[110:113], v[144:147], v[184:187], v[110:113]
	v_mfma_f32_16x16x32_bf16 v[102:105], v[152:155], v[184:187], v[102:105]
	v_mfma_f32_16x16x32_bf16 v[94:97], v[144:147], v[192:195], v[94:97]
	v_mfma_f32_16x16x32_bf16 v[86:89], v[152:155], v[192:195], v[86:89]
	v_mfma_f32_16x16x32_bf16 v[78:81], v[144:147], v[206:209], v[78:81]
	v_mfma_f32_16x16x32_bf16 v[70:73], v[152:155], v[206:209], v[70:73]
	v_mfma_f32_16x16x32_bf16 v[126:129], v[148:151], v[180:183], v[126:129]
	v_mfma_f32_16x16x32_bf16 v[118:121], v[156:159], v[180:183], v[118:121]
	v_mfma_f32_16x16x32_bf16 v[110:113], v[148:151], v[188:191], v[110:113]
	v_mfma_f32_16x16x32_bf16 v[102:105], v[156:159], v[188:191], v[102:105]
	v_mfma_f32_16x16x32_bf16 v[94:97], v[148:151], v[202:205], v[94:97]
	v_mfma_f32_16x16x32_bf16 v[86:89], v[156:159], v[202:205], v[86:89]
	v_mfma_f32_16x16x32_bf16 v[78:81], v[148:151], v[210:213], v[78:81]
	v_mfma_f32_16x16x32_bf16 v[70:73], v[156:159], v[210:213], v[70:73]
	v_mfma_f32_16x16x32_bf16 v[122:125], v[160:163], v[176:179], v[122:125]
	v_mfma_f32_16x16x32_bf16 v[114:117], v[168:171], v[176:179], v[114:117]
	v_mfma_f32_16x16x32_bf16 v[106:109], v[160:163], v[184:187], v[106:109]
	v_mfma_f32_16x16x32_bf16 v[98:101], v[168:171], v[184:187], v[98:101]
	v_mfma_f32_16x16x32_bf16 v[90:93], v[160:163], v[192:195], v[90:93]
	v_mfma_f32_16x16x32_bf16 v[82:85], v[168:171], v[192:195], v[82:85]
	v_mfma_f32_16x16x32_bf16 v[74:77], v[160:163], v[206:209], v[74:77]
	v_mfma_f32_16x16x32_bf16 v[66:69], v[168:171], v[206:209], v[66:69]
	v_mfma_f32_16x16x32_bf16 v[122:125], v[164:167], v[180:183], v[122:125]
	v_mfma_f32_16x16x32_bf16 v[114:117], v[172:175], v[180:183], v[114:117]
	v_mfma_f32_16x16x32_bf16 v[106:109], v[164:167], v[188:191], v[106:109]
	v_mfma_f32_16x16x32_bf16 v[98:101], v[172:175], v[188:191], v[98:101]
	v_mfma_f32_16x16x32_bf16 v[90:93], v[164:167], v[202:205], v[90:93]
	v_mfma_f32_16x16x32_bf16 v[82:85], v[172:175], v[202:205], v[82:85]
	v_mfma_f32_16x16x32_bf16 v[74:77], v[164:167], v[210:213], v[74:77]
	v_mfma_f32_16x16x32_bf16 v[66:69], v[172:175], v[210:213], v[66:69]
	s_barrier
	s_setprio 0
	s_add_i32 s0, s70, s26
	s_mov_b32 m0, s0
	s_nop 0
	global_load_lds_dwordx4 v196, s[98:99]
	s_add_i32 m0, s0, 0x2000
	s_add_u32 s0, s8, 0x80080
	s_addc_u32 s1, s9, 0
	s_add_i32 s8, s71, s26
	global_load_lds_dwordx4 v130, s[98:99]
	s_mov_b32 m0, s8
	s_nop 0
	global_load_lds_dwordx4 v196, s[0:1]
	s_add_i32 m0, s8, 0x2000
	s_nop 0
	global_load_lds_dwordx4 v130, s[0:1]
	s_mov_b32 m0, s31
	s_nop 0
	global_load_lds_dwordx4 v134, s[78:79]
	s_mov_b32 m0, s34
	s_nop 0
	global_load_lds_dwordx4 v132, s[78:79]
	ds_read_b128 v[176:179], v143 offset:49152
	ds_read_b128 v[180:183], v143 offset:50176
	ds_read_b128 v[184:187], v143 offset:51200
	ds_read_b128 v[188:191], v143 offset:52224
	ds_read_b128 v[192:195], v143 offset:53248
	ds_read_b128 v[202:205], v143 offset:54272
	ds_read_b128 v[206:209], v143 offset:55296
	ds_read_b128 v[210:213], v143 offset:56320
	s_waitcnt vmcnt(8)
	s_waitcnt lgkmcnt(0)
	s_setprio 1
	s_barrier
	v_mfma_f32_16x16x32_bf16 v[62:65], v[144:147], v[176:179], v[62:65]
	v_mfma_f32_16x16x32_bf16 v[54:57], v[152:155], v[176:179], v[54:57]
	v_mfma_f32_16x16x32_bf16 v[46:49], v[144:147], v[184:187], v[46:49]
	v_mfma_f32_16x16x32_bf16 v[38:41], v[152:155], v[184:187], v[38:41]
	v_mfma_f32_16x16x32_bf16 v[30:33], v[144:147], v[192:195], v[30:33]
	v_mfma_f32_16x16x32_bf16 v[22:25], v[152:155], v[192:195], v[22:25]
	v_mfma_f32_16x16x32_bf16 v[14:17], v[144:147], v[206:209], v[14:17]
	v_mfma_f32_16x16x32_bf16 v[6:9], v[152:155], v[206:209], v[6:9]
	v_mfma_f32_16x16x32_bf16 v[62:65], v[148:151], v[180:183], v[62:65]
	v_mfma_f32_16x16x32_bf16 v[54:57], v[156:159], v[180:183], v[54:57]
	v_mfma_f32_16x16x32_bf16 v[46:49], v[148:151], v[188:191], v[46:49]
	v_mfma_f32_16x16x32_bf16 v[38:41], v[156:159], v[188:191], v[38:41]
	v_mfma_f32_16x16x32_bf16 v[30:33], v[148:151], v[202:205], v[30:33]
	v_mfma_f32_16x16x32_bf16 v[22:25], v[156:159], v[202:205], v[22:25]
	v_mfma_f32_16x16x32_bf16 v[14:17], v[148:151], v[210:213], v[14:17]
	v_mfma_f32_16x16x32_bf16 v[6:9], v[156:159], v[210:213], v[6:9]
	v_mfma_f32_16x16x32_bf16 v[58:61], v[160:163], v[176:179], v[58:61]
	v_mfma_f32_16x16x32_bf16 v[50:53], v[168:171], v[176:179], v[50:53]
	v_mfma_f32_16x16x32_bf16 v[42:45], v[160:163], v[184:187], v[42:45]
	v_mfma_f32_16x16x32_bf16 v[34:37], v[168:171], v[184:187], v[34:37]
	v_mfma_f32_16x16x32_bf16 v[26:29], v[160:163], v[192:195], v[26:29]
	v_mfma_f32_16x16x32_bf16 v[18:21], v[168:171], v[192:195], v[18:21]
	v_mfma_f32_16x16x32_bf16 v[10:13], v[160:163], v[206:209], v[10:13]
	v_mfma_f32_16x16x32_bf16 v[2:5], v[168:171], v[206:209], v[2:5]
	v_mfma_f32_16x16x32_bf16 v[58:61], v[164:167], v[180:183], v[58:61]
	v_mfma_f32_16x16x32_bf16 v[50:53], v[172:175], v[180:183], v[50:53]
	v_mfma_f32_16x16x32_bf16 v[42:45], v[164:167], v[188:191], v[42:45]
	v_mfma_f32_16x16x32_bf16 v[34:37], v[172:175], v[188:191], v[34:37]
	v_mfma_f32_16x16x32_bf16 v[26:29], v[164:167], v[202:205], v[26:29]
	v_mfma_f32_16x16x32_bf16 v[18:21], v[172:175], v[202:205], v[18:21]
	v_mfma_f32_16x16x32_bf16 v[10:13], v[164:167], v[210:213], v[10:13]
	v_mfma_f32_16x16x32_bf16 v[2:5], v[172:175], v[210:213], v[2:5]
	s_barrier
	s_setprio 0
	s_add_u32 s67, s67, 0x100
	s_addc_u32 s68, s68, 0
	s_add_u32 s52, s52, 0x100
	s_addc_u32 s53, s53, 0
	s_cmp_ge_i32 s69, s62
	s_mov_b32 s8, s69
	s_cbranch_scc0 .LBB0_2507
	s_and_b64 vcc, exec, s[38:39]
	s_cbranch_vccz .LBB0_2510
	s_barrier

.Ldefbar_skip_6:
	v_add_u32_e32 v250, 0x10000, v188
	s_add_i32 s72, s48, 2
	s_add_u32 s8, s46, 0x100
	s_addc_u32 s9, s47, 0
	s_add_i32 s0, 0, 0x10000
	s_cmp_eq_u32 s41, s48
	s_cselect_b32 s51, s43, s9
	s_cselect_b32 s50, s42, s8
	s_cselect_b32 s49, s45, s71
	s_cselect_b32 s48, s44, s70
	s_add_i32 s73, 0, 0x14000
	v_lshl_add_u64 v[194:195], s[46:47], 0, v[162:163]
	s_add_i32 m0, s27, 0xc000
	s_nop 0
	global_load_lds_dwordx4 v[194:195], off
	v_lshl_add_u64 v[194:195], s[46:47], 0, v[160:161]
	s_add_i32 m0, s27, 0xe000
	s_nop 0
	global_load_lds_dwordx4 v[194:195], off
	ds_read_b128 v[130:133], v250
	ds_read_b128 v[134:137], v250 offset:1024
	ds_read_b128 v[138:141], v250 offset:2048
	ds_read_b128 v[142:145], v250 offset:3072
	ds_read_b128 v[146:149], v250 offset:16384
	ds_read_b128 v[164:167], v250 offset:17408
	ds_read_b128 v[168:171], v250 offset:18432
	ds_read_b128 v[172:175], v250 offset:19456
	ds_read_b128 v[176:179], v189
	ds_read_b128 v[180:183], v189 offset:1024
	ds_read_b128 v[184:187], v189 offset:2048
	ds_read_b128 v[190:193], v189 offset:3072
	ds_read_b128 v[202:205], v189 offset:4096
	ds_read_b128 v[206:209], v189 offset:5120
	ds_read_b128 v[210:213], v189 offset:6144
	ds_read_b128 v[214:217], v189 offset:7168
	s_waitcnt vmcnt(8)
	s_waitcnt lgkmcnt(0)
	s_setprio 1
	s_barrier
	v_mfma_f32_16x16x32_bf16 v[126:129], v[130:133], v[176:179], 0
	v_mfma_f32_16x16x32_bf16 v[122:125], v[138:141], v[176:179], 0
	v_mfma_f32_16x16x32_bf16 v[110:113], v[130:133], v[184:187], 0
	v_mfma_f32_16x16x32_bf16 v[106:109], v[138:141], v[184:187], 0
	v_mfma_f32_16x16x32_bf16 v[98:101], v[130:133], v[202:205], 0
	v_mfma_f32_16x16x32_bf16 v[90:93], v[138:141], v[202:205], 0
	v_mfma_f32_16x16x32_bf16 v[82:85], v[130:133], v[210:213], 0
	v_mfma_f32_16x16x32_bf16 v[74:77], v[138:141], v[210:213], 0
	v_mfma_f32_16x16x32_bf16 v[126:129], v[134:137], v[180:183], v[126:129]
	v_mfma_f32_16x16x32_bf16 v[122:125], v[142:145], v[180:183], v[122:125]
	v_mfma_f32_16x16x32_bf16 v[110:113], v[134:137], v[190:193], v[110:113]
	v_mfma_f32_16x16x32_bf16 v[106:109], v[142:145], v[190:193], v[106:109]
	v_mfma_f32_16x16x32_bf16 v[98:101], v[134:137], v[206:209], v[98:101]
	v_mfma_f32_16x16x32_bf16 v[90:93], v[142:145], v[206:209], v[90:93]
	v_mfma_f32_16x16x32_bf16 v[82:85], v[134:137], v[214:217], v[82:85]
	v_mfma_f32_16x16x32_bf16 v[74:77], v[142:145], v[214:217], v[74:77]
	v_mfma_f32_16x16x32_bf16 v[118:121], v[146:149], v[176:179], 0
	v_mfma_f32_16x16x32_bf16 v[114:117], v[168:171], v[176:179], 0
	v_mfma_f32_16x16x32_bf16 v[102:105], v[146:149], v[184:187], 0
	v_mfma_f32_16x16x32_bf16 v[94:97], v[168:171], v[184:187], 0
	v_mfma_f32_16x16x32_bf16 v[86:89], v[146:149], v[202:205], 0
	v_mfma_f32_16x16x32_bf16 v[78:81], v[168:171], v[202:205], 0
	v_mfma_f32_16x16x32_bf16 v[70:73], v[146:149], v[210:213], 0
	v_mfma_f32_16x16x32_bf16 v[66:69], v[168:171], v[210:213], 0
	v_mfma_f32_16x16x32_bf16 v[118:121], v[164:167], v[180:183], v[118:121]
	v_mfma_f32_16x16x32_bf16 v[114:117], v[172:175], v[180:183], v[114:117]
	v_mfma_f32_16x16x32_bf16 v[102:105], v[164:167], v[190:193], v[102:105]
	v_mfma_f32_16x16x32_bf16 v[94:97], v[172:175], v[190:193], v[94:97]
	v_mfma_f32_16x16x32_bf16 v[86:89], v[164:167], v[206:209], v[86:89]
	v_mfma_f32_16x16x32_bf16 v[78:81], v[172:175], v[206:209], v[78:81]
	v_mfma_f32_16x16x32_bf16 v[70:73], v[164:167], v[214:217], v[70:73]
	v_mfma_f32_16x16x32_bf16 v[66:69], v[172:175], v[214:217], v[66:69]
	s_barrier
	s_setprio 0
	s_add_i32 s0, s0, s26
	s_add_u32 s98, s48, s16
	s_addc_u32 s99, s49, s17
	s_mov_b32 m0, s0
	s_nop 0
	global_load_lds_dwordx4 v196, s[48:49]
	s_add_i32 m0, s0, 0x2000
	s_add_u32 s0, s48, 0x158000
	s_addc_u32 s1, s49, 0
	s_add_i32 s46, s73, s26
	global_load_lds_dwordx4 v154, s[48:49]
	s_mov_b32 m0, s46
	s_nop 0
	global_load_lds_dwordx4 v196, s[0:1]
	s_add_i32 m0, s46, 0x2000
	s_nop 0
	global_load_lds_dwordx4 v154, s[0:1]
	s_add_u32 s78, s50, s16
	s_addc_u32 s79, s51, s17
	s_mov_b32 m0, s27
	s_nop 0
	global_load_lds_dwordx4 v150, s[50:51]
	s_mov_b32 m0, s30
	s_nop 0
	global_load_lds_dwordx4 v152, s[50:51]
	ds_read_b128 v[176:179], v189 offset:16384
	ds_read_b128 v[180:183], v189 offset:17408
	ds_read_b128 v[184:187], v189 offset:18432
	ds_read_b128 v[190:193], v189 offset:19456
	ds_read_b128 v[202:205], v189 offset:20480
	ds_read_b128 v[206:209], v189 offset:21504
	ds_read_b128 v[210:213], v189 offset:22528
	ds_read_b128 v[214:217], v189 offset:23552
	s_waitcnt vmcnt(8)
	s_waitcnt lgkmcnt(0)
	s_setprio 1
	s_barrier
	v_mfma_f32_16x16x32_bf16 v[62:65], v[130:133], v[176:179], 0
	v_mfma_f32_16x16x32_bf16 v[58:61], v[138:141], v[176:179], 0
	v_mfma_f32_16x16x32_bf16 v[50:53], v[130:133], v[184:187], 0
	v_mfma_f32_16x16x32_bf16 v[42:45], v[138:141], v[184:187], 0
	v_mfma_f32_16x16x32_bf16 v[34:37], v[130:133], v[202:205], 0
	v_mfma_f32_16x16x32_bf16 v[26:29], v[138:141], v[202:205], 0
	v_mfma_f32_16x16x32_bf16 v[18:21], v[130:133], v[210:213], 0
	v_mfma_f32_16x16x32_bf16 v[10:13], v[138:141], v[210:213], 0
	v_mfma_f32_16x16x32_bf16 v[62:65], v[134:137], v[180:183], v[62:65]
	v_mfma_f32_16x16x32_bf16 v[58:61], v[142:145], v[180:183], v[58:61]
	v_mfma_f32_16x16x32_bf16 v[50:53], v[134:137], v[190:193], v[50:53]
	v_mfma_f32_16x16x32_bf16 v[42:45], v[142:145], v[190:193], v[42:45]
	v_mfma_f32_16x16x32_bf16 v[34:37], v[134:137], v[206:209], v[34:37]
	v_mfma_f32_16x16x32_bf16 v[26:29], v[142:145], v[206:209], v[26:29]
	v_mfma_f32_16x16x32_bf16 v[18:21], v[134:137], v[214:217], v[18:21]
	v_mfma_f32_16x16x32_bf16 v[10:13], v[142:145], v[214:217], v[10:13]
	v_mfma_f32_16x16x32_bf16 v[54:57], v[146:149], v[176:179], 0
	v_mfma_f32_16x16x32_bf16 v[46:49], v[168:171], v[176:179], 0
	v_mfma_f32_16x16x32_bf16 v[38:41], v[146:149], v[184:187], 0
	v_mfma_f32_16x16x32_bf16 v[30:33], v[168:171], v[184:187], 0
	v_mfma_f32_16x16x32_bf16 v[22:25], v[146:149], v[202:205], 0
	v_mfma_f32_16x16x32_bf16 v[14:17], v[168:171], v[202:205], 0
	v_mfma_f32_16x16x32_bf16 v[6:9], v[146:149], v[210:213], 0
	v_mfma_f32_16x16x32_bf16 v[2:5], v[168:171], v[210:213], 0
	v_mfma_f32_16x16x32_bf16 v[54:57], v[164:167], v[180:183], v[54:57]
	v_mfma_f32_16x16x32_bf16 v[46:49], v[172:175], v[180:183], v[46:49]
	v_mfma_f32_16x16x32_bf16 v[38:41], v[164:167], v[190:193], v[38:41]
	v_mfma_f32_16x16x32_bf16 v[30:33], v[172:175], v[190:193], v[30:33]
	v_mfma_f32_16x16x32_bf16 v[22:25], v[164:167], v[206:209], v[22:25]
	v_mfma_f32_16x16x32_bf16 v[14:17], v[172:175], v[206:209], v[14:17]
	v_mfma_f32_16x16x32_bf16 v[6:9], v[164:167], v[214:217], v[6:9]
	v_mfma_f32_16x16x32_bf16 v[2:5], v[172:175], v[214:217], v[2:5]
	s_barrier
	s_setprio 0
	s_branch .Lkmid_6
.LBB0_2588:
	s_add_i32 s72, s48, 2
	s_add_u32 s8, s46, 0x100
	s_addc_u32 s9, s47, 0
	s_add_i32 s0, 0, 0x10000
	s_cmp_eq_u32 s41, s48
	s_cselect_b32 s51, s43, s9
	s_cselect_b32 s50, s42, s8
	s_cselect_b32 s49, s45, s71
	s_cselect_b32 s48, s44, s70
	s_add_i32 s73, 0, 0x14000
	v_lshl_add_u64 v[194:195], s[46:47], 0, v[162:163]
	s_add_i32 m0, s27, 0xc000
	s_nop 0
	global_load_lds_dwordx4 v[194:195], off
	v_lshl_add_u64 v[194:195], s[46:47], 0, v[160:161]
	s_add_i32 m0, s27, 0xe000
	s_nop 0
	global_load_lds_dwordx4 v[194:195], off
	ds_read_b128 v[130:133], v250
	ds_read_b128 v[134:137], v250 offset:1024
	ds_read_b128 v[138:141], v250 offset:2048
	ds_read_b128 v[142:145], v250 offset:3072
	ds_read_b128 v[146:149], v250 offset:16384
	ds_read_b128 v[164:167], v250 offset:17408
	ds_read_b128 v[168:171], v250 offset:18432
	ds_read_b128 v[172:175], v250 offset:19456
	ds_read_b128 v[176:179], v189
	ds_read_b128 v[180:183], v189 offset:1024
	ds_read_b128 v[184:187], v189 offset:2048
	ds_read_b128 v[190:193], v189 offset:3072
	ds_read_b128 v[202:205], v189 offset:4096
	ds_read_b128 v[206:209], v189 offset:5120
	ds_read_b128 v[210:213], v189 offset:6144
	ds_read_b128 v[214:217], v189 offset:7168
	s_waitcnt vmcnt(8)
	s_waitcnt lgkmcnt(0)
	s_setprio 1
	s_barrier
	v_mfma_f32_16x16x32_bf16 v[126:129], v[130:133], v[176:179], v[126:129]
	v_mfma_f32_16x16x32_bf16 v[122:125], v[138:141], v[176:179], v[122:125]
	v_mfma_f32_16x16x32_bf16 v[110:113], v[130:133], v[184:187], v[110:113]
	v_mfma_f32_16x16x32_bf16 v[106:109], v[138:141], v[184:187], v[106:109]
	v_mfma_f32_16x16x32_bf16 v[98:101], v[130:133], v[202:205], v[98:101]
	v_mfma_f32_16x16x32_bf16 v[90:93], v[138:141], v[202:205], v[90:93]
	v_mfma_f32_16x16x32_bf16 v[82:85], v[130:133], v[210:213], v[82:85]
	v_mfma_f32_16x16x32_bf16 v[74:77], v[138:141], v[210:213], v[74:77]
	v_mfma_f32_16x16x32_bf16 v[126:129], v[134:137], v[180:183], v[126:129]
	v_mfma_f32_16x16x32_bf16 v[122:125], v[142:145], v[180:183], v[122:125]
	v_mfma_f32_16x16x32_bf16 v[110:113], v[134:137], v[190:193], v[110:113]
	v_mfma_f32_16x16x32_bf16 v[106:109], v[142:145], v[190:193], v[106:109]
	v_mfma_f32_16x16x32_bf16 v[98:101], v[134:137], v[206:209], v[98:101]
	v_mfma_f32_16x16x32_bf16 v[90:93], v[142:145], v[206:209], v[90:93]
	v_mfma_f32_16x16x32_bf16 v[82:85], v[134:137], v[214:217], v[82:85]
	v_mfma_f32_16x16x32_bf16 v[74:77], v[142:145], v[214:217], v[74:77]
	v_mfma_f32_16x16x32_bf16 v[118:121], v[146:149], v[176:179], v[118:121]
	v_mfma_f32_16x16x32_bf16 v[114:117], v[168:171], v[176:179], v[114:117]
	v_mfma_f32_16x16x32_bf16 v[102:105], v[146:149], v[184:187], v[102:105]
	v_mfma_f32_16x16x32_bf16 v[94:97], v[168:171], v[184:187], v[94:97]
	v_mfma_f32_16x16x32_bf16 v[86:89], v[146:149], v[202:205], v[86:89]
	v_mfma_f32_16x16x32_bf16 v[78:81], v[168:171], v[202:205], v[78:81]
	v_mfma_f32_16x16x32_bf16 v[70:73], v[146:149], v[210:213], v[70:73]
	v_mfma_f32_16x16x32_bf16 v[66:69], v[168:171], v[210:213], v[66:69]
	v_mfma_f32_16x16x32_bf16 v[118:121], v[164:167], v[180:183], v[118:121]
	v_mfma_f32_16x16x32_bf16 v[114:117], v[172:175], v[180:183], v[114:117]
	v_mfma_f32_16x16x32_bf16 v[102:105], v[164:167], v[190:193], v[102:105]
	v_mfma_f32_16x16x32_bf16 v[94:97], v[172:175], v[190:193], v[94:97]
	v_mfma_f32_16x16x32_bf16 v[86:89], v[164:167], v[206:209], v[86:89]
	v_mfma_f32_16x16x32_bf16 v[78:81], v[172:175], v[206:209], v[78:81]
	v_mfma_f32_16x16x32_bf16 v[70:73], v[164:167], v[214:217], v[70:73]
	v_mfma_f32_16x16x32_bf16 v[66:69], v[172:175], v[214:217], v[66:69]
	s_barrier
	s_setprio 0
	s_add_i32 s0, s0, s26
	s_add_u32 s98, s48, s16
	s_addc_u32 s99, s49, s17
	s_mov_b32 m0, s0
	s_nop 0
	global_load_lds_dwordx4 v196, s[48:49]
	s_add_i32 m0, s0, 0x2000
	s_add_u32 s0, s48, 0x158000
	s_addc_u32 s1, s49, 0
	s_add_i32 s46, s73, s26
	global_load_lds_dwordx4 v154, s[48:49]
	s_mov_b32 m0, s46
	s_nop 0
	global_load_lds_dwordx4 v196, s[0:1]
	s_add_i32 m0, s46, 0x2000
	s_nop 0
	global_load_lds_dwordx4 v154, s[0:1]
	s_add_u32 s78, s50, s16
	s_addc_u32 s79, s51, s17
	s_mov_b32 m0, s27
	s_nop 0
	global_load_lds_dwordx4 v150, s[50:51]
	s_mov_b32 m0, s30
	s_nop 0
	global_load_lds_dwordx4 v152, s[50:51]
	ds_read_b128 v[176:179], v189 offset:16384
	ds_read_b128 v[180:183], v189 offset:17408
	ds_read_b128 v[184:187], v189 offset:18432
	ds_read_b128 v[190:193], v189 offset:19456
	ds_read_b128 v[202:205], v189 offset:20480
	ds_read_b128 v[206:209], v189 offset:21504
	ds_read_b128 v[210:213], v189 offset:22528
	ds_read_b128 v[214:217], v189 offset:23552
	s_waitcnt vmcnt(8)
	s_waitcnt lgkmcnt(0)
	s_setprio 1
	s_barrier
	v_mfma_f32_16x16x32_bf16 v[62:65], v[130:133], v[176:179], v[62:65]
	v_mfma_f32_16x16x32_bf16 v[58:61], v[138:141], v[176:179], v[58:61]
	v_mfma_f32_16x16x32_bf16 v[50:53], v[130:133], v[184:187], v[50:53]
	v_mfma_f32_16x16x32_bf16 v[42:45], v[138:141], v[184:187], v[42:45]
	v_mfma_f32_16x16x32_bf16 v[34:37], v[130:133], v[202:205], v[34:37]
	v_mfma_f32_16x16x32_bf16 v[26:29], v[138:141], v[202:205], v[26:29]
	v_mfma_f32_16x16x32_bf16 v[18:21], v[130:133], v[210:213], v[18:21]
	v_mfma_f32_16x16x32_bf16 v[10:13], v[138:141], v[210:213], v[10:13]
	v_mfma_f32_16x16x32_bf16 v[62:65], v[134:137], v[180:183], v[62:65]
	v_mfma_f32_16x16x32_bf16 v[58:61], v[142:145], v[180:183], v[58:61]
	v_mfma_f32_16x16x32_bf16 v[50:53], v[134:137], v[190:193], v[50:53]
	v_mfma_f32_16x16x32_bf16 v[42:45], v[142:145], v[190:193], v[42:45]
	v_mfma_f32_16x16x32_bf16 v[34:37], v[134:137], v[206:209], v[34:37]
	v_mfma_f32_16x16x32_bf16 v[26:29], v[142:145], v[206:209], v[26:29]
	v_mfma_f32_16x16x32_bf16 v[18:21], v[134:137], v[214:217], v[18:21]
	v_mfma_f32_16x16x32_bf16 v[10:13], v[142:145], v[214:217], v[10:13]
	v_mfma_f32_16x16x32_bf16 v[54:57], v[146:149], v[176:179], v[54:57]
	v_mfma_f32_16x16x32_bf16 v[46:49], v[168:171], v[176:179], v[46:49]
	v_mfma_f32_16x16x32_bf16 v[38:41], v[146:149], v[184:187], v[38:41]
	v_mfma_f32_16x16x32_bf16 v[30:33], v[168:171], v[184:187], v[30:33]
	v_mfma_f32_16x16x32_bf16 v[22:25], v[146:149], v[202:205], v[22:25]
	v_mfma_f32_16x16x32_bf16 v[14:17], v[168:171], v[202:205], v[14:17]
	v_mfma_f32_16x16x32_bf16 v[6:9], v[146:149], v[210:213], v[6:9]
	v_mfma_f32_16x16x32_bf16 v[2:5], v[168:171], v[210:213], v[2:5]
	v_mfma_f32_16x16x32_bf16 v[54:57], v[164:167], v[180:183], v[54:57]
	v_mfma_f32_16x16x32_bf16 v[46:49], v[172:175], v[180:183], v[46:49]
	v_mfma_f32_16x16x32_bf16 v[38:41], v[164:167], v[190:193], v[38:41]
	v_mfma_f32_16x16x32_bf16 v[30:33], v[172:175], v[190:193], v[30:33]
	v_mfma_f32_16x16x32_bf16 v[22:25], v[164:167], v[206:209], v[22:25]
	v_mfma_f32_16x16x32_bf16 v[14:17], v[172:175], v[206:209], v[14:17]
	v_mfma_f32_16x16x32_bf16 v[6:9], v[164:167], v[214:217], v[6:9]
	v_mfma_f32_16x16x32_bf16 v[2:5], v[172:175], v[214:217], v[2:5]
	s_barrier
	s_setprio 0
.Lkmid_6:
	s_add_i32 s46, 0, 0x18000
	s_add_i32 s47, 0, 0x1c000
	s_add_u32 s0, s50, 0x158000
	s_addc_u32 s1, s51, 0
	s_mov_b32 m0, s31
	s_nop 0
	global_load_lds_dwordx4 v150, s[0:1]
	s_mov_b32 m0, s34
	s_nop 0
	global_load_lds_dwordx4 v152, s[0:1]
	ds_read_b128 v[130:133], v250 offset:32768
	ds_read_b128 v[134:137], v250 offset:33792
	ds_read_b128 v[138:141], v250 offset:34816
	ds_read_b128 v[142:145], v250 offset:35840
	ds_read_b128 v[146:149], v250 offset:49152
	ds_read_b128 v[164:167], v250 offset:50176
	ds_read_b128 v[168:171], v250 offset:51200
	ds_read_b128 v[172:175], v250 offset:52224
	ds_read_b128 v[176:179], v189 offset:32768
	ds_read_b128 v[180:183], v189 offset:33792
	ds_read_b128 v[184:187], v189 offset:34816
	ds_read_b128 v[190:193], v189 offset:35840
	ds_read_b128 v[202:205], v189 offset:36864
	ds_read_b128 v[206:209], v189 offset:37888
	ds_read_b128 v[210:213], v189 offset:38912
	ds_read_b128 v[214:217], v189 offset:39936
	s_waitcnt vmcnt(8)
	s_waitcnt lgkmcnt(0)
	s_setprio 1
	s_barrier
	v_mfma_f32_16x16x32_bf16 v[126:129], v[130:133], v[176:179], v[126:129]
	v_mfma_f32_16x16x32_bf16 v[122:125], v[138:141], v[176:179], v[122:125]
	v_mfma_f32_16x16x32_bf16 v[110:113], v[130:133], v[184:187], v[110:113]
	v_mfma_f32_16x16x32_bf16 v[106:109], v[138:141], v[184:187], v[106:109]
	v_mfma_f32_16x16x32_bf16 v[98:101], v[130:133], v[202:205], v[98:101]
	v_mfma_f32_16x16x32_bf16 v[90:93], v[138:141], v[202:205], v[90:93]
	v_mfma_f32_16x16x32_bf16 v[82:85], v[130:133], v[210:213], v[82:85]
	v_mfma_f32_16x16x32_bf16 v[74:77], v[138:141], v[210:213], v[74:77]
	v_mfma_f32_16x16x32_bf16 v[126:129], v[134:137], v[180:183], v[126:129]
	v_mfma_f32_16x16x32_bf16 v[122:125], v[142:145], v[180:183], v[122:125]
	v_mfma_f32_16x16x32_bf16 v[110:113], v[134:137], v[190:193], v[110:113]
	v_mfma_f32_16x16x32_bf16 v[106:109], v[142:145], v[190:193], v[106:109]
	v_mfma_f32_16x16x32_bf16 v[98:101], v[134:137], v[206:209], v[98:101]
	v_mfma_f32_16x16x32_bf16 v[90:93], v[142:145], v[206:209], v[90:93]
	v_mfma_f32_16x16x32_bf16 v[82:85], v[134:137], v[214:217], v[82:85]
	v_mfma_f32_16x16x32_bf16 v[74:77], v[142:145], v[214:217], v[74:77]
	v_mfma_f32_16x16x32_bf16 v[118:121], v[146:149], v[176:179], v[118:121]
	v_mfma_f32_16x16x32_bf16 v[114:117], v[168:171], v[176:179], v[114:117]
	v_mfma_f32_16x16x32_bf16 v[102:105], v[146:149], v[184:187], v[102:105]
	v_mfma_f32_16x16x32_bf16 v[94:97], v[168:171], v[184:187], v[94:97]
	v_mfma_f32_16x16x32_bf16 v[86:89], v[146:149], v[202:205], v[86:89]
	v_mfma_f32_16x16x32_bf16 v[78:81], v[168:171], v[202:205], v[78:81]
	v_mfma_f32_16x16x32_bf16 v[70:73], v[146:149], v[210:213], v[70:73]
	v_mfma_f32_16x16x32_bf16 v[66:69], v[168:171], v[210:213], v[66:69]
	v_mfma_f32_16x16x32_bf16 v[118:121], v[164:167], v[180:183], v[118:121]
	v_mfma_f32_16x16x32_bf16 v[114:117], v[172:175], v[180:183], v[114:117]
	v_mfma_f32_16x16x32_bf16 v[102:105], v[164:167], v[190:193], v[102:105]
	v_mfma_f32_16x16x32_bf16 v[94:97], v[172:175], v[190:193], v[94:97]
	v_mfma_f32_16x16x32_bf16 v[86:89], v[164:167], v[206:209], v[86:89]
	v_mfma_f32_16x16x32_bf16 v[78:81], v[172:175], v[206:209], v[78:81]
	v_mfma_f32_16x16x32_bf16 v[70:73], v[164:167], v[214:217], v[70:73]
	v_mfma_f32_16x16x32_bf16 v[66:69], v[172:175], v[214:217], v[66:69]
	s_barrier
	s_setprio 0
	s_add_i32 s0, s46, s26
	s_mov_b32 m0, s0
	s_nop 0
	global_load_lds_dwordx4 v196, s[98:99]
	s_add_i32 m0, s0, 0x2000
	s_add_u32 s0, s48, 0x158080
	s_addc_u32 s1, s49, 0
	s_add_i32 s46, s47, s26
	global_load_lds_dwordx4 v154, s[98:99]
	s_mov_b32 m0, s46
	s_nop 0
	global_load_lds_dwordx4 v196, s[0:1]
	s_add_i32 m0, s46, 0x2000
	s_nop 0
	global_load_lds_dwordx4 v154, s[0:1]
	s_mov_b32 m0, s53
	s_nop 0
	global_load_lds_dwordx4 v150, s[78:79]
	s_mov_b32 m0, s58
	s_nop 0
	global_load_lds_dwordx4 v152, s[78:79]
	ds_read_b128 v[176:179], v189 offset:49152
	ds_read_b128 v[180:183], v189 offset:50176
	ds_read_b128 v[184:187], v189 offset:51200
	ds_read_b128 v[190:193], v189 offset:52224
	ds_read_b128 v[202:205], v189 offset:53248
	ds_read_b128 v[206:209], v189 offset:54272
	ds_read_b128 v[210:213], v189 offset:55296
	ds_read_b128 v[214:217], v189 offset:56320
	s_waitcnt vmcnt(8)
	s_waitcnt lgkmcnt(0)
	s_setprio 1
	s_barrier
	v_mfma_f32_16x16x32_bf16 v[62:65], v[130:133], v[176:179], v[62:65]
	v_mfma_f32_16x16x32_bf16 v[58:61], v[138:141], v[176:179], v[58:61]
	v_mfma_f32_16x16x32_bf16 v[50:53], v[130:133], v[184:187], v[50:53]
	v_mfma_f32_16x16x32_bf16 v[42:45], v[138:141], v[184:187], v[42:45]
	v_mfma_f32_16x16x32_bf16 v[34:37], v[130:133], v[202:205], v[34:37]
	v_mfma_f32_16x16x32_bf16 v[26:29], v[138:141], v[202:205], v[26:29]
	v_mfma_f32_16x16x32_bf16 v[18:21], v[130:133], v[210:213], v[18:21]
	v_mfma_f32_16x16x32_bf16 v[10:13], v[138:141], v[210:213], v[10:13]
	v_mfma_f32_16x16x32_bf16 v[62:65], v[134:137], v[180:183], v[62:65]
	v_mfma_f32_16x16x32_bf16 v[58:61], v[142:145], v[180:183], v[58:61]
	v_mfma_f32_16x16x32_bf16 v[50:53], v[134:137], v[190:193], v[50:53]
	v_mfma_f32_16x16x32_bf16 v[42:45], v[142:145], v[190:193], v[42:45]
	v_mfma_f32_16x16x32_bf16 v[34:37], v[134:137], v[206:209], v[34:37]
	v_mfma_f32_16x16x32_bf16 v[26:29], v[142:145], v[206:209], v[26:29]
	v_mfma_f32_16x16x32_bf16 v[18:21], v[134:137], v[214:217], v[18:21]
	v_mfma_f32_16x16x32_bf16 v[10:13], v[142:145], v[214:217], v[10:13]
	v_mfma_f32_16x16x32_bf16 v[54:57], v[146:149], v[176:179], v[54:57]
	v_mfma_f32_16x16x32_bf16 v[46:49], v[168:171], v[176:179], v[46:49]
	v_mfma_f32_16x16x32_bf16 v[38:41], v[146:149], v[184:187], v[38:41]
	v_mfma_f32_16x16x32_bf16 v[30:33], v[168:171], v[184:187], v[30:33]
	v_mfma_f32_16x16x32_bf16 v[22:25], v[146:149], v[202:205], v[22:25]
	v_mfma_f32_16x16x32_bf16 v[14:17], v[168:171], v[202:205], v[14:17]
	v_mfma_f32_16x16x32_bf16 v[6:9], v[146:149], v[210:213], v[6:9]
	v_mfma_f32_16x16x32_bf16 v[2:5], v[168:171], v[210:213], v[2:5]
	v_mfma_f32_16x16x32_bf16 v[54:57], v[164:167], v[180:183], v[54:57]
	v_mfma_f32_16x16x32_bf16 v[46:49], v[172:175], v[180:183], v[46:49]
	v_mfma_f32_16x16x32_bf16 v[38:41], v[164:167], v[190:193], v[38:41]
	v_mfma_f32_16x16x32_bf16 v[30:33], v[172:175], v[190:193], v[30:33]
	v_mfma_f32_16x16x32_bf16 v[22:25], v[164:167], v[206:209], v[22:25]
	v_mfma_f32_16x16x32_bf16 v[14:17], v[172:175], v[206:209], v[14:17]
	v_mfma_f32_16x16x32_bf16 v[6:9], v[164:167], v[214:217], v[6:9]
	v_mfma_f32_16x16x32_bf16 v[2:5], v[172:175], v[214:217], v[2:5]
	s_barrier
	s_setprio 0
	s_add_u32 s70, s70, 0x100
	s_addc_u32 s71, s71, 0
	s_cmp_ge_i32 s72, s69
	s_mov_b64 s[46:47], s[8:9]
	s_mov_b32 s48, s72
	s_cbranch_scc0 .LBB0_2588
	s_and_b64 vcc, exec, s[28:29]
	s_cbranch_vccz .LBB0_2591
	s_barrier
